# GEMM K-loops: first 4 MFMAs of each MMA block issued before the phase barrier at low priority (fills the hand-over bubble); retention epilogue deferred
# speedup vs baseline: 1.0049x; 1.0049x over previous
.LBB0_285:
	ds_read_b128 v[154:157], v151
	ds_read_b128 v[158:161], v151 offset:1024
	ds_read_b128 v[164:167], v151 offset:2048
	ds_read_b128 v[168:171], v151 offset:3072
	ds_read_b128 v[172:175], v152
	ds_read_b128 v[176:179], v152 offset:1024
	ds_read_b128 v[180:183], v152 offset:2048
	ds_read_b128 v[184:187], v152 offset:3072
	s_add_u32 s36, s34, 0xfff80080
	s_addc_u32 s37, s35, -1
	s_cmp_eq_u32 s53, 28
	s_cselect_b32 s39, s16, s37
	s_cselect_b32 s38, s17, s36
	s_cselect_b32 s37, s18, s25
	s_cselect_b32 s36, s19, s23
	v_lshl_add_u64 v[146:147], s[34:35], 0, v[138:139]
	s_add_i32 m0, s31, 0xc000
	ds_read_b128 v[188:191], v153
	ds_read_b128 v[192:195], v153 offset:1024
	ds_read_b128 v[196:199], v153 offset:2048
	ds_read_b128 v[200:203], v153 offset:3072
	ds_read_b128 v[204:207], v153 offset:4096
	ds_read_b128 v[208:211], v153 offset:5120
	ds_read_b128 v[212:215], v153 offset:6144
	ds_read_b128 v[216:219], v153 offset:7168
	global_load_lds_dwordx4 v[146:147], off
	v_lshl_add_u64 v[146:147], s[34:35], 0, v[140:141]
	s_add_i32 m0, s31, 0xe000
	s_nop 0
	global_load_lds_dwordx4 v[146:147], off
	s_waitcnt vmcnt(8)
	s_waitcnt lgkmcnt(0)
	s_waitcnt lgkmcnt(0)
	v_mfma_f32_16x16x32_bf16 v[126:129], v[154:157], v[188:191], v[126:129]
	v_mfma_f32_16x16x32_bf16 v[122:125], v[164:167], v[188:191], v[122:125]
	v_mfma_f32_16x16x32_bf16 v[110:113], v[154:157], v[196:199], v[110:113]
	v_mfma_f32_16x16x32_bf16 v[106:109], v[164:167], v[196:199], v[106:109]
	s_barrier
	s_setprio 1
	v_mfma_f32_16x16x32_bf16 v[94:97], v[154:157], v[204:207], v[94:97]
	v_mfma_f32_16x16x32_bf16 v[90:93], v[164:167], v[204:207], v[90:93]
	v_mfma_f32_16x16x32_bf16 v[78:81], v[154:157], v[212:215], v[78:81]
	v_mfma_f32_16x16x32_bf16 v[74:77], v[164:167], v[212:215], v[74:77]
	v_mfma_f32_16x16x32_bf16 v[126:129], v[158:161], v[192:195], v[126:129]
	v_mfma_f32_16x16x32_bf16 v[122:125], v[168:171], v[192:195], v[122:125]
	v_mfma_f32_16x16x32_bf16 v[110:113], v[158:161], v[200:203], v[110:113]
	v_mfma_f32_16x16x32_bf16 v[106:109], v[168:171], v[200:203], v[106:109]
	v_mfma_f32_16x16x32_bf16 v[94:97], v[158:161], v[208:211], v[94:97]
	v_mfma_f32_16x16x32_bf16 v[90:93], v[168:171], v[208:211], v[90:93]
	v_mfma_f32_16x16x32_bf16 v[78:81], v[158:161], v[216:219], v[78:81]
	v_mfma_f32_16x16x32_bf16 v[74:77], v[168:171], v[216:219], v[74:77]
	s_setprio 0
	s_setprio 1
	v_mfma_f32_16x16x32_bf16 v[118:121], v[172:175], v[188:191], v[118:121]
	v_mfma_f32_16x16x32_bf16 v[114:117], v[180:183], v[188:191], v[114:117]
	v_mfma_f32_16x16x32_bf16 v[102:105], v[172:175], v[196:199], v[102:105]
	v_mfma_f32_16x16x32_bf16 v[98:101], v[180:183], v[196:199], v[98:101]
	v_mfma_f32_16x16x32_bf16 v[86:89], v[172:175], v[204:207], v[86:89]
	v_mfma_f32_16x16x32_bf16 v[82:85], v[180:183], v[204:207], v[82:85]
	v_mfma_f32_16x16x32_bf16 v[70:73], v[172:175], v[212:215], v[70:73]
	v_mfma_f32_16x16x32_bf16 v[66:69], v[180:183], v[212:215], v[66:69]
	v_mfma_f32_16x16x32_bf16 v[118:121], v[176:179], v[192:195], v[118:121]
	v_mfma_f32_16x16x32_bf16 v[114:117], v[184:187], v[192:195], v[114:117]
	v_mfma_f32_16x16x32_bf16 v[102:105], v[176:179], v[200:203], v[102:105]
	v_mfma_f32_16x16x32_bf16 v[98:101], v[184:187], v[200:203], v[98:101]
	v_mfma_f32_16x16x32_bf16 v[86:89], v[176:179], v[208:211], v[86:89]
	v_mfma_f32_16x16x32_bf16 v[82:85], v[184:187], v[208:211], v[82:85]
	v_mfma_f32_16x16x32_bf16 v[70:73], v[176:179], v[216:219], v[70:73]
	v_mfma_f32_16x16x32_bf16 v[66:69], v[184:187], v[216:219], v[66:69]
	s_setprio 0
	s_barrier
	s_add_i32 s54, s15, s44
	v_lshl_add_u64 v[146:147], s[36:37], 0, v[134:135]
	s_mov_b32 m0, s54
	ds_read_b128 v[188:191], v153 offset:16384
	ds_read_b128 v[192:195], v153 offset:17408
	ds_read_b128 v[196:199], v153 offset:18432
	ds_read_b128 v[200:203], v153 offset:19456
	ds_read_b128 v[204:207], v153 offset:20480
	ds_read_b128 v[208:211], v153 offset:21504
	ds_read_b128 v[212:215], v153 offset:22528
	ds_read_b128 v[216:219], v153 offset:23552
	global_load_lds_dwordx4 v[146:147], off
	s_add_i32 m0, s54, 0x2000
	s_add_u32 s54, s36, 0x80000
	v_lshl_add_u64 v[220:221], s[36:37], 0, v[130:131]
	s_addc_u32 s55, s37, 0
	s_add_i32 s56, s51, s44
	global_load_lds_dwordx4 v[220:221], off
	v_lshl_add_u64 v[222:223], s[54:55], 0, v[134:135]
	s_mov_b32 m0, s56
	v_lshl_add_u64 v[224:225], s[38:39], 0, v[132:133]
	global_load_lds_dwordx4 v[222:223], off
	v_lshl_add_u64 v[222:223], s[54:55], 0, v[130:131]
	s_add_i32 m0, s56, 0x2000
	s_nop 0
	global_load_lds_dwordx4 v[222:223], off
	v_lshl_add_u64 v[222:223], s[38:39], 0, v[136:137]
	s_mov_b32 m0, s31
	s_nop 0
	global_load_lds_dwordx4 v[222:223], off
	s_mov_b32 m0, s47
	s_nop 0
	global_load_lds_dwordx4 v[224:225], off
	s_waitcnt vmcnt(8)
	s_waitcnt lgkmcnt(0)
	s_waitcnt lgkmcnt(0)
	v_mfma_f32_16x16x32_bf16 v[62:65], v[154:157], v[188:191], v[62:65]
	v_mfma_f32_16x16x32_bf16 v[58:61], v[164:167], v[188:191], v[58:61]
	v_mfma_f32_16x16x32_bf16 v[46:49], v[154:157], v[196:199], v[46:49]
	v_mfma_f32_16x16x32_bf16 v[42:45], v[164:167], v[196:199], v[42:45]
	s_barrier
	s_setprio 1
	v_mfma_f32_16x16x32_bf16 v[30:33], v[154:157], v[204:207], v[30:33]
	v_mfma_f32_16x16x32_bf16 v[26:29], v[164:167], v[204:207], v[26:29]
	v_mfma_f32_16x16x32_bf16 v[14:17], v[154:157], v[212:215], v[14:17]
	v_mfma_f32_16x16x32_bf16 v[10:13], v[164:167], v[212:215], v[10:13]
	v_mfma_f32_16x16x32_bf16 v[62:65], v[158:161], v[192:195], v[62:65]
	v_mfma_f32_16x16x32_bf16 v[58:61], v[168:171], v[192:195], v[58:61]
	v_mfma_f32_16x16x32_bf16 v[46:49], v[158:161], v[200:203], v[46:49]
	v_mfma_f32_16x16x32_bf16 v[42:45], v[168:171], v[200:203], v[42:45]
	v_mfma_f32_16x16x32_bf16 v[30:33], v[158:161], v[208:211], v[30:33]
	v_mfma_f32_16x16x32_bf16 v[26:29], v[168:171], v[208:211], v[26:29]
	v_mfma_f32_16x16x32_bf16 v[14:17], v[158:161], v[216:219], v[14:17]
	v_mfma_f32_16x16x32_bf16 v[10:13], v[168:171], v[216:219], v[10:13]
	s_setprio 0
	s_setprio 1
	v_mfma_f32_16x16x32_bf16 v[54:57], v[172:175], v[188:191], v[54:57]
	v_mfma_f32_16x16x32_bf16 v[50:53], v[180:183], v[188:191], v[50:53]
	v_mfma_f32_16x16x32_bf16 v[38:41], v[172:175], v[196:199], v[38:41]
	v_mfma_f32_16x16x32_bf16 v[34:37], v[180:183], v[196:199], v[34:37]
	v_mfma_f32_16x16x32_bf16 v[22:25], v[172:175], v[204:207], v[22:25]
	v_mfma_f32_16x16x32_bf16 v[18:21], v[180:183], v[204:207], v[18:21]
	v_mfma_f32_16x16x32_bf16 v[6:9], v[172:175], v[212:215], v[6:9]
	v_mfma_f32_16x16x32_bf16 v[2:5], v[180:183], v[212:215], v[2:5]
	v_mfma_f32_16x16x32_bf16 v[54:57], v[176:179], v[192:195], v[54:57]
	v_mfma_f32_16x16x32_bf16 v[50:53], v[184:187], v[192:195], v[50:53]
	v_mfma_f32_16x16x32_bf16 v[38:41], v[176:179], v[200:203], v[38:41]
	v_mfma_f32_16x16x32_bf16 v[34:37], v[184:187], v[200:203], v[34:37]
	v_mfma_f32_16x16x32_bf16 v[22:25], v[176:179], v[208:211], v[22:25]
	v_mfma_f32_16x16x32_bf16 v[18:21], v[184:187], v[208:211], v[18:21]
	v_mfma_f32_16x16x32_bf16 v[6:9], v[176:179], v[216:219], v[6:9]
	v_mfma_f32_16x16x32_bf16 v[2:5], v[184:187], v[216:219], v[2:5]
	s_setprio 0
	s_barrier
	s_add_i32 s54, 0, 0x18000
	v_add_u32_e32 v163, s54, v149
	s_add_i32 s55, 0, 0x1c000
	ds_read_b128 v[154:157], v163
	ds_read_b128 v[158:161], v163 offset:1024
	ds_read_b128 v[164:167], v163 offset:2048
	ds_read_b128 v[168:171], v163 offset:3072
	v_add_u32_e32 v163, s55, v149
	ds_read_b128 v[172:175], v163
	ds_read_b128 v[176:179], v163 offset:1024
	ds_read_b128 v[180:183], v163 offset:2048
	ds_read_b128 v[184:187], v163 offset:3072
	s_add_u32 s38, s38, 0x80000
	s_addc_u32 s39, s39, 0
	s_mov_b32 m0, s48
	v_lshl_add_u64 v[226:227], s[38:39], 0, v[136:137]
	ds_read_b128 v[188:191], v153 offset:32768
	ds_read_b128 v[192:195], v153 offset:33792
	ds_read_b128 v[196:199], v153 offset:34816
	ds_read_b128 v[200:203], v153 offset:35840
	ds_read_b128 v[204:207], v153 offset:36864
	ds_read_b128 v[208:211], v153 offset:37888
	ds_read_b128 v[212:215], v153 offset:38912
	ds_read_b128 v[216:219], v153 offset:39936
	global_load_lds_dwordx4 v[226:227], off
	v_lshl_add_u64 v[226:227], s[38:39], 0, v[132:133]
	s_mov_b32 m0, s49
	s_nop 0
	global_load_lds_dwordx4 v[226:227], off
	s_waitcnt vmcnt(8)
	s_waitcnt lgkmcnt(0)
	s_waitcnt lgkmcnt(0)
	v_mfma_f32_16x16x32_bf16 v[126:129], v[154:157], v[188:191], v[126:129]
	v_mfma_f32_16x16x32_bf16 v[122:125], v[164:167], v[188:191], v[122:125]
	v_mfma_f32_16x16x32_bf16 v[110:113], v[154:157], v[196:199], v[110:113]
	v_mfma_f32_16x16x32_bf16 v[106:109], v[164:167], v[196:199], v[106:109]
	s_barrier
	s_setprio 1
	v_mfma_f32_16x16x32_bf16 v[94:97], v[154:157], v[204:207], v[94:97]
	v_mfma_f32_16x16x32_bf16 v[90:93], v[164:167], v[204:207], v[90:93]
	v_mfma_f32_16x16x32_bf16 v[78:81], v[154:157], v[212:215], v[78:81]
	v_mfma_f32_16x16x32_bf16 v[74:77], v[164:167], v[212:215], v[74:77]
	v_mfma_f32_16x16x32_bf16 v[126:129], v[158:161], v[192:195], v[126:129]
	v_mfma_f32_16x16x32_bf16 v[122:125], v[168:171], v[192:195], v[122:125]
	v_mfma_f32_16x16x32_bf16 v[110:113], v[158:161], v[200:203], v[110:113]
	v_mfma_f32_16x16x32_bf16 v[106:109], v[168:171], v[200:203], v[106:109]
	v_mfma_f32_16x16x32_bf16 v[94:97], v[158:161], v[208:211], v[94:97]
	v_mfma_f32_16x16x32_bf16 v[90:93], v[168:171], v[208:211], v[90:93]
	v_mfma_f32_16x16x32_bf16 v[78:81], v[158:161], v[216:219], v[78:81]
	v_mfma_f32_16x16x32_bf16 v[74:77], v[168:171], v[216:219], v[74:77]
	s_setprio 0
	s_setprio 1
	v_mfma_f32_16x16x32_bf16 v[118:121], v[172:175], v[188:191], v[118:121]
	v_mfma_f32_16x16x32_bf16 v[114:117], v[180:183], v[188:191], v[114:117]
	v_mfma_f32_16x16x32_bf16 v[102:105], v[172:175], v[196:199], v[102:105]
	v_mfma_f32_16x16x32_bf16 v[98:101], v[180:183], v[196:199], v[98:101]
	v_mfma_f32_16x16x32_bf16 v[86:89], v[172:175], v[204:207], v[86:89]
	v_mfma_f32_16x16x32_bf16 v[82:85], v[180:183], v[204:207], v[82:85]
	v_mfma_f32_16x16x32_bf16 v[70:73], v[172:175], v[212:215], v[70:73]
	v_mfma_f32_16x16x32_bf16 v[66:69], v[180:183], v[212:215], v[66:69]
	v_mfma_f32_16x16x32_bf16 v[118:121], v[176:179], v[192:195], v[118:121]
	v_mfma_f32_16x16x32_bf16 v[114:117], v[184:187], v[192:195], v[114:117]
	v_mfma_f32_16x16x32_bf16 v[102:105], v[176:179], v[200:203], v[102:105]
	v_mfma_f32_16x16x32_bf16 v[98:101], v[184:187], v[200:203], v[98:101]
	v_mfma_f32_16x16x32_bf16 v[86:89], v[176:179], v[208:211], v[86:89]
	v_mfma_f32_16x16x32_bf16 v[82:85], v[184:187], v[208:211], v[82:85]
	v_mfma_f32_16x16x32_bf16 v[70:73], v[176:179], v[216:219], v[70:73]
	v_mfma_f32_16x16x32_bf16 v[66:69], v[184:187], v[216:219], v[66:69]
	s_setprio 0
	s_barrier
	s_add_i32 s38, s54, s44
	v_lshl_add_u64 v[146:147], v[146:147], 0, s[10:11]
	s_mov_b32 m0, s38
	ds_read_b128 v[188:191], v153 offset:49152
	ds_read_b128 v[192:195], v153 offset:50176
	ds_read_b128 v[196:199], v153 offset:51200
	ds_read_b128 v[200:203], v153 offset:52224
	ds_read_b128 v[204:207], v153 offset:53248
	ds_read_b128 v[208:211], v153 offset:54272
	ds_read_b128 v[212:215], v153 offset:55296
	ds_read_b128 v[216:219], v153 offset:56320
	global_load_lds_dwordx4 v[146:147], off
	s_add_i32 m0, s38, 0x2000
	s_add_u32 s36, s36, 0x80080
	v_lshl_add_u64 v[146:147], v[220:221], 0, s[10:11]
	s_addc_u32 s37, s37, 0
	s_add_i32 s38, s55, s44
	global_load_lds_dwordx4 v[146:147], off
	v_lshl_add_u64 v[146:147], s[36:37], 0, v[134:135]
	s_mov_b32 m0, s38
	s_nop 0
	global_load_lds_dwordx4 v[146:147], off
	v_lshl_add_u64 v[146:147], s[36:37], 0, v[130:131]
	s_add_i32 m0, s38, 0x2000
	s_nop 0
	global_load_lds_dwordx4 v[146:147], off
	v_lshl_add_u64 v[146:147], v[222:223], 0, s[10:11]
	s_mov_b32 m0, s20
	s_nop 0
	global_load_lds_dwordx4 v[146:147], off
	v_lshl_add_u64 v[146:147], v[224:225], 0, s[10:11]
	s_mov_b32 m0, s21
	s_nop 0
	global_load_lds_dwordx4 v[146:147], off
	s_waitcnt vmcnt(8)
	s_waitcnt lgkmcnt(0)
	s_waitcnt lgkmcnt(0)
	v_mfma_f32_16x16x32_bf16 v[62:65], v[154:157], v[188:191], v[62:65]
	v_mfma_f32_16x16x32_bf16 v[58:61], v[164:167], v[188:191], v[58:61]
	v_mfma_f32_16x16x32_bf16 v[46:49], v[154:157], v[196:199], v[46:49]
	v_mfma_f32_16x16x32_bf16 v[42:45], v[164:167], v[196:199], v[42:45]
	s_barrier
	s_setprio 1
	v_mfma_f32_16x16x32_bf16 v[30:33], v[154:157], v[204:207], v[30:33]
	v_mfma_f32_16x16x32_bf16 v[26:29], v[164:167], v[204:207], v[26:29]
	v_mfma_f32_16x16x32_bf16 v[14:17], v[154:157], v[212:215], v[14:17]
	v_mfma_f32_16x16x32_bf16 v[10:13], v[164:167], v[212:215], v[10:13]
	v_mfma_f32_16x16x32_bf16 v[62:65], v[158:161], v[192:195], v[62:65]
	v_mfma_f32_16x16x32_bf16 v[58:61], v[168:171], v[192:195], v[58:61]
	v_mfma_f32_16x16x32_bf16 v[46:49], v[158:161], v[200:203], v[46:49]
	v_mfma_f32_16x16x32_bf16 v[42:45], v[168:171], v[200:203], v[42:45]
	v_mfma_f32_16x16x32_bf16 v[30:33], v[158:161], v[208:211], v[30:33]
	v_mfma_f32_16x16x32_bf16 v[26:29], v[168:171], v[208:211], v[26:29]
	v_mfma_f32_16x16x32_bf16 v[14:17], v[158:161], v[216:219], v[14:17]
	v_mfma_f32_16x16x32_bf16 v[10:13], v[168:171], v[216:219], v[10:13]
	s_setprio 0
	s_setprio 1
	v_mfma_f32_16x16x32_bf16 v[54:57], v[172:175], v[188:191], v[54:57]
	v_mfma_f32_16x16x32_bf16 v[50:53], v[180:183], v[188:191], v[50:53]
	v_mfma_f32_16x16x32_bf16 v[38:41], v[172:175], v[196:199], v[38:41]
	v_mfma_f32_16x16x32_bf16 v[34:37], v[180:183], v[196:199], v[34:37]
	v_mfma_f32_16x16x32_bf16 v[22:25], v[172:175], v[204:207], v[22:25]
	v_mfma_f32_16x16x32_bf16 v[18:21], v[180:183], v[204:207], v[18:21]
	v_mfma_f32_16x16x32_bf16 v[6:9], v[172:175], v[212:215], v[6:9]
	v_mfma_f32_16x16x32_bf16 v[2:5], v[180:183], v[212:215], v[2:5]
	v_mfma_f32_16x16x32_bf16 v[54:57], v[176:179], v[192:195], v[54:57]
	v_mfma_f32_16x16x32_bf16 v[50:53], v[184:187], v[192:195], v[50:53]
	v_mfma_f32_16x16x32_bf16 v[38:41], v[176:179], v[200:203], v[38:41]
	v_mfma_f32_16x16x32_bf16 v[34:37], v[184:187], v[200:203], v[34:37]
	v_mfma_f32_16x16x32_bf16 v[22:25], v[176:179], v[208:211], v[22:25]
	v_mfma_f32_16x16x32_bf16 v[18:21], v[184:187], v[208:211], v[18:21]
	v_mfma_f32_16x16x32_bf16 v[6:9], v[176:179], v[216:219], v[6:9]
	v_mfma_f32_16x16x32_bf16 v[2:5], v[184:187], v[216:219], v[2:5]
	s_setprio 0
	s_barrier
	s_add_i32 s53, s53, 2
	s_add_u32 s34, s34, 0x100
	s_addc_u32 s35, s35, 0
	s_add_u32 s23, s23, 0x100
	s_addc_u32 s25, s25, 0
	s_cmp_gt_u32 s53, 29
	s_cbranch_scc0 .LBB0_285
	s_and_b64 vcc, exec, s[12:13]
	s_cbranch_vccz .LBB0_288
	s_barrier

.LBB0_356:
	ds_read_b128 v[134:137], v213
	ds_read_b128 v[138:141], v213 offset:1024
	ds_read_b128 v[142:145], v213 offset:2048
	ds_read_b128 v[178:181], v213 offset:3072
	ds_read_b128 v[182:185], v214
	ds_read_b128 v[186:189], v214 offset:1024
	ds_read_b128 v[190:193], v214 offset:2048
	ds_read_b128 v[194:197], v214 offset:3072
	s_add_u32 s36, s34, 0x100
	s_addc_u32 s37, s35, 0
	s_add_u32 s16, s3, s34
	s_addc_u32 s17, s14, s35
	s_cmpk_eq_i32 s15, 0x54
	s_cselect_b32 s41, s27, s17
	s_cselect_b32 s17, 0, s36
	s_cselect_b32 s40, s26, s16
	s_cselect_b32 s16, 0, s37
	s_add_u32 s38, s8, s17
	s_addc_u32 s39, s9, s16
	s_mov_b32 m0, s63
	v_lshl_add_u64 v[244:245], v[130:131], 0, s[34:35]
	ds_read_b128 v[198:201], v215
	ds_read_b128 v[202:205], v215 offset:1024
	ds_read_b128 v[206:209], v215 offset:2048
	ds_read_b128 v[224:227], v215 offset:3072
	ds_read_b128 v[228:231], v215 offset:4096
	ds_read_b128 v[232:235], v215 offset:5120
	ds_read_b128 v[236:239], v215 offset:6144
	ds_read_b128 v[240:243], v215 offset:7168
	global_load_lds_dwordx4 v[244:245], off
	v_lshl_add_u64 v[244:245], v[132:133], 0, s[34:35]
	s_mov_b32 m0, s64
	s_nop 0
	global_load_lds_dwordx4 v[244:245], off
	s_waitcnt vmcnt(8)
	s_waitcnt lgkmcnt(0)
	s_waitcnt lgkmcnt(0)
	v_mfma_f32_16x16x32_bf16 v[86:89], v[134:137], v[198:201], v[86:89]
	v_mfma_f32_16x16x32_bf16 v[82:85], v[142:145], v[198:201], v[82:85]
	v_mfma_f32_16x16x32_bf16 v[110:113], v[134:137], v[206:209], v[110:113]
	v_mfma_f32_16x16x32_bf16 v[106:109], v[142:145], v[206:209], v[106:109]
	s_barrier
	s_setprio 1
	v_mfma_f32_16x16x32_bf16 v[118:121], v[134:137], v[228:231], v[118:121]
	v_mfma_f32_16x16x32_bf16 v[114:117], v[142:145], v[228:231], v[114:117]
	v_mfma_f32_16x16x32_bf16 v[126:129], v[134:137], v[236:239], v[126:129]
	v_mfma_f32_16x16x32_bf16 v[122:125], v[142:145], v[236:239], v[122:125]
	v_mfma_f32_16x16x32_bf16 v[86:89], v[138:141], v[202:205], v[86:89]
	v_mfma_f32_16x16x32_bf16 v[82:85], v[178:181], v[202:205], v[82:85]
	v_mfma_f32_16x16x32_bf16 v[110:113], v[138:141], v[224:227], v[110:113]
	v_mfma_f32_16x16x32_bf16 v[106:109], v[178:181], v[224:227], v[106:109]
	v_mfma_f32_16x16x32_bf16 v[118:121], v[138:141], v[232:235], v[118:121]
	v_mfma_f32_16x16x32_bf16 v[114:117], v[178:181], v[232:235], v[114:117]
	v_mfma_f32_16x16x32_bf16 v[126:129], v[138:141], v[240:243], v[126:129]
	v_mfma_f32_16x16x32_bf16 v[122:125], v[178:181], v[240:243], v[122:125]
	s_setprio 0
	s_setprio 1
	v_mfma_f32_16x16x32_bf16 v[26:29], v[182:185], v[198:201], v[26:29]
	v_mfma_f32_16x16x32_bf16 v[30:33], v[190:193], v[198:201], v[30:33]
	v_mfma_f32_16x16x32_bf16 v[42:45], v[182:185], v[206:209], v[42:45]
	v_mfma_f32_16x16x32_bf16 v[50:53], v[190:193], v[206:209], v[50:53]
	v_mfma_f32_16x16x32_bf16 v[66:69], v[182:185], v[228:231], v[66:69]
	v_mfma_f32_16x16x32_bf16 v[70:73], v[190:193], v[228:231], v[70:73]
	v_mfma_f32_16x16x32_bf16 v[90:93], v[182:185], v[236:239], v[90:93]
	v_mfma_f32_16x16x32_bf16 v[94:97], v[190:193], v[236:239], v[94:97]
	v_mfma_f32_16x16x32_bf16 v[26:29], v[186:189], v[202:205], v[26:29]
	v_mfma_f32_16x16x32_bf16 v[30:33], v[194:197], v[202:205], v[30:33]
	v_mfma_f32_16x16x32_bf16 v[42:45], v[186:189], v[224:227], v[42:45]
	v_mfma_f32_16x16x32_bf16 v[50:53], v[194:197], v[224:227], v[50:53]
	v_mfma_f32_16x16x32_bf16 v[66:69], v[186:189], v[232:235], v[66:69]
	v_mfma_f32_16x16x32_bf16 v[70:73], v[194:197], v[232:235], v[70:73]
	v_mfma_f32_16x16x32_bf16 v[90:93], v[186:189], v[240:243], v[90:93]
	v_mfma_f32_16x16x32_bf16 v[94:97], v[194:197], v[240:243], v[94:97]
	s_setprio 0
	s_barrier
	s_mov_b32 m0, s65
	v_lshl_add_u64 v[244:245], s[38:39], 0, v[150:151]
	s_add_u32 s16, s38, 0x160000
	ds_read_b128 v[198:201], v215 offset:16384
	ds_read_b128 v[202:205], v215 offset:17408
	ds_read_b128 v[206:209], v215 offset:18432
	ds_read_b128 v[224:227], v215 offset:19456
	ds_read_b128 v[228:231], v215 offset:20480
	ds_read_b128 v[232:235], v215 offset:21504
	ds_read_b128 v[236:239], v215 offset:22528
	ds_read_b128 v[240:243], v215 offset:23552
	global_load_lds_dwordx4 v[244:245], off
	v_lshl_add_u64 v[246:247], s[38:39], 0, v[146:147]
	s_mov_b32 m0, s66
	s_addc_u32 s17, s39, 0
	global_load_lds_dwordx4 v[246:247], off
	v_lshl_add_u64 v[248:249], s[16:17], 0, v[150:151]
	s_mov_b32 m0, s67
	v_lshl_add_u64 v[250:251], s[40:41], 0, v[148:149]
	global_load_lds_dwordx4 v[248:249], off
	v_lshl_add_u64 v[248:249], s[16:17], 0, v[146:147]
	s_mov_b32 m0, s68
	s_nop 0
	global_load_lds_dwordx4 v[248:249], off
	v_lshl_add_u64 v[248:249], s[40:41], 0, v[152:153]
	s_mov_b32 m0, s51
	s_nop 0
	global_load_lds_dwordx4 v[248:249], off
	s_mov_b32 m0, s52
	s_nop 0
	global_load_lds_dwordx4 v[250:251], off
	s_waitcnt vmcnt(8)
	s_waitcnt lgkmcnt(0)
	s_waitcnt lgkmcnt(0)
	v_mfma_f32_16x16x32_bf16 v[102:105], v[134:137], v[198:201], v[102:105]
	v_mfma_f32_16x16x32_bf16 v[98:101], v[142:145], v[198:201], v[98:101]
	v_mfma_f32_16x16x32_bf16 v[62:65], v[134:137], v[206:209], v[62:65]
	v_mfma_f32_16x16x32_bf16 v[58:61], v[142:145], v[206:209], v[58:61]
	s_barrier
	s_setprio 1
	v_mfma_f32_16x16x32_bf16 v[38:41], v[134:137], v[228:231], v[38:41]
	v_mfma_f32_16x16x32_bf16 v[34:37], v[142:145], v[228:231], v[34:37]
	v_mfma_f32_16x16x32_bf16 v[14:17], v[134:137], v[236:239], v[14:17]
	v_mfma_f32_16x16x32_bf16 v[10:13], v[142:145], v[236:239], v[10:13]
	v_mfma_f32_16x16x32_bf16 v[102:105], v[138:141], v[202:205], v[102:105]
	v_mfma_f32_16x16x32_bf16 v[98:101], v[178:181], v[202:205], v[98:101]
	v_mfma_f32_16x16x32_bf16 v[62:65], v[138:141], v[224:227], v[62:65]
	v_mfma_f32_16x16x32_bf16 v[58:61], v[178:181], v[224:227], v[58:61]
	v_mfma_f32_16x16x32_bf16 v[38:41], v[138:141], v[232:235], v[38:41]
	v_mfma_f32_16x16x32_bf16 v[34:37], v[178:181], v[232:235], v[34:37]
	v_mfma_f32_16x16x32_bf16 v[14:17], v[138:141], v[240:243], v[14:17]
	v_mfma_f32_16x16x32_bf16 v[10:13], v[178:181], v[240:243], v[10:13]
	s_setprio 0
	s_setprio 1
	v_mfma_f32_16x16x32_bf16 v[78:81], v[182:185], v[198:201], v[78:81]
	v_mfma_f32_16x16x32_bf16 v[74:77], v[190:193], v[198:201], v[74:77]
	v_mfma_f32_16x16x32_bf16 v[54:57], v[182:185], v[206:209], v[54:57]
	v_mfma_f32_16x16x32_bf16 v[46:49], v[190:193], v[206:209], v[46:49]
	v_mfma_f32_16x16x32_bf16 v[22:25], v[182:185], v[228:231], v[22:25]
	v_mfma_f32_16x16x32_bf16 v[18:21], v[190:193], v[228:231], v[18:21]
	v_mfma_f32_16x16x32_bf16 v[6:9], v[182:185], v[236:239], v[6:9]
	v_mfma_f32_16x16x32_bf16 v[2:5], v[190:193], v[236:239], v[2:5]
	v_mfma_f32_16x16x32_bf16 v[78:81], v[186:189], v[202:205], v[78:81]
	v_mfma_f32_16x16x32_bf16 v[74:77], v[194:197], v[202:205], v[74:77]
	v_mfma_f32_16x16x32_bf16 v[54:57], v[186:189], v[224:227], v[54:57]
	v_mfma_f32_16x16x32_bf16 v[46:49], v[194:197], v[224:227], v[46:49]
	v_mfma_f32_16x16x32_bf16 v[22:25], v[186:189], v[232:235], v[22:25]
	v_mfma_f32_16x16x32_bf16 v[18:21], v[194:197], v[232:235], v[18:21]
	v_mfma_f32_16x16x32_bf16 v[6:9], v[186:189], v[240:243], v[6:9]
	v_mfma_f32_16x16x32_bf16 v[2:5], v[194:197], v[240:243], v[2:5]
	s_setprio 0
	s_barrier
	ds_read_b128 v[134:137], v219
	ds_read_b128 v[138:141], v219 offset:1024
	ds_read_b128 v[142:145], v219 offset:2048
	ds_read_b128 v[178:181], v219 offset:3072
	ds_read_b128 v[182:185], v220
	ds_read_b128 v[186:189], v220 offset:1024
	ds_read_b128 v[190:193], v220 offset:2048
	ds_read_b128 v[194:197], v220 offset:3072
	s_add_u32 s16, s40, 0x160000
	s_addc_u32 s17, s41, 0
	s_mov_b32 m0, s53
	v_lshl_add_u64 v[252:253], s[16:17], 0, v[152:153]
	ds_read_b128 v[198:201], v215 offset:32768
	ds_read_b128 v[202:205], v215 offset:33792
	ds_read_b128 v[206:209], v215 offset:34816
	ds_read_b128 v[224:227], v215 offset:35840
	ds_read_b128 v[228:231], v215 offset:36864
	ds_read_b128 v[232:235], v215 offset:37888
	ds_read_b128 v[236:239], v215 offset:38912
	ds_read_b128 v[240:243], v215 offset:39936
	global_load_lds_dwordx4 v[252:253], off
	v_lshl_add_u64 v[252:253], s[16:17], 0, v[148:149]
	s_mov_b32 m0, s54
	s_nop 0
	global_load_lds_dwordx4 v[252:253], off
	s_waitcnt vmcnt(8)
	s_waitcnt lgkmcnt(0)
	s_waitcnt lgkmcnt(0)
	v_mfma_f32_16x16x32_bf16 v[86:89], v[134:137], v[198:201], v[86:89]
	v_mfma_f32_16x16x32_bf16 v[82:85], v[142:145], v[198:201], v[82:85]
	v_mfma_f32_16x16x32_bf16 v[110:113], v[134:137], v[206:209], v[110:113]
	v_mfma_f32_16x16x32_bf16 v[106:109], v[142:145], v[206:209], v[106:109]
	s_barrier
	s_setprio 1
	v_mfma_f32_16x16x32_bf16 v[118:121], v[134:137], v[228:231], v[118:121]
	v_mfma_f32_16x16x32_bf16 v[114:117], v[142:145], v[228:231], v[114:117]
	v_mfma_f32_16x16x32_bf16 v[126:129], v[134:137], v[236:239], v[126:129]
	v_mfma_f32_16x16x32_bf16 v[122:125], v[142:145], v[236:239], v[122:125]
	v_mfma_f32_16x16x32_bf16 v[86:89], v[138:141], v[202:205], v[86:89]
	v_mfma_f32_16x16x32_bf16 v[82:85], v[178:181], v[202:205], v[82:85]
	v_mfma_f32_16x16x32_bf16 v[110:113], v[138:141], v[224:227], v[110:113]
	v_mfma_f32_16x16x32_bf16 v[106:109], v[178:181], v[224:227], v[106:109]
	v_mfma_f32_16x16x32_bf16 v[118:121], v[138:141], v[232:235], v[118:121]
	v_mfma_f32_16x16x32_bf16 v[114:117], v[178:181], v[232:235], v[114:117]
	v_mfma_f32_16x16x32_bf16 v[126:129], v[138:141], v[240:243], v[126:129]
	v_mfma_f32_16x16x32_bf16 v[122:125], v[178:181], v[240:243], v[122:125]
	s_setprio 0
	s_setprio 1
	v_mfma_f32_16x16x32_bf16 v[26:29], v[182:185], v[198:201], v[26:29]
	v_mfma_f32_16x16x32_bf16 v[30:33], v[190:193], v[198:201], v[30:33]
	v_mfma_f32_16x16x32_bf16 v[42:45], v[182:185], v[206:209], v[42:45]
	v_mfma_f32_16x16x32_bf16 v[50:53], v[190:193], v[206:209], v[50:53]
	v_mfma_f32_16x16x32_bf16 v[66:69], v[182:185], v[228:231], v[66:69]
	v_mfma_f32_16x16x32_bf16 v[70:73], v[190:193], v[228:231], v[70:73]
	v_mfma_f32_16x16x32_bf16 v[90:93], v[182:185], v[236:239], v[90:93]
	v_mfma_f32_16x16x32_bf16 v[94:97], v[190:193], v[236:239], v[94:97]
	v_mfma_f32_16x16x32_bf16 v[26:29], v[186:189], v[202:205], v[26:29]
	v_mfma_f32_16x16x32_bf16 v[30:33], v[194:197], v[202:205], v[30:33]
	v_mfma_f32_16x16x32_bf16 v[42:45], v[186:189], v[224:227], v[42:45]
	v_mfma_f32_16x16x32_bf16 v[50:53], v[194:197], v[224:227], v[50:53]
	v_mfma_f32_16x16x32_bf16 v[66:69], v[186:189], v[232:235], v[66:69]
	v_mfma_f32_16x16x32_bf16 v[70:73], v[194:197], v[232:235], v[70:73]
	v_mfma_f32_16x16x32_bf16 v[90:93], v[186:189], v[240:243], v[90:93]
	v_mfma_f32_16x16x32_bf16 v[94:97], v[194:197], v[240:243], v[94:97]
	s_setprio 0
	s_barrier
	s_mov_b32 m0, s69
	v_lshl_add_u64 v[244:245], v[244:245], 0, s[22:23]
	s_add_u32 s16, s38, 0x160080
	ds_read_b128 v[198:201], v215 offset:49152
	ds_read_b128 v[202:205], v215 offset:50176
	ds_read_b128 v[206:209], v215 offset:51200
	ds_read_b128 v[224:227], v215 offset:52224
	ds_read_b128 v[228:231], v215 offset:53248
	ds_read_b128 v[232:235], v215 offset:54272
	ds_read_b128 v[236:239], v215 offset:55296
	ds_read_b128 v[240:243], v215 offset:56320
	global_load_lds_dwordx4 v[244:245], off
	v_lshl_add_u64 v[244:245], v[246:247], 0, s[22:23]
	s_mov_b32 m0, s73
	s_addc_u32 s17, s39, 0
	global_load_lds_dwordx4 v[244:245], off
	v_lshl_add_u64 v[244:245], s[16:17], 0, v[150:151]
	s_mov_b32 m0, s74
	s_nop 0
	global_load_lds_dwordx4 v[244:245], off
	v_lshl_add_u64 v[244:245], s[16:17], 0, v[146:147]
	s_mov_b32 m0, s75
	s_nop 0
	global_load_lds_dwordx4 v[244:245], off
	v_lshl_add_u64 v[244:245], v[248:249], 0, s[22:23]
	s_mov_b32 m0, s60
	s_nop 0
	global_load_lds_dwordx4 v[244:245], off
	v_lshl_add_u64 v[244:245], v[250:251], 0, s[22:23]
	s_mov_b32 m0, s61
	s_nop 0
	global_load_lds_dwordx4 v[244:245], off
	s_waitcnt vmcnt(8)
	s_waitcnt lgkmcnt(0)
	s_waitcnt lgkmcnt(0)
	v_mfma_f32_16x16x32_bf16 v[102:105], v[134:137], v[198:201], v[102:105]
	v_mfma_f32_16x16x32_bf16 v[98:101], v[142:145], v[198:201], v[98:101]
	v_mfma_f32_16x16x32_bf16 v[62:65], v[134:137], v[206:209], v[62:65]
	v_mfma_f32_16x16x32_bf16 v[58:61], v[142:145], v[206:209], v[58:61]
	s_barrier
	s_setprio 1
	v_mfma_f32_16x16x32_bf16 v[38:41], v[134:137], v[228:231], v[38:41]
	v_mfma_f32_16x16x32_bf16 v[34:37], v[142:145], v[228:231], v[34:37]
	v_mfma_f32_16x16x32_bf16 v[14:17], v[134:137], v[236:239], v[14:17]
	v_mfma_f32_16x16x32_bf16 v[10:13], v[142:145], v[236:239], v[10:13]
	v_mfma_f32_16x16x32_bf16 v[102:105], v[138:141], v[202:205], v[102:105]
	v_mfma_f32_16x16x32_bf16 v[98:101], v[178:181], v[202:205], v[98:101]
	v_mfma_f32_16x16x32_bf16 v[62:65], v[138:141], v[224:227], v[62:65]
	v_mfma_f32_16x16x32_bf16 v[58:61], v[178:181], v[224:227], v[58:61]
	v_mfma_f32_16x16x32_bf16 v[38:41], v[138:141], v[232:235], v[38:41]
	v_mfma_f32_16x16x32_bf16 v[34:37], v[178:181], v[232:235], v[34:37]
	v_mfma_f32_16x16x32_bf16 v[14:17], v[138:141], v[240:243], v[14:17]
	v_mfma_f32_16x16x32_bf16 v[10:13], v[178:181], v[240:243], v[10:13]
	s_setprio 0
	s_setprio 1
	v_mfma_f32_16x16x32_bf16 v[78:81], v[182:185], v[198:201], v[78:81]
	v_mfma_f32_16x16x32_bf16 v[74:77], v[190:193], v[198:201], v[74:77]
	v_mfma_f32_16x16x32_bf16 v[54:57], v[182:185], v[206:209], v[54:57]
	v_mfma_f32_16x16x32_bf16 v[46:49], v[190:193], v[206:209], v[46:49]
	v_mfma_f32_16x16x32_bf16 v[22:25], v[182:185], v[228:231], v[22:25]
	v_mfma_f32_16x16x32_bf16 v[18:21], v[190:193], v[228:231], v[18:21]
	v_mfma_f32_16x16x32_bf16 v[6:9], v[182:185], v[236:239], v[6:9]
	v_mfma_f32_16x16x32_bf16 v[2:5], v[190:193], v[236:239], v[2:5]
	v_mfma_f32_16x16x32_bf16 v[78:81], v[186:189], v[202:205], v[78:81]
	v_mfma_f32_16x16x32_bf16 v[74:77], v[194:197], v[202:205], v[74:77]
	v_mfma_f32_16x16x32_bf16 v[54:57], v[186:189], v[224:227], v[54:57]
	v_mfma_f32_16x16x32_bf16 v[46:49], v[194:197], v[224:227], v[46:49]
	v_mfma_f32_16x16x32_bf16 v[22:25], v[186:189], v[232:235], v[22:25]
	v_mfma_f32_16x16x32_bf16 v[18:21], v[194:197], v[232:235], v[18:21]
	v_mfma_f32_16x16x32_bf16 v[6:9], v[186:189], v[240:243], v[6:9]
	v_mfma_f32_16x16x32_bf16 v[2:5], v[194:197], v[240:243], v[2:5]
	s_setprio 0
	s_barrier
	s_add_i32 s15, s15, 2
	s_cmpk_gt_u32 s15, 0x55
	s_mov_b64 s[34:35], s[36:37]
	s_cbranch_scc0 .LBB0_356
	s_and_b64 vcc, exec, s[24:25]
	s_cbranch_vccz .LBB0_359
	s_barrier

.LBB0_466:
	ds_read_b128 v[130:133], v170
	ds_read_b128 v[134:137], v170 offset:1024
	ds_read_b128 v[164:167], v170 offset:2048
	ds_read_b128 v[174:177], v170 offset:3072
	ds_read_b128 v[178:181], v171
	ds_read_b128 v[182:185], v171 offset:1024
	ds_read_b128 v[186:189], v171 offset:2048
	ds_read_b128 v[190:193], v171 offset:3072
	s_add_u32 s19, s42, 0xfff80080
	s_addc_u32 s20, s43, -1
	s_cmp_eq_u32 s18, 28
	s_cselect_b32 s47, s3, s20
	s_cselect_b32 s46, s7, s19
	s_cselect_b32 s45, s14, s17
	s_cselect_b32 s44, s15, s16
	v_lshl_add_u64 v[168:169], s[42:43], 0, v[154:155]
	s_add_i32 m0, s41, 0xc000
	ds_read_b128 v[194:197], v172
	ds_read_b128 v[198:201], v172 offset:1024
	ds_read_b128 v[202:205], v172 offset:2048
	ds_read_b128 v[206:209], v172 offset:3072
	ds_read_b128 v[210:213], v172 offset:4096
	ds_read_b128 v[214:217], v172 offset:5120
	ds_read_b128 v[218:221], v172 offset:6144
	ds_read_b128 v[222:225], v172 offset:7168
	global_load_lds_dwordx4 v[168:169], off
	v_lshl_add_u64 v[168:169], s[42:43], 0, v[156:157]
	s_add_i32 m0, s41, 0xe000
	s_nop 0
	global_load_lds_dwordx4 v[168:169], off
	s_waitcnt vmcnt(8)
	s_waitcnt lgkmcnt(0)
	s_waitcnt lgkmcnt(0)
	v_mfma_f32_16x16x32_bf16 v[126:129], v[130:133], v[194:197], v[126:129]
	v_mfma_f32_16x16x32_bf16 v[122:125], v[164:167], v[194:197], v[122:125]
	v_mfma_f32_16x16x32_bf16 v[110:113], v[130:133], v[202:205], v[110:113]
	v_mfma_f32_16x16x32_bf16 v[106:109], v[164:167], v[202:205], v[106:109]
	s_barrier
	s_setprio 1
	v_mfma_f32_16x16x32_bf16 v[94:97], v[130:133], v[210:213], v[94:97]
	v_mfma_f32_16x16x32_bf16 v[90:93], v[164:167], v[210:213], v[90:93]
	v_mfma_f32_16x16x32_bf16 v[78:81], v[130:133], v[218:221], v[78:81]
	v_mfma_f32_16x16x32_bf16 v[74:77], v[164:167], v[218:221], v[74:77]
	v_mfma_f32_16x16x32_bf16 v[126:129], v[134:137], v[198:201], v[126:129]
	v_mfma_f32_16x16x32_bf16 v[122:125], v[174:177], v[198:201], v[122:125]
	v_mfma_f32_16x16x32_bf16 v[110:113], v[134:137], v[206:209], v[110:113]
	v_mfma_f32_16x16x32_bf16 v[106:109], v[174:177], v[206:209], v[106:109]
	v_mfma_f32_16x16x32_bf16 v[94:97], v[134:137], v[214:217], v[94:97]
	v_mfma_f32_16x16x32_bf16 v[90:93], v[174:177], v[214:217], v[90:93]
	v_mfma_f32_16x16x32_bf16 v[78:81], v[134:137], v[222:225], v[78:81]
	v_mfma_f32_16x16x32_bf16 v[74:77], v[174:177], v[222:225], v[74:77]
	s_setprio 0
	s_setprio 1
	v_mfma_f32_16x16x32_bf16 v[118:121], v[178:181], v[194:197], v[118:121]
	v_mfma_f32_16x16x32_bf16 v[114:117], v[186:189], v[194:197], v[114:117]
	v_mfma_f32_16x16x32_bf16 v[102:105], v[178:181], v[202:205], v[102:105]
	v_mfma_f32_16x16x32_bf16 v[98:101], v[186:189], v[202:205], v[98:101]
	v_mfma_f32_16x16x32_bf16 v[86:89], v[178:181], v[210:213], v[86:89]
	v_mfma_f32_16x16x32_bf16 v[82:85], v[186:189], v[210:213], v[82:85]
	v_mfma_f32_16x16x32_bf16 v[70:73], v[178:181], v[218:221], v[70:73]
	v_mfma_f32_16x16x32_bf16 v[66:69], v[186:189], v[218:221], v[66:69]
	v_mfma_f32_16x16x32_bf16 v[118:121], v[182:185], v[198:201], v[118:121]
	v_mfma_f32_16x16x32_bf16 v[114:117], v[190:193], v[198:201], v[114:117]
	v_mfma_f32_16x16x32_bf16 v[102:105], v[182:185], v[206:209], v[102:105]
	v_mfma_f32_16x16x32_bf16 v[98:101], v[190:193], v[206:209], v[98:101]
	v_mfma_f32_16x16x32_bf16 v[86:89], v[182:185], v[214:217], v[86:89]
	v_mfma_f32_16x16x32_bf16 v[82:85], v[190:193], v[214:217], v[82:85]
	v_mfma_f32_16x16x32_bf16 v[70:73], v[182:185], v[222:225], v[70:73]
	v_mfma_f32_16x16x32_bf16 v[66:69], v[190:193], v[222:225], v[66:69]
	s_setprio 0
	s_barrier
	s_add_i32 s19, s75, s52
	v_lshl_add_u64 v[168:169], s[44:45], 0, v[140:141]
	s_mov_b32 m0, s19
	ds_read_b128 v[194:197], v172 offset:16384
	ds_read_b128 v[198:201], v172 offset:17408
	ds_read_b128 v[202:205], v172 offset:18432
	ds_read_b128 v[206:209], v172 offset:19456
	ds_read_b128 v[210:213], v172 offset:20480
	ds_read_b128 v[214:217], v172 offset:21504
	ds_read_b128 v[218:221], v172 offset:22528
	ds_read_b128 v[222:225], v172 offset:23552
	global_load_lds_dwordx4 v[168:169], off
	s_add_i32 m0, s19, 0x2000
	s_add_u32 s20, s44, 0x80000
	v_lshl_add_u64 v[226:227], s[44:45], 0, v[144:145]
	s_addc_u32 s21, s45, 0
	s_add_i32 s19, s76, s52
	global_load_lds_dwordx4 v[226:227], off
	v_lshl_add_u64 v[228:229], s[20:21], 0, v[140:141]
	s_mov_b32 m0, s19
	v_lshl_add_u64 v[230:231], s[46:47], 0, v[142:143]
	global_load_lds_dwordx4 v[228:229], off
	v_lshl_add_u64 v[228:229], s[20:21], 0, v[144:145]
	s_add_i32 m0, s19, 0x2000
	s_nop 0
	global_load_lds_dwordx4 v[228:229], off
	v_lshl_add_u64 v[228:229], s[46:47], 0, v[138:139]
	s_mov_b32 m0, s41
	s_nop 0
	global_load_lds_dwordx4 v[228:229], off
	s_mov_b32 m0, s53
	s_nop 0
	global_load_lds_dwordx4 v[230:231], off
	s_waitcnt vmcnt(8)
	s_waitcnt lgkmcnt(0)
	s_waitcnt lgkmcnt(0)
	v_mfma_f32_16x16x32_bf16 v[62:65], v[130:133], v[194:197], v[62:65]
	v_mfma_f32_16x16x32_bf16 v[58:61], v[164:167], v[194:197], v[58:61]
	v_mfma_f32_16x16x32_bf16 v[46:49], v[130:133], v[202:205], v[46:49]
	v_mfma_f32_16x16x32_bf16 v[42:45], v[164:167], v[202:205], v[42:45]
	s_barrier
	s_setprio 1
	v_mfma_f32_16x16x32_bf16 v[30:33], v[130:133], v[210:213], v[30:33]
	v_mfma_f32_16x16x32_bf16 v[26:29], v[164:167], v[210:213], v[26:29]
	v_mfma_f32_16x16x32_bf16 v[14:17], v[130:133], v[218:221], v[14:17]
	v_mfma_f32_16x16x32_bf16 v[10:13], v[164:167], v[218:221], v[10:13]
	v_mfma_f32_16x16x32_bf16 v[62:65], v[134:137], v[198:201], v[62:65]
	v_mfma_f32_16x16x32_bf16 v[58:61], v[174:177], v[198:201], v[58:61]
	v_mfma_f32_16x16x32_bf16 v[46:49], v[134:137], v[206:209], v[46:49]
	v_mfma_f32_16x16x32_bf16 v[42:45], v[174:177], v[206:209], v[42:45]
	v_mfma_f32_16x16x32_bf16 v[30:33], v[134:137], v[214:217], v[30:33]
	v_mfma_f32_16x16x32_bf16 v[26:29], v[174:177], v[214:217], v[26:29]
	v_mfma_f32_16x16x32_bf16 v[14:17], v[134:137], v[222:225], v[14:17]
	v_mfma_f32_16x16x32_bf16 v[10:13], v[174:177], v[222:225], v[10:13]
	s_setprio 0
	s_setprio 1
	v_mfma_f32_16x16x32_bf16 v[54:57], v[178:181], v[194:197], v[54:57]
	v_mfma_f32_16x16x32_bf16 v[50:53], v[186:189], v[194:197], v[50:53]
	v_mfma_f32_16x16x32_bf16 v[38:41], v[178:181], v[202:205], v[38:41]
	v_mfma_f32_16x16x32_bf16 v[34:37], v[186:189], v[202:205], v[34:37]
	v_mfma_f32_16x16x32_bf16 v[22:25], v[178:181], v[210:213], v[22:25]
	v_mfma_f32_16x16x32_bf16 v[18:21], v[186:189], v[210:213], v[18:21]
	v_mfma_f32_16x16x32_bf16 v[6:9], v[178:181], v[218:221], v[6:9]
	v_mfma_f32_16x16x32_bf16 v[2:5], v[186:189], v[218:221], v[2:5]
	v_mfma_f32_16x16x32_bf16 v[54:57], v[182:185], v[198:201], v[54:57]
	v_mfma_f32_16x16x32_bf16 v[50:53], v[190:193], v[198:201], v[50:53]
	v_mfma_f32_16x16x32_bf16 v[38:41], v[182:185], v[206:209], v[38:41]
	v_mfma_f32_16x16x32_bf16 v[34:37], v[190:193], v[206:209], v[34:37]
	v_mfma_f32_16x16x32_bf16 v[22:25], v[182:185], v[214:217], v[22:25]
	v_mfma_f32_16x16x32_bf16 v[18:21], v[190:193], v[214:217], v[18:21]
	v_mfma_f32_16x16x32_bf16 v[6:9], v[182:185], v[222:225], v[6:9]
	v_mfma_f32_16x16x32_bf16 v[2:5], v[190:193], v[222:225], v[2:5]
	s_setprio 0
	s_barrier
	s_add_i32 s19, 0, 0x18000
	v_add_u32_e32 v146, s19, v163
	s_add_i32 s31, 0, 0x1c000
	ds_read_b128 v[130:133], v146
	ds_read_b128 v[134:137], v146 offset:1024
	ds_read_b128 v[164:167], v146 offset:2048
	ds_read_b128 v[174:177], v146 offset:3072
	v_add_u32_e32 v146, s31, v163
	ds_read_b128 v[178:181], v146
	ds_read_b128 v[182:185], v146 offset:1024
	ds_read_b128 v[186:189], v146 offset:2048
	ds_read_b128 v[190:193], v146 offset:3072
	s_add_u32 s20, s46, 0x80000
	s_addc_u32 s21, s47, 0
	s_mov_b32 m0, s54
	v_lshl_add_u64 v[232:233], s[20:21], 0, v[138:139]
	ds_read_b128 v[194:197], v172 offset:32768
	ds_read_b128 v[198:201], v172 offset:33792
	ds_read_b128 v[202:205], v172 offset:34816
	ds_read_b128 v[206:209], v172 offset:35840
	ds_read_b128 v[210:213], v172 offset:36864
	ds_read_b128 v[214:217], v172 offset:37888
	ds_read_b128 v[218:221], v172 offset:38912
	ds_read_b128 v[222:225], v172 offset:39936
	global_load_lds_dwordx4 v[232:233], off
	v_lshl_add_u64 v[232:233], s[20:21], 0, v[142:143]
	s_mov_b32 m0, s55
	s_nop 0
	global_load_lds_dwordx4 v[232:233], off
	s_waitcnt vmcnt(8)
	s_waitcnt lgkmcnt(0)
	s_waitcnt lgkmcnt(0)
	v_mfma_f32_16x16x32_bf16 v[126:129], v[130:133], v[194:197], v[126:129]
	v_mfma_f32_16x16x32_bf16 v[122:125], v[164:167], v[194:197], v[122:125]
	v_mfma_f32_16x16x32_bf16 v[110:113], v[130:133], v[202:205], v[110:113]
	v_mfma_f32_16x16x32_bf16 v[106:109], v[164:167], v[202:205], v[106:109]
	s_barrier
	s_setprio 1
	v_mfma_f32_16x16x32_bf16 v[94:97], v[130:133], v[210:213], v[94:97]
	v_mfma_f32_16x16x32_bf16 v[90:93], v[164:167], v[210:213], v[90:93]
	v_mfma_f32_16x16x32_bf16 v[78:81], v[130:133], v[218:221], v[78:81]
	v_mfma_f32_16x16x32_bf16 v[74:77], v[164:167], v[218:221], v[74:77]
	v_mfma_f32_16x16x32_bf16 v[126:129], v[134:137], v[198:201], v[126:129]
	v_mfma_f32_16x16x32_bf16 v[122:125], v[174:177], v[198:201], v[122:125]
	v_mfma_f32_16x16x32_bf16 v[110:113], v[134:137], v[206:209], v[110:113]
	v_mfma_f32_16x16x32_bf16 v[106:109], v[174:177], v[206:209], v[106:109]
	v_mfma_f32_16x16x32_bf16 v[94:97], v[134:137], v[214:217], v[94:97]
	v_mfma_f32_16x16x32_bf16 v[90:93], v[174:177], v[214:217], v[90:93]
	v_mfma_f32_16x16x32_bf16 v[78:81], v[134:137], v[222:225], v[78:81]
	v_mfma_f32_16x16x32_bf16 v[74:77], v[174:177], v[222:225], v[74:77]
	s_setprio 0
	s_setprio 1
	v_mfma_f32_16x16x32_bf16 v[118:121], v[178:181], v[194:197], v[118:121]
	v_mfma_f32_16x16x32_bf16 v[114:117], v[186:189], v[194:197], v[114:117]
	v_mfma_f32_16x16x32_bf16 v[102:105], v[178:181], v[202:205], v[102:105]
	v_mfma_f32_16x16x32_bf16 v[98:101], v[186:189], v[202:205], v[98:101]
	v_mfma_f32_16x16x32_bf16 v[86:89], v[178:181], v[210:213], v[86:89]
	v_mfma_f32_16x16x32_bf16 v[82:85], v[186:189], v[210:213], v[82:85]
	v_mfma_f32_16x16x32_bf16 v[70:73], v[178:181], v[218:221], v[70:73]
	v_mfma_f32_16x16x32_bf16 v[66:69], v[186:189], v[218:221], v[66:69]
	v_mfma_f32_16x16x32_bf16 v[118:121], v[182:185], v[198:201], v[118:121]
	v_mfma_f32_16x16x32_bf16 v[114:117], v[190:193], v[198:201], v[114:117]
	v_mfma_f32_16x16x32_bf16 v[102:105], v[182:185], v[206:209], v[102:105]
	v_mfma_f32_16x16x32_bf16 v[98:101], v[190:193], v[206:209], v[98:101]
	v_mfma_f32_16x16x32_bf16 v[86:89], v[182:185], v[214:217], v[86:89]
	v_mfma_f32_16x16x32_bf16 v[82:85], v[190:193], v[214:217], v[82:85]
	v_mfma_f32_16x16x32_bf16 v[70:73], v[182:185], v[222:225], v[70:73]
	v_mfma_f32_16x16x32_bf16 v[66:69], v[190:193], v[222:225], v[66:69]
	s_setprio 0
	s_barrier
	s_add_i32 s19, s19, s52
	v_lshl_add_u64 v[168:169], v[168:169], 0, s[10:11]
	s_mov_b32 m0, s19
	ds_read_b128 v[194:197], v172 offset:49152
	ds_read_b128 v[198:201], v172 offset:50176
	ds_read_b128 v[202:205], v172 offset:51200
	ds_read_b128 v[206:209], v172 offset:52224
	ds_read_b128 v[210:213], v172 offset:53248
	ds_read_b128 v[214:217], v172 offset:54272
	ds_read_b128 v[218:221], v172 offset:55296
	ds_read_b128 v[222:225], v172 offset:56320
	global_load_lds_dwordx4 v[168:169], off
	s_add_i32 m0, s19, 0x2000
	s_add_u32 s20, s44, 0x80080
	v_lshl_add_u64 v[168:169], v[226:227], 0, s[10:11]
	s_addc_u32 s21, s45, 0
	s_add_i32 s19, s31, s52
	global_load_lds_dwordx4 v[168:169], off
	v_lshl_add_u64 v[168:169], s[20:21], 0, v[140:141]
	s_mov_b32 m0, s19
	s_nop 0
	global_load_lds_dwordx4 v[168:169], off
	v_lshl_add_u64 v[168:169], s[20:21], 0, v[144:145]
	s_add_i32 m0, s19, 0x2000
	s_nop 0
	global_load_lds_dwordx4 v[168:169], off
	v_lshl_add_u64 v[168:169], v[228:229], 0, s[10:11]
	s_mov_b32 m0, s67
	s_nop 0
	global_load_lds_dwordx4 v[168:169], off
	v_lshl_add_u64 v[168:169], v[230:231], 0, s[10:11]
	s_mov_b32 m0, s68
	s_nop 0
	global_load_lds_dwordx4 v[168:169], off
	s_waitcnt vmcnt(8)
	s_waitcnt lgkmcnt(0)
	s_waitcnt lgkmcnt(0)
	v_mfma_f32_16x16x32_bf16 v[62:65], v[130:133], v[194:197], v[62:65]
	v_mfma_f32_16x16x32_bf16 v[58:61], v[164:167], v[194:197], v[58:61]
	v_mfma_f32_16x16x32_bf16 v[46:49], v[130:133], v[202:205], v[46:49]
	v_mfma_f32_16x16x32_bf16 v[42:45], v[164:167], v[202:205], v[42:45]
	s_barrier
	s_setprio 1
	v_mfma_f32_16x16x32_bf16 v[30:33], v[130:133], v[210:213], v[30:33]
	v_mfma_f32_16x16x32_bf16 v[26:29], v[164:167], v[210:213], v[26:29]
	v_mfma_f32_16x16x32_bf16 v[14:17], v[130:133], v[218:221], v[14:17]
	v_mfma_f32_16x16x32_bf16 v[10:13], v[164:167], v[218:221], v[10:13]
	v_mfma_f32_16x16x32_bf16 v[62:65], v[134:137], v[198:201], v[62:65]
	v_mfma_f32_16x16x32_bf16 v[58:61], v[174:177], v[198:201], v[58:61]
	v_mfma_f32_16x16x32_bf16 v[46:49], v[134:137], v[206:209], v[46:49]
	v_mfma_f32_16x16x32_bf16 v[42:45], v[174:177], v[206:209], v[42:45]
	v_mfma_f32_16x16x32_bf16 v[30:33], v[134:137], v[214:217], v[30:33]
	v_mfma_f32_16x16x32_bf16 v[26:29], v[174:177], v[214:217], v[26:29]
	v_mfma_f32_16x16x32_bf16 v[14:17], v[134:137], v[222:225], v[14:17]
	v_mfma_f32_16x16x32_bf16 v[10:13], v[174:177], v[222:225], v[10:13]
	s_setprio 0
	s_setprio 1
	v_mfma_f32_16x16x32_bf16 v[54:57], v[178:181], v[194:197], v[54:57]
	v_mfma_f32_16x16x32_bf16 v[50:53], v[186:189], v[194:197], v[50:53]
	v_mfma_f32_16x16x32_bf16 v[38:41], v[178:181], v[202:205], v[38:41]
	v_mfma_f32_16x16x32_bf16 v[34:37], v[186:189], v[202:205], v[34:37]
	v_mfma_f32_16x16x32_bf16 v[22:25], v[178:181], v[210:213], v[22:25]
	v_mfma_f32_16x16x32_bf16 v[18:21], v[186:189], v[210:213], v[18:21]
	v_mfma_f32_16x16x32_bf16 v[6:9], v[178:181], v[218:221], v[6:9]
	v_mfma_f32_16x16x32_bf16 v[2:5], v[186:189], v[218:221], v[2:5]
	v_mfma_f32_16x16x32_bf16 v[54:57], v[182:185], v[198:201], v[54:57]
	v_mfma_f32_16x16x32_bf16 v[50:53], v[190:193], v[198:201], v[50:53]
	v_mfma_f32_16x16x32_bf16 v[38:41], v[182:185], v[206:209], v[38:41]
	v_mfma_f32_16x16x32_bf16 v[34:37], v[190:193], v[206:209], v[34:37]
	v_mfma_f32_16x16x32_bf16 v[22:25], v[182:185], v[214:217], v[22:25]
	v_mfma_f32_16x16x32_bf16 v[18:21], v[190:193], v[214:217], v[18:21]
	v_mfma_f32_16x16x32_bf16 v[6:9], v[182:185], v[222:225], v[6:9]
	v_mfma_f32_16x16x32_bf16 v[2:5], v[190:193], v[222:225], v[2:5]
	s_setprio 0
	s_barrier
	s_add_i32 s18, s18, 2
	s_add_u32 s42, s42, 0x100
	s_addc_u32 s43, s43, 0
	s_add_u32 s16, s16, 0x100
	s_addc_u32 s17, s17, 0
	s_cmp_gt_u32 s18, 29
	s_cbranch_scc0 .LBB0_466
	s_and_b64 vcc, exec, s[12:13]
	s_cbranch_vccz .LBB0_469
	s_barrier

.LBB0_699:
	ds_read_b128 v[134:137], v214
	ds_read_b128 v[138:141], v214 offset:1024
	ds_read_b128 v[142:145], v214 offset:2048
	ds_read_b128 v[178:181], v214 offset:3072
	ds_read_b128 v[182:185], v215
	ds_read_b128 v[186:189], v215 offset:1024
	ds_read_b128 v[190:193], v215 offset:2048
	ds_read_b128 v[194:197], v215 offset:3072
	s_add_u32 s40, s38, 0x100
	s_addc_u32 s41, s39, 0
	s_add_u32 s18, s15, s38
	s_addc_u32 s19, s16, s39
	s_cmp_eq_u32 s17, 60
	s_cselect_b32 s45, s3, s19
	s_cselect_b32 s19, 0, s40
	s_cselect_b32 s44, s14, s18
	s_cselect_b32 s18, 0, s41
	s_add_u32 s42, s10, s19
	s_addc_u32 s43, s11, s18
	s_mov_b32 m0, s66
	v_lshl_add_u64 v[244:245], v[130:131], 0, s[38:39]
	ds_read_b128 v[198:201], v216
	ds_read_b128 v[202:205], v216 offset:1024
	ds_read_b128 v[206:209], v216 offset:2048
	ds_read_b128 v[224:227], v216 offset:3072
	ds_read_b128 v[228:231], v216 offset:4096
	ds_read_b128 v[232:235], v216 offset:5120
	ds_read_b128 v[236:239], v216 offset:6144
	ds_read_b128 v[240:243], v216 offset:7168
	global_load_lds_dwordx4 v[244:245], off
	v_lshl_add_u64 v[244:245], v[132:133], 0, s[38:39]
	s_mov_b32 m0, s67
	s_nop 0
	global_load_lds_dwordx4 v[244:245], off
	s_waitcnt vmcnt(8)
	s_waitcnt lgkmcnt(0)
	s_waitcnt lgkmcnt(0)
	v_mfma_f32_16x16x32_bf16 v[82:85], v[134:137], v[198:201], v[82:85]
	v_mfma_f32_16x16x32_bf16 v[78:81], v[142:145], v[198:201], v[78:81]
	v_mfma_f32_16x16x32_bf16 v[110:113], v[134:137], v[206:209], v[110:113]
	v_mfma_f32_16x16x32_bf16 v[106:109], v[142:145], v[206:209], v[106:109]
	s_barrier
	s_setprio 1
	v_mfma_f32_16x16x32_bf16 v[118:121], v[134:137], v[228:231], v[118:121]
	v_mfma_f32_16x16x32_bf16 v[114:117], v[142:145], v[228:231], v[114:117]
	v_mfma_f32_16x16x32_bf16 v[126:129], v[134:137], v[236:239], v[126:129]
	v_mfma_f32_16x16x32_bf16 v[122:125], v[142:145], v[236:239], v[122:125]
	v_mfma_f32_16x16x32_bf16 v[82:85], v[138:141], v[202:205], v[82:85]
	v_mfma_f32_16x16x32_bf16 v[78:81], v[178:181], v[202:205], v[78:81]
	v_mfma_f32_16x16x32_bf16 v[110:113], v[138:141], v[224:227], v[110:113]
	v_mfma_f32_16x16x32_bf16 v[106:109], v[178:181], v[224:227], v[106:109]
	v_mfma_f32_16x16x32_bf16 v[118:121], v[138:141], v[232:235], v[118:121]
	v_mfma_f32_16x16x32_bf16 v[114:117], v[178:181], v[232:235], v[114:117]
	v_mfma_f32_16x16x32_bf16 v[126:129], v[138:141], v[240:243], v[126:129]
	v_mfma_f32_16x16x32_bf16 v[122:125], v[178:181], v[240:243], v[122:125]
	s_setprio 0
	s_setprio 1
	v_mfma_f32_16x16x32_bf16 v[22:25], v[182:185], v[198:201], v[22:25]
	v_mfma_f32_16x16x32_bf16 v[26:29], v[190:193], v[198:201], v[26:29]
	v_mfma_f32_16x16x32_bf16 v[42:45], v[182:185], v[206:209], v[42:45]
	v_mfma_f32_16x16x32_bf16 v[46:49], v[190:193], v[206:209], v[46:49]
	v_mfma_f32_16x16x32_bf16 v[62:65], v[182:185], v[228:231], v[62:65]
	v_mfma_f32_16x16x32_bf16 v[70:73], v[190:193], v[228:231], v[70:73]
	v_mfma_f32_16x16x32_bf16 v[90:93], v[182:185], v[236:239], v[90:93]
	v_mfma_f32_16x16x32_bf16 v[94:97], v[190:193], v[236:239], v[94:97]
	v_mfma_f32_16x16x32_bf16 v[22:25], v[186:189], v[202:205], v[22:25]
	v_mfma_f32_16x16x32_bf16 v[26:29], v[194:197], v[202:205], v[26:29]
	v_mfma_f32_16x16x32_bf16 v[42:45], v[186:189], v[224:227], v[42:45]
	v_mfma_f32_16x16x32_bf16 v[46:49], v[194:197], v[224:227], v[46:49]
	v_mfma_f32_16x16x32_bf16 v[62:65], v[186:189], v[232:235], v[62:65]
	v_mfma_f32_16x16x32_bf16 v[70:73], v[194:197], v[232:235], v[70:73]
	v_mfma_f32_16x16x32_bf16 v[90:93], v[186:189], v[240:243], v[90:93]
	v_mfma_f32_16x16x32_bf16 v[94:97], v[194:197], v[240:243], v[94:97]
	s_setprio 0
	s_barrier
	s_mov_b32 m0, s68
	v_lshl_add_u64 v[244:245], s[42:43], 0, v[150:151]
	s_add_u32 s18, s42, 0x100000
	ds_read_b128 v[198:201], v216 offset:16384
	ds_read_b128 v[202:205], v216 offset:17408
	ds_read_b128 v[206:209], v216 offset:18432
	ds_read_b128 v[224:227], v216 offset:19456
	ds_read_b128 v[228:231], v216 offset:20480
	ds_read_b128 v[232:235], v216 offset:21504
	ds_read_b128 v[236:239], v216 offset:22528
	ds_read_b128 v[240:243], v216 offset:23552
	global_load_lds_dwordx4 v[244:245], off
	v_lshl_add_u64 v[246:247], s[42:43], 0, v[146:147]
	s_mov_b32 m0, s69
	s_addc_u32 s19, s43, 0
	global_load_lds_dwordx4 v[246:247], off
	v_lshl_add_u64 v[248:249], s[18:19], 0, v[150:151]
	s_mov_b32 m0, s73
	v_lshl_add_u64 v[250:251], s[44:45], 0, v[148:149]
	global_load_lds_dwordx4 v[248:249], off
	v_lshl_add_u64 v[248:249], s[18:19], 0, v[146:147]
	s_mov_b32 m0, s74
	s_nop 0
	global_load_lds_dwordx4 v[248:249], off
	v_lshl_add_u64 v[248:249], s[44:45], 0, v[152:153]
	s_mov_b32 m0, s9
	s_nop 0
	global_load_lds_dwordx4 v[248:249], off
	s_mov_b32 m0, s55
	s_nop 0
	global_load_lds_dwordx4 v[250:251], off
	s_waitcnt vmcnt(8)
	s_waitcnt lgkmcnt(0)
	s_waitcnt lgkmcnt(0)
	v_mfma_f32_16x16x32_bf16 v[102:105], v[134:137], v[198:201], v[102:105]
	v_mfma_f32_16x16x32_bf16 v[98:101], v[142:145], v[198:201], v[98:101]
	v_mfma_f32_16x16x32_bf16 v[66:69], v[134:137], v[206:209], v[66:69]
	v_mfma_f32_16x16x32_bf16 v[58:61], v[142:145], v[206:209], v[58:61]
	s_barrier
	s_setprio 1
	v_mfma_f32_16x16x32_bf16 v[38:41], v[134:137], v[228:231], v[38:41]
	v_mfma_f32_16x16x32_bf16 v[34:37], v[142:145], v[228:231], v[34:37]
	v_mfma_f32_16x16x32_bf16 v[14:17], v[134:137], v[236:239], v[14:17]
	v_mfma_f32_16x16x32_bf16 v[10:13], v[142:145], v[236:239], v[10:13]
	v_mfma_f32_16x16x32_bf16 v[102:105], v[138:141], v[202:205], v[102:105]
	v_mfma_f32_16x16x32_bf16 v[98:101], v[178:181], v[202:205], v[98:101]
	v_mfma_f32_16x16x32_bf16 v[66:69], v[138:141], v[224:227], v[66:69]
	v_mfma_f32_16x16x32_bf16 v[58:61], v[178:181], v[224:227], v[58:61]
	v_mfma_f32_16x16x32_bf16 v[38:41], v[138:141], v[232:235], v[38:41]
	v_mfma_f32_16x16x32_bf16 v[34:37], v[178:181], v[232:235], v[34:37]
	v_mfma_f32_16x16x32_bf16 v[14:17], v[138:141], v[240:243], v[14:17]
	v_mfma_f32_16x16x32_bf16 v[10:13], v[178:181], v[240:243], v[10:13]
	s_setprio 0
	s_setprio 1
	v_mfma_f32_16x16x32_bf16 v[86:89], v[182:185], v[198:201], v[86:89]
	v_mfma_f32_16x16x32_bf16 v[74:77], v[190:193], v[198:201], v[74:77]
	v_mfma_f32_16x16x32_bf16 v[54:57], v[182:185], v[206:209], v[54:57]
	v_mfma_f32_16x16x32_bf16 v[50:53], v[190:193], v[206:209], v[50:53]
	v_mfma_f32_16x16x32_bf16 v[30:33], v[182:185], v[228:231], v[30:33]
	v_mfma_f32_16x16x32_bf16 v[18:21], v[190:193], v[228:231], v[18:21]
	v_mfma_f32_16x16x32_bf16 v[6:9], v[182:185], v[236:239], v[6:9]
	v_mfma_f32_16x16x32_bf16 v[2:5], v[190:193], v[236:239], v[2:5]
	v_mfma_f32_16x16x32_bf16 v[86:89], v[186:189], v[202:205], v[86:89]
	v_mfma_f32_16x16x32_bf16 v[74:77], v[194:197], v[202:205], v[74:77]
	v_mfma_f32_16x16x32_bf16 v[54:57], v[186:189], v[224:227], v[54:57]
	v_mfma_f32_16x16x32_bf16 v[50:53], v[194:197], v[224:227], v[50:53]
	v_mfma_f32_16x16x32_bf16 v[30:33], v[186:189], v[232:235], v[30:33]
	v_mfma_f32_16x16x32_bf16 v[18:21], v[194:197], v[232:235], v[18:21]
	v_mfma_f32_16x16x32_bf16 v[6:9], v[186:189], v[240:243], v[6:9]
	v_mfma_f32_16x16x32_bf16 v[2:5], v[194:197], v[240:243], v[2:5]
	s_setprio 0
	s_barrier
	s_add_i32 s20, 0, 0x1c000
	v_add_u32_e32 v194, s20, v212
	ds_read_b128 v[134:137], v220
	ds_read_b128 v[138:141], v220 offset:1024
	ds_read_b128 v[142:145], v220 offset:2048
	ds_read_b128 v[178:181], v220 offset:3072
	ds_read_b128 v[182:185], v194
	ds_read_b128 v[186:189], v194 offset:1024
	ds_read_b128 v[190:193], v194 offset:2048
	ds_read_b128 v[194:197], v194 offset:3072
	s_add_u32 s18, s44, 0x100000
	s_addc_u32 s19, s45, 0
	s_mov_b32 m0, s56
	v_lshl_add_u64 v[252:253], s[18:19], 0, v[152:153]
	ds_read_b128 v[198:201], v216 offset:32768
	ds_read_b128 v[202:205], v216 offset:33792
	ds_read_b128 v[206:209], v216 offset:34816
	ds_read_b128 v[224:227], v216 offset:35840
	ds_read_b128 v[228:231], v216 offset:36864
	ds_read_b128 v[232:235], v216 offset:37888
	ds_read_b128 v[236:239], v216 offset:38912
	ds_read_b128 v[240:243], v216 offset:39936
	global_load_lds_dwordx4 v[252:253], off
	v_lshl_add_u64 v[252:253], s[18:19], 0, v[148:149]
	s_mov_b32 m0, s57
	s_nop 0
	global_load_lds_dwordx4 v[252:253], off
	s_waitcnt vmcnt(8)
	s_waitcnt lgkmcnt(0)
	s_waitcnt lgkmcnt(0)
	v_mfma_f32_16x16x32_bf16 v[82:85], v[134:137], v[198:201], v[82:85]
	v_mfma_f32_16x16x32_bf16 v[78:81], v[142:145], v[198:201], v[78:81]
	v_mfma_f32_16x16x32_bf16 v[110:113], v[134:137], v[206:209], v[110:113]
	v_mfma_f32_16x16x32_bf16 v[106:109], v[142:145], v[206:209], v[106:109]
	s_barrier
	s_setprio 1
	v_mfma_f32_16x16x32_bf16 v[118:121], v[134:137], v[228:231], v[118:121]
	v_mfma_f32_16x16x32_bf16 v[114:117], v[142:145], v[228:231], v[114:117]
	v_mfma_f32_16x16x32_bf16 v[126:129], v[134:137], v[236:239], v[126:129]
	v_mfma_f32_16x16x32_bf16 v[122:125], v[142:145], v[236:239], v[122:125]
	v_mfma_f32_16x16x32_bf16 v[82:85], v[138:141], v[202:205], v[82:85]
	v_mfma_f32_16x16x32_bf16 v[78:81], v[178:181], v[202:205], v[78:81]
	v_mfma_f32_16x16x32_bf16 v[110:113], v[138:141], v[224:227], v[110:113]
	v_mfma_f32_16x16x32_bf16 v[106:109], v[178:181], v[224:227], v[106:109]
	v_mfma_f32_16x16x32_bf16 v[118:121], v[138:141], v[232:235], v[118:121]
	v_mfma_f32_16x16x32_bf16 v[114:117], v[178:181], v[232:235], v[114:117]
	v_mfma_f32_16x16x32_bf16 v[126:129], v[138:141], v[240:243], v[126:129]
	v_mfma_f32_16x16x32_bf16 v[122:125], v[178:181], v[240:243], v[122:125]
	s_setprio 0
	s_setprio 1
	v_mfma_f32_16x16x32_bf16 v[22:25], v[182:185], v[198:201], v[22:25]
	v_mfma_f32_16x16x32_bf16 v[26:29], v[190:193], v[198:201], v[26:29]
	v_mfma_f32_16x16x32_bf16 v[42:45], v[182:185], v[206:209], v[42:45]
	v_mfma_f32_16x16x32_bf16 v[46:49], v[190:193], v[206:209], v[46:49]
	v_mfma_f32_16x16x32_bf16 v[62:65], v[182:185], v[228:231], v[62:65]
	v_mfma_f32_16x16x32_bf16 v[70:73], v[190:193], v[228:231], v[70:73]
	v_mfma_f32_16x16x32_bf16 v[90:93], v[182:185], v[236:239], v[90:93]
	v_mfma_f32_16x16x32_bf16 v[94:97], v[190:193], v[236:239], v[94:97]
	v_mfma_f32_16x16x32_bf16 v[22:25], v[186:189], v[202:205], v[22:25]
	v_mfma_f32_16x16x32_bf16 v[26:29], v[194:197], v[202:205], v[26:29]
	v_mfma_f32_16x16x32_bf16 v[42:45], v[186:189], v[224:227], v[42:45]
	v_mfma_f32_16x16x32_bf16 v[46:49], v[194:197], v[224:227], v[46:49]
	v_mfma_f32_16x16x32_bf16 v[62:65], v[186:189], v[232:235], v[62:65]
	v_mfma_f32_16x16x32_bf16 v[70:73], v[194:197], v[232:235], v[70:73]
	v_mfma_f32_16x16x32_bf16 v[90:93], v[186:189], v[240:243], v[90:93]
	v_mfma_f32_16x16x32_bf16 v[94:97], v[194:197], v[240:243], v[94:97]
	s_setprio 0
	s_barrier
	s_add_i32 s18, s75, s54
	v_lshl_add_u64 v[244:245], v[244:245], 0, s[26:27]
	s_mov_b32 m0, s18
	ds_read_b128 v[198:201], v216 offset:49152
	ds_read_b128 v[202:205], v216 offset:50176
	ds_read_b128 v[206:209], v216 offset:51200
	ds_read_b128 v[224:227], v216 offset:52224
	ds_read_b128 v[228:231], v216 offset:53248
	ds_read_b128 v[232:235], v216 offset:54272
	ds_read_b128 v[236:239], v216 offset:55296
	ds_read_b128 v[240:243], v216 offset:56320
	global_load_lds_dwordx4 v[244:245], off
	s_add_i32 m0, s18, 0x2000
	s_add_u32 s18, s42, 0x100080
	v_lshl_add_u64 v[244:245], v[246:247], 0, s[26:27]
	s_addc_u32 s19, s43, 0
	s_add_i32 s20, s20, s54
	global_load_lds_dwordx4 v[244:245], off
	v_lshl_add_u64 v[244:245], s[18:19], 0, v[150:151]
	s_mov_b32 m0, s20
	s_nop 0
	global_load_lds_dwordx4 v[244:245], off
	v_lshl_add_u64 v[244:245], s[18:19], 0, v[146:147]
	s_add_i32 m0, s20, 0x2000
	s_nop 0
	global_load_lds_dwordx4 v[244:245], off
	v_lshl_add_u64 v[244:245], v[248:249], 0, s[26:27]
	s_mov_b32 m0, s63
	s_nop 0
	global_load_lds_dwordx4 v[244:245], off
	v_lshl_add_u64 v[244:245], v[250:251], 0, s[26:27]
	s_mov_b32 m0, s64
	s_nop 0
	global_load_lds_dwordx4 v[244:245], off
	s_waitcnt vmcnt(8)
	s_waitcnt lgkmcnt(0)
	s_waitcnt lgkmcnt(0)
	v_mfma_f32_16x16x32_bf16 v[102:105], v[134:137], v[198:201], v[102:105]
	v_mfma_f32_16x16x32_bf16 v[98:101], v[142:145], v[198:201], v[98:101]
	v_mfma_f32_16x16x32_bf16 v[66:69], v[134:137], v[206:209], v[66:69]
	v_mfma_f32_16x16x32_bf16 v[58:61], v[142:145], v[206:209], v[58:61]
	s_barrier
	s_setprio 1
	v_mfma_f32_16x16x32_bf16 v[38:41], v[134:137], v[228:231], v[38:41]
	v_mfma_f32_16x16x32_bf16 v[34:37], v[142:145], v[228:231], v[34:37]
	v_mfma_f32_16x16x32_bf16 v[14:17], v[134:137], v[236:239], v[14:17]
	v_mfma_f32_16x16x32_bf16 v[10:13], v[142:145], v[236:239], v[10:13]
	v_mfma_f32_16x16x32_bf16 v[102:105], v[138:141], v[202:205], v[102:105]
	v_mfma_f32_16x16x32_bf16 v[98:101], v[178:181], v[202:205], v[98:101]
	v_mfma_f32_16x16x32_bf16 v[66:69], v[138:141], v[224:227], v[66:69]
	v_mfma_f32_16x16x32_bf16 v[58:61], v[178:181], v[224:227], v[58:61]
	v_mfma_f32_16x16x32_bf16 v[38:41], v[138:141], v[232:235], v[38:41]
	v_mfma_f32_16x16x32_bf16 v[34:37], v[178:181], v[232:235], v[34:37]
	v_mfma_f32_16x16x32_bf16 v[14:17], v[138:141], v[240:243], v[14:17]
	v_mfma_f32_16x16x32_bf16 v[10:13], v[178:181], v[240:243], v[10:13]
	s_setprio 0
	s_setprio 1
	v_mfma_f32_16x16x32_bf16 v[86:89], v[182:185], v[198:201], v[86:89]
	v_mfma_f32_16x16x32_bf16 v[74:77], v[190:193], v[198:201], v[74:77]
	v_mfma_f32_16x16x32_bf16 v[54:57], v[182:185], v[206:209], v[54:57]
	v_mfma_f32_16x16x32_bf16 v[50:53], v[190:193], v[206:209], v[50:53]
	v_mfma_f32_16x16x32_bf16 v[30:33], v[182:185], v[228:231], v[30:33]
	v_mfma_f32_16x16x32_bf16 v[18:21], v[190:193], v[228:231], v[18:21]
	v_mfma_f32_16x16x32_bf16 v[6:9], v[182:185], v[236:239], v[6:9]
	v_mfma_f32_16x16x32_bf16 v[2:5], v[190:193], v[236:239], v[2:5]
	v_mfma_f32_16x16x32_bf16 v[86:89], v[186:189], v[202:205], v[86:89]
	v_mfma_f32_16x16x32_bf16 v[74:77], v[194:197], v[202:205], v[74:77]
	v_mfma_f32_16x16x32_bf16 v[54:57], v[186:189], v[224:227], v[54:57]
	v_mfma_f32_16x16x32_bf16 v[50:53], v[194:197], v[224:227], v[50:53]
	v_mfma_f32_16x16x32_bf16 v[30:33], v[186:189], v[232:235], v[30:33]
	v_mfma_f32_16x16x32_bf16 v[18:21], v[194:197], v[232:235], v[18:21]
	v_mfma_f32_16x16x32_bf16 v[6:9], v[186:189], v[240:243], v[6:9]
	v_mfma_f32_16x16x32_bf16 v[2:5], v[194:197], v[240:243], v[2:5]
	s_setprio 0
	s_barrier
	s_add_i32 s17, s17, 2
	s_cmp_gt_u32 s17, 61
	s_mov_b64 s[38:39], s[40:41]
	s_cbranch_scc0 .LBB0_699
	s_and_b64 vcc, exec, s[28:29]
	s_cbranch_vccz .LBB0_702
	s_barrier

.LBB0_877:
	ds_read_b128 v[130:133], v220
	ds_read_b128 v[134:137], v220 offset:1024
	ds_read_b128 v[138:141], v220 offset:2048
	ds_read_b128 v[142:145], v220 offset:3072
	ds_read_b128 v[184:187], v224
	ds_read_b128 v[188:191], v224 offset:1024
	ds_read_b128 v[192:195], v224 offset:2048
	ds_read_b128 v[196:199], v224 offset:3072
	s_add_u32 s14, s36, 0xffea0080
	s_addc_u32 s15, s37, -1
	s_cmpk_eq_i32 s3, 0x54
	s_cselect_b32 s43, s29, s15
	s_cselect_b32 s42, s28, s14
	s_cselect_b32 s41, s9, s39
	s_cselect_b32 s40, s8, s38
	s_mov_b32 m0, s50
	v_lshl_add_u64 v[244:245], s[36:37], 0, v[178:179]
	ds_read_b128 v[200:203], v221
	ds_read_b128 v[204:207], v221 offset:1024
	ds_read_b128 v[208:211], v221 offset:2048
	ds_read_b128 v[212:215], v221 offset:3072
	ds_read_b128 v[228:231], v221 offset:4096
	ds_read_b128 v[232:235], v221 offset:5120
	ds_read_b128 v[236:239], v221 offset:6144
	ds_read_b128 v[240:243], v221 offset:7168
	global_load_lds_dwordx4 v[244:245], off
	v_lshl_add_u64 v[244:245], s[36:37], 0, v[180:181]
	s_mov_b32 m0, s51
	s_nop 0
	global_load_lds_dwordx4 v[244:245], off
	s_waitcnt vmcnt(8)
	s_waitcnt lgkmcnt(0)
	s_waitcnt lgkmcnt(0)
	v_mfma_f32_16x16x32_bf16 v[30:33], v[130:133], v[200:203], v[30:33]
	v_mfma_f32_16x16x32_bf16 v[26:29], v[138:141], v[200:203], v[26:29]
	v_mfma_f32_16x16x32_bf16 v[46:49], v[130:133], v[208:211], v[46:49]
	v_mfma_f32_16x16x32_bf16 v[42:45], v[138:141], v[208:211], v[42:45]
	s_barrier
	s_setprio 1
	v_mfma_f32_16x16x32_bf16 v[62:65], v[130:133], v[228:231], v[62:65]
	v_mfma_f32_16x16x32_bf16 v[58:61], v[138:141], v[228:231], v[58:61]
	v_mfma_f32_16x16x32_bf16 v[94:97], v[130:133], v[236:239], v[94:97]
	v_mfma_f32_16x16x32_bf16 v[90:93], v[138:141], v[236:239], v[90:93]
	v_mfma_f32_16x16x32_bf16 v[30:33], v[134:137], v[204:207], v[30:33]
	v_mfma_f32_16x16x32_bf16 v[26:29], v[142:145], v[204:207], v[26:29]
	v_mfma_f32_16x16x32_bf16 v[46:49], v[134:137], v[212:215], v[46:49]
	v_mfma_f32_16x16x32_bf16 v[42:45], v[142:145], v[212:215], v[42:45]
	v_mfma_f32_16x16x32_bf16 v[62:65], v[134:137], v[232:235], v[62:65]
	v_mfma_f32_16x16x32_bf16 v[58:61], v[142:145], v[232:235], v[58:61]
	v_mfma_f32_16x16x32_bf16 v[94:97], v[134:137], v[240:243], v[94:97]
	v_mfma_f32_16x16x32_bf16 v[90:93], v[142:145], v[240:243], v[90:93]
	s_setprio 0
	s_setprio 1
	v_mfma_f32_16x16x32_bf16 v[2:5], v[184:187], v[200:203], v[2:5]
	v_mfma_f32_16x16x32_bf16 v[6:9], v[192:195], v[200:203], v[6:9]
	v_mfma_f32_16x16x32_bf16 v[10:13], v[184:187], v[208:211], v[10:13]
	v_mfma_f32_16x16x32_bf16 v[14:17], v[192:195], v[208:211], v[14:17]
	v_mfma_f32_16x16x32_bf16 v[18:21], v[184:187], v[228:231], v[18:21]
	v_mfma_f32_16x16x32_bf16 v[22:25], v[192:195], v[228:231], v[22:25]
	v_mfma_f32_16x16x32_bf16 v[34:37], v[184:187], v[236:239], v[34:37]
	v_mfma_f32_16x16x32_bf16 v[38:41], v[192:195], v[236:239], v[38:41]
	v_mfma_f32_16x16x32_bf16 v[2:5], v[188:191], v[204:207], v[2:5]
	v_mfma_f32_16x16x32_bf16 v[6:9], v[196:199], v[204:207], v[6:9]
	v_mfma_f32_16x16x32_bf16 v[10:13], v[188:191], v[212:215], v[10:13]
	v_mfma_f32_16x16x32_bf16 v[14:17], v[196:199], v[212:215], v[14:17]
	v_mfma_f32_16x16x32_bf16 v[18:21], v[188:191], v[232:235], v[18:21]
	v_mfma_f32_16x16x32_bf16 v[22:25], v[196:199], v[232:235], v[22:25]
	v_mfma_f32_16x16x32_bf16 v[34:37], v[188:191], v[240:243], v[34:37]
	v_mfma_f32_16x16x32_bf16 v[38:41], v[196:199], v[240:243], v[38:41]
	s_setprio 0
	s_barrier
	s_mov_b32 m0, s52
	v_lshl_add_u64 v[244:245], s[40:41], 0, v[150:151]
	s_add_u32 s14, s40, 0x160000
	ds_read_b128 v[200:203], v221 offset:16384
	ds_read_b128 v[204:207], v221 offset:17408
	ds_read_b128 v[208:211], v221 offset:18432
	ds_read_b128 v[212:215], v221 offset:19456
	ds_read_b128 v[228:231], v221 offset:20480
	ds_read_b128 v[232:235], v221 offset:21504
	ds_read_b128 v[236:239], v221 offset:22528
	ds_read_b128 v[240:243], v221 offset:23552
	global_load_lds_dwordx4 v[244:245], off
	v_lshl_add_u64 v[246:247], s[40:41], 0, v[146:147]
	s_mov_b32 m0, s53
	s_addc_u32 s15, s41, 0
	global_load_lds_dwordx4 v[246:247], off
	v_lshl_add_u64 v[248:249], s[14:15], 0, v[150:151]
	s_mov_b32 m0, s54
	v_lshl_add_u64 v[250:251], s[42:43], 0, v[148:149]
	global_load_lds_dwordx4 v[248:249], off
	v_lshl_add_u64 v[248:249], s[14:15], 0, v[146:147]
	s_mov_b32 m0, s55
	s_nop 0
	global_load_lds_dwordx4 v[248:249], off
	v_lshl_add_u64 v[248:249], s[42:43], 0, v[152:153]
	s_mov_b32 m0, s61
	s_nop 0
	global_load_lds_dwordx4 v[248:249], off
	s_mov_b32 m0, s62
	s_nop 0
	global_load_lds_dwordx4 v[250:251], off
	s_waitcnt vmcnt(8)
	s_waitcnt lgkmcnt(0)
	s_waitcnt lgkmcnt(0)
	v_mfma_f32_16x16x32_bf16 v[114:117], v[130:133], v[200:203], v[114:117]
	v_mfma_f32_16x16x32_bf16 v[110:113], v[138:141], v[200:203], v[110:113]
	v_mfma_f32_16x16x32_bf16 v[126:129], v[130:133], v[208:211], v[126:129]
	v_mfma_f32_16x16x32_bf16 v[122:125], v[138:141], v[208:211], v[122:125]
	s_barrier
	s_setprio 1
	v_mfma_f32_16x16x32_bf16 v[118:121], v[130:133], v[228:231], v[118:121]
	v_mfma_f32_16x16x32_bf16 v[106:109], v[138:141], v[228:231], v[106:109]
	v_mfma_f32_16x16x32_bf16 v[78:81], v[130:133], v[236:239], v[78:81]
	v_mfma_f32_16x16x32_bf16 v[74:77], v[138:141], v[236:239], v[74:77]
	v_mfma_f32_16x16x32_bf16 v[114:117], v[134:137], v[204:207], v[114:117]
	v_mfma_f32_16x16x32_bf16 v[110:113], v[142:145], v[204:207], v[110:113]
	v_mfma_f32_16x16x32_bf16 v[126:129], v[134:137], v[212:215], v[126:129]
	v_mfma_f32_16x16x32_bf16 v[122:125], v[142:145], v[212:215], v[122:125]
	v_mfma_f32_16x16x32_bf16 v[118:121], v[134:137], v[232:235], v[118:121]
	v_mfma_f32_16x16x32_bf16 v[106:109], v[142:145], v[232:235], v[106:109]
	v_mfma_f32_16x16x32_bf16 v[78:81], v[134:137], v[240:243], v[78:81]
	v_mfma_f32_16x16x32_bf16 v[74:77], v[142:145], v[240:243], v[74:77]
	s_setprio 0
	s_setprio 1
	v_mfma_f32_16x16x32_bf16 v[50:53], v[184:187], v[200:203], v[50:53]
	v_mfma_f32_16x16x32_bf16 v[54:57], v[192:195], v[200:203], v[54:57]
	v_mfma_f32_16x16x32_bf16 v[82:85], v[184:187], v[208:211], v[82:85]
	v_mfma_f32_16x16x32_bf16 v[86:89], v[192:195], v[208:211], v[86:89]
	v_mfma_f32_16x16x32_bf16 v[102:105], v[184:187], v[228:231], v[102:105]
	v_mfma_f32_16x16x32_bf16 v[98:101], v[192:195], v[228:231], v[98:101]
	v_mfma_f32_16x16x32_bf16 v[70:73], v[184:187], v[236:239], v[70:73]
	v_mfma_f32_16x16x32_bf16 v[66:69], v[192:195], v[236:239], v[66:69]
	v_mfma_f32_16x16x32_bf16 v[50:53], v[188:191], v[204:207], v[50:53]
	v_mfma_f32_16x16x32_bf16 v[54:57], v[196:199], v[204:207], v[54:57]
	v_mfma_f32_16x16x32_bf16 v[82:85], v[188:191], v[212:215], v[82:85]
	v_mfma_f32_16x16x32_bf16 v[86:89], v[196:199], v[212:215], v[86:89]
	v_mfma_f32_16x16x32_bf16 v[102:105], v[188:191], v[232:235], v[102:105]
	v_mfma_f32_16x16x32_bf16 v[98:101], v[196:199], v[232:235], v[98:101]
	v_mfma_f32_16x16x32_bf16 v[70:73], v[188:191], v[240:243], v[70:73]
	v_mfma_f32_16x16x32_bf16 v[66:69], v[196:199], v[240:243], v[66:69]
	s_setprio 0
	s_barrier
	v_add_u32_e32 v196, s74, v218
	ds_read_b128 v[130:133], v225
	ds_read_b128 v[134:137], v225 offset:1024
	ds_read_b128 v[138:141], v225 offset:2048
	ds_read_b128 v[142:145], v225 offset:3072
	ds_read_b128 v[184:187], v196
	ds_read_b128 v[188:191], v196 offset:1024
	ds_read_b128 v[192:195], v196 offset:2048
	ds_read_b128 v[196:199], v196 offset:3072
	s_add_u32 s14, s42, 0x160000
	s_addc_u32 s15, s43, 0
	s_mov_b32 m0, s63
	v_lshl_add_u64 v[252:253], s[14:15], 0, v[152:153]
	ds_read_b128 v[200:203], v221 offset:32768
	ds_read_b128 v[204:207], v221 offset:33792
	ds_read_b128 v[208:211], v221 offset:34816
	ds_read_b128 v[212:215], v221 offset:35840
	ds_read_b128 v[228:231], v221 offset:36864
	ds_read_b128 v[232:235], v221 offset:37888
	ds_read_b128 v[236:239], v221 offset:38912
	ds_read_b128 v[240:243], v221 offset:39936
	global_load_lds_dwordx4 v[252:253], off
	v_lshl_add_u64 v[252:253], s[14:15], 0, v[148:149]
	s_mov_b32 m0, s64
	s_nop 0
	global_load_lds_dwordx4 v[252:253], off
	s_waitcnt vmcnt(8)
	s_waitcnt lgkmcnt(0)
	s_waitcnt lgkmcnt(0)
	v_mfma_f32_16x16x32_bf16 v[30:33], v[130:133], v[200:203], v[30:33]
	v_mfma_f32_16x16x32_bf16 v[26:29], v[138:141], v[200:203], v[26:29]
	v_mfma_f32_16x16x32_bf16 v[46:49], v[130:133], v[208:211], v[46:49]
	v_mfma_f32_16x16x32_bf16 v[42:45], v[138:141], v[208:211], v[42:45]
	s_barrier
	s_setprio 1
	v_mfma_f32_16x16x32_bf16 v[62:65], v[130:133], v[228:231], v[62:65]
	v_mfma_f32_16x16x32_bf16 v[58:61], v[138:141], v[228:231], v[58:61]
	v_mfma_f32_16x16x32_bf16 v[94:97], v[130:133], v[236:239], v[94:97]
	v_mfma_f32_16x16x32_bf16 v[90:93], v[138:141], v[236:239], v[90:93]
	v_mfma_f32_16x16x32_bf16 v[30:33], v[134:137], v[204:207], v[30:33]
	v_mfma_f32_16x16x32_bf16 v[26:29], v[142:145], v[204:207], v[26:29]
	v_mfma_f32_16x16x32_bf16 v[46:49], v[134:137], v[212:215], v[46:49]
	v_mfma_f32_16x16x32_bf16 v[42:45], v[142:145], v[212:215], v[42:45]
	v_mfma_f32_16x16x32_bf16 v[62:65], v[134:137], v[232:235], v[62:65]
	v_mfma_f32_16x16x32_bf16 v[58:61], v[142:145], v[232:235], v[58:61]
	v_mfma_f32_16x16x32_bf16 v[94:97], v[134:137], v[240:243], v[94:97]
	v_mfma_f32_16x16x32_bf16 v[90:93], v[142:145], v[240:243], v[90:93]
	s_setprio 0
	s_setprio 1
	v_mfma_f32_16x16x32_bf16 v[2:5], v[184:187], v[200:203], v[2:5]
	v_mfma_f32_16x16x32_bf16 v[6:9], v[192:195], v[200:203], v[6:9]
	v_mfma_f32_16x16x32_bf16 v[10:13], v[184:187], v[208:211], v[10:13]
	v_mfma_f32_16x16x32_bf16 v[14:17], v[192:195], v[208:211], v[14:17]
	v_mfma_f32_16x16x32_bf16 v[18:21], v[184:187], v[228:231], v[18:21]
	v_mfma_f32_16x16x32_bf16 v[22:25], v[192:195], v[228:231], v[22:25]
	v_mfma_f32_16x16x32_bf16 v[34:37], v[184:187], v[236:239], v[34:37]
	v_mfma_f32_16x16x32_bf16 v[38:41], v[192:195], v[236:239], v[38:41]
	v_mfma_f32_16x16x32_bf16 v[2:5], v[188:191], v[204:207], v[2:5]
	v_mfma_f32_16x16x32_bf16 v[6:9], v[196:199], v[204:207], v[6:9]
	v_mfma_f32_16x16x32_bf16 v[10:13], v[188:191], v[212:215], v[10:13]
	v_mfma_f32_16x16x32_bf16 v[14:17], v[196:199], v[212:215], v[14:17]
	v_mfma_f32_16x16x32_bf16 v[18:21], v[188:191], v[232:235], v[18:21]
	v_mfma_f32_16x16x32_bf16 v[22:25], v[196:199], v[232:235], v[22:25]
	v_mfma_f32_16x16x32_bf16 v[34:37], v[188:191], v[240:243], v[34:37]
	v_mfma_f32_16x16x32_bf16 v[38:41], v[196:199], v[240:243], v[38:41]
	s_setprio 0
	s_barrier
	s_mov_b32 m0, s75
	v_lshl_add_u64 v[244:245], v[244:245], 0, s[22:23]
	s_add_u32 s14, s40, 0x160080
	ds_read_b128 v[200:203], v221 offset:49152
	ds_read_b128 v[204:207], v221 offset:50176
	ds_read_b128 v[208:211], v221 offset:51200
	ds_read_b128 v[212:215], v221 offset:52224
	ds_read_b128 v[228:231], v221 offset:53248
	ds_read_b128 v[232:235], v221 offset:54272
	ds_read_b128 v[236:239], v221 offset:55296
	ds_read_b128 v[240:243], v221 offset:56320
	global_load_lds_dwordx4 v[244:245], off
	v_lshl_add_u64 v[244:245], v[246:247], 0, s[22:23]
	s_mov_b32 m0, s76
	s_addc_u32 s15, s41, 0
	global_load_lds_dwordx4 v[244:245], off
	v_lshl_add_u64 v[244:245], s[14:15], 0, v[150:151]
	s_mov_b32 m0, s77
	s_nop 0
	global_load_lds_dwordx4 v[244:245], off
	v_lshl_add_u64 v[244:245], s[14:15], 0, v[146:147]
	s_mov_b32 m0, s78
	s_nop 0
	global_load_lds_dwordx4 v[244:245], off
	v_lshl_add_u64 v[244:245], v[248:249], 0, s[22:23]
	s_mov_b32 m0, s68
	s_nop 0
	global_load_lds_dwordx4 v[244:245], off
	v_lshl_add_u64 v[244:245], v[250:251], 0, s[22:23]
	s_mov_b32 m0, s69
	s_nop 0
	global_load_lds_dwordx4 v[244:245], off
	s_waitcnt vmcnt(8)
	s_waitcnt lgkmcnt(0)
	s_waitcnt lgkmcnt(0)
	v_mfma_f32_16x16x32_bf16 v[114:117], v[130:133], v[200:203], v[114:117]
	v_mfma_f32_16x16x32_bf16 v[110:113], v[138:141], v[200:203], v[110:113]
	v_mfma_f32_16x16x32_bf16 v[126:129], v[130:133], v[208:211], v[126:129]
	v_mfma_f32_16x16x32_bf16 v[122:125], v[138:141], v[208:211], v[122:125]
	s_barrier
	s_setprio 1
	v_mfma_f32_16x16x32_bf16 v[118:121], v[130:133], v[228:231], v[118:121]
	v_mfma_f32_16x16x32_bf16 v[106:109], v[138:141], v[228:231], v[106:109]
	v_mfma_f32_16x16x32_bf16 v[78:81], v[130:133], v[236:239], v[78:81]
	v_mfma_f32_16x16x32_bf16 v[74:77], v[138:141], v[236:239], v[74:77]
	v_mfma_f32_16x16x32_bf16 v[114:117], v[134:137], v[204:207], v[114:117]
	v_mfma_f32_16x16x32_bf16 v[110:113], v[142:145], v[204:207], v[110:113]
	v_mfma_f32_16x16x32_bf16 v[126:129], v[134:137], v[212:215], v[126:129]
	v_mfma_f32_16x16x32_bf16 v[122:125], v[142:145], v[212:215], v[122:125]
	v_mfma_f32_16x16x32_bf16 v[118:121], v[134:137], v[232:235], v[118:121]
	v_mfma_f32_16x16x32_bf16 v[106:109], v[142:145], v[232:235], v[106:109]
	v_mfma_f32_16x16x32_bf16 v[78:81], v[134:137], v[240:243], v[78:81]
	v_mfma_f32_16x16x32_bf16 v[74:77], v[142:145], v[240:243], v[74:77]
	s_setprio 0
	s_setprio 1
	v_mfma_f32_16x16x32_bf16 v[50:53], v[184:187], v[200:203], v[50:53]
	v_mfma_f32_16x16x32_bf16 v[54:57], v[192:195], v[200:203], v[54:57]
	v_mfma_f32_16x16x32_bf16 v[82:85], v[184:187], v[208:211], v[82:85]
	v_mfma_f32_16x16x32_bf16 v[86:89], v[192:195], v[208:211], v[86:89]
	v_mfma_f32_16x16x32_bf16 v[102:105], v[184:187], v[228:231], v[102:105]
	v_mfma_f32_16x16x32_bf16 v[98:101], v[192:195], v[228:231], v[98:101]
	v_mfma_f32_16x16x32_bf16 v[70:73], v[184:187], v[236:239], v[70:73]
	v_mfma_f32_16x16x32_bf16 v[66:69], v[192:195], v[236:239], v[66:69]
	v_mfma_f32_16x16x32_bf16 v[50:53], v[188:191], v[204:207], v[50:53]
	v_mfma_f32_16x16x32_bf16 v[54:57], v[196:199], v[204:207], v[54:57]
	v_mfma_f32_16x16x32_bf16 v[82:85], v[188:191], v[212:215], v[82:85]
	v_mfma_f32_16x16x32_bf16 v[86:89], v[196:199], v[212:215], v[86:89]
	v_mfma_f32_16x16x32_bf16 v[102:105], v[188:191], v[232:235], v[102:105]
	v_mfma_f32_16x16x32_bf16 v[98:101], v[196:199], v[232:235], v[98:101]
	v_mfma_f32_16x16x32_bf16 v[70:73], v[188:191], v[240:243], v[70:73]
	v_mfma_f32_16x16x32_bf16 v[66:69], v[196:199], v[240:243], v[66:69]
	s_setprio 0
	s_barrier
	s_add_i32 s3, s3, 2
	s_add_u32 s36, s36, 0x100
	s_addc_u32 s37, s37, 0
	s_add_u32 s38, s38, 0x100
	s_addc_u32 s39, s39, 0
	s_cmpk_gt_u32 s3, 0x55
	s_cbranch_scc0 .LBB0_877
	s_and_b64 vcc, exec, s[24:25]
	s_cbranch_vccz .LBB0_880
	s_barrier

.LBB0_986:
	ds_read_b128 v[130:133], v172
	ds_read_b128 v[134:137], v172 offset:1024
	ds_read_b128 v[138:141], v172 offset:2048
	ds_read_b128 v[142:145], v172 offset:3072
	ds_read_b128 v[166:169], v173
	ds_read_b128 v[176:179], v173 offset:1024
	ds_read_b128 v[180:183], v173 offset:2048
	ds_read_b128 v[184:187], v173 offset:3072
	s_add_u32 s20, s52, 0xfff80080
	s_addc_u32 s21, s53, -1
	s_cmp_eq_u32 s19, 28
	s_cselect_b32 s57, s3, s21
	s_cselect_b32 s56, s14, s20
	s_cselect_b32 s55, s15, s18
	s_cselect_b32 s54, s16, s17
	v_lshl_add_u64 v[220:221], s[52:53], 0, v[156:157]
	s_add_i32 m0, s65, 0xc000
	ds_read_b128 v[188:191], v174
	ds_read_b128 v[192:195], v174 offset:1024
	ds_read_b128 v[196:199], v174 offset:2048
	ds_read_b128 v[200:203], v174 offset:3072
	ds_read_b128 v[204:207], v174 offset:4096
	ds_read_b128 v[208:211], v174 offset:5120
	ds_read_b128 v[212:215], v174 offset:6144
	ds_read_b128 v[216:219], v174 offset:7168
	global_load_lds_dwordx4 v[220:221], off
	v_lshl_add_u64 v[220:221], s[52:53], 0, v[158:159]
	s_add_i32 m0, s65, 0xe000
	s_nop 0
	global_load_lds_dwordx4 v[220:221], off
	s_waitcnt vmcnt(8)
	s_waitcnt lgkmcnt(0)
	s_waitcnt lgkmcnt(0)
	v_mfma_f32_16x16x32_bf16 v[126:129], v[130:133], v[188:191], v[126:129]
	v_mfma_f32_16x16x32_bf16 v[122:125], v[138:141], v[188:191], v[122:125]
	v_mfma_f32_16x16x32_bf16 v[110:113], v[130:133], v[196:199], v[110:113]
	v_mfma_f32_16x16x32_bf16 v[106:109], v[138:141], v[196:199], v[106:109]
	s_barrier
	s_setprio 1
	v_mfma_f32_16x16x32_bf16 v[94:97], v[130:133], v[204:207], v[94:97]
	v_mfma_f32_16x16x32_bf16 v[90:93], v[138:141], v[204:207], v[90:93]
	v_mfma_f32_16x16x32_bf16 v[78:81], v[130:133], v[212:215], v[78:81]
	v_mfma_f32_16x16x32_bf16 v[74:77], v[138:141], v[212:215], v[74:77]
	v_mfma_f32_16x16x32_bf16 v[126:129], v[134:137], v[192:195], v[126:129]
	v_mfma_f32_16x16x32_bf16 v[122:125], v[142:145], v[192:195], v[122:125]
	v_mfma_f32_16x16x32_bf16 v[110:113], v[134:137], v[200:203], v[110:113]
	v_mfma_f32_16x16x32_bf16 v[106:109], v[142:145], v[200:203], v[106:109]
	v_mfma_f32_16x16x32_bf16 v[94:97], v[134:137], v[208:211], v[94:97]
	v_mfma_f32_16x16x32_bf16 v[90:93], v[142:145], v[208:211], v[90:93]
	v_mfma_f32_16x16x32_bf16 v[78:81], v[134:137], v[216:219], v[78:81]
	v_mfma_f32_16x16x32_bf16 v[74:77], v[142:145], v[216:219], v[74:77]
	s_setprio 0
	s_setprio 1
	v_mfma_f32_16x16x32_bf16 v[118:121], v[166:169], v[188:191], v[118:121]
	v_mfma_f32_16x16x32_bf16 v[114:117], v[180:183], v[188:191], v[114:117]
	v_mfma_f32_16x16x32_bf16 v[102:105], v[166:169], v[196:199], v[102:105]
	v_mfma_f32_16x16x32_bf16 v[98:101], v[180:183], v[196:199], v[98:101]
	v_mfma_f32_16x16x32_bf16 v[86:89], v[166:169], v[204:207], v[86:89]
	v_mfma_f32_16x16x32_bf16 v[82:85], v[180:183], v[204:207], v[82:85]
	v_mfma_f32_16x16x32_bf16 v[70:73], v[166:169], v[212:215], v[70:73]
	v_mfma_f32_16x16x32_bf16 v[66:69], v[180:183], v[212:215], v[66:69]
	v_mfma_f32_16x16x32_bf16 v[118:121], v[176:179], v[192:195], v[118:121]
	v_mfma_f32_16x16x32_bf16 v[114:117], v[184:187], v[192:195], v[114:117]
	v_mfma_f32_16x16x32_bf16 v[102:105], v[176:179], v[200:203], v[102:105]
	v_mfma_f32_16x16x32_bf16 v[98:101], v[184:187], v[200:203], v[98:101]
	v_mfma_f32_16x16x32_bf16 v[86:89], v[176:179], v[208:211], v[86:89]
	v_mfma_f32_16x16x32_bf16 v[82:85], v[184:187], v[208:211], v[82:85]
	v_mfma_f32_16x16x32_bf16 v[70:73], v[176:179], v[216:219], v[70:73]
	v_mfma_f32_16x16x32_bf16 v[66:69], v[184:187], v[216:219], v[66:69]
	s_setprio 0
	s_barrier
	s_add_i32 s20, s77, s64
	v_lshl_add_u64 v[220:221], s[54:55], 0, v[146:147]
	s_mov_b32 m0, s20
	ds_read_b128 v[188:191], v174 offset:16384
	ds_read_b128 v[192:195], v174 offset:17408
	ds_read_b128 v[196:199], v174 offset:18432
	ds_read_b128 v[200:203], v174 offset:19456
	ds_read_b128 v[204:207], v174 offset:20480
	ds_read_b128 v[208:211], v174 offset:21504
	ds_read_b128 v[212:215], v174 offset:22528
	ds_read_b128 v[216:219], v174 offset:23552
	global_load_lds_dwordx4 v[220:221], off
	s_add_i32 m0, s20, 0x2000
	s_add_u32 s20, s54, 0x80000
	v_lshl_add_u64 v[222:223], s[54:55], 0, v[148:149]
	s_addc_u32 s21, s55, 0
	s_add_i32 s43, s78, s64
	global_load_lds_dwordx4 v[222:223], off
	v_lshl_add_u64 v[224:225], s[20:21], 0, v[146:147]
	s_mov_b32 m0, s43
	v_lshl_add_u64 v[226:227], s[56:57], 0, v[148:149]
	global_load_lds_dwordx4 v[224:225], off
	v_lshl_add_u64 v[224:225], s[20:21], 0, v[148:149]
	s_add_i32 m0, s43, 0x2000
	s_nop 0
	global_load_lds_dwordx4 v[224:225], off
	v_lshl_add_u64 v[224:225], s[56:57], 0, v[146:147]
	s_mov_b32 m0, s65
	s_nop 0
	global_load_lds_dwordx4 v[224:225], off
	s_mov_b32 m0, s66
	s_nop 0
	global_load_lds_dwordx4 v[226:227], off
	s_waitcnt vmcnt(8)
	s_waitcnt lgkmcnt(0)
	s_waitcnt lgkmcnt(0)
	v_mfma_f32_16x16x32_bf16 v[62:65], v[130:133], v[188:191], v[62:65]
	v_mfma_f32_16x16x32_bf16 v[58:61], v[138:141], v[188:191], v[58:61]
	v_mfma_f32_16x16x32_bf16 v[46:49], v[130:133], v[196:199], v[46:49]
	v_mfma_f32_16x16x32_bf16 v[42:45], v[138:141], v[196:199], v[42:45]
	s_barrier
	s_setprio 1
	v_mfma_f32_16x16x32_bf16 v[30:33], v[130:133], v[204:207], v[30:33]
	v_mfma_f32_16x16x32_bf16 v[26:29], v[138:141], v[204:207], v[26:29]
	v_mfma_f32_16x16x32_bf16 v[14:17], v[130:133], v[212:215], v[14:17]
	v_mfma_f32_16x16x32_bf16 v[10:13], v[138:141], v[212:215], v[10:13]
	v_mfma_f32_16x16x32_bf16 v[62:65], v[134:137], v[192:195], v[62:65]
	v_mfma_f32_16x16x32_bf16 v[58:61], v[142:145], v[192:195], v[58:61]
	v_mfma_f32_16x16x32_bf16 v[46:49], v[134:137], v[200:203], v[46:49]
	v_mfma_f32_16x16x32_bf16 v[42:45], v[142:145], v[200:203], v[42:45]
	v_mfma_f32_16x16x32_bf16 v[30:33], v[134:137], v[208:211], v[30:33]
	v_mfma_f32_16x16x32_bf16 v[26:29], v[142:145], v[208:211], v[26:29]
	v_mfma_f32_16x16x32_bf16 v[14:17], v[134:137], v[216:219], v[14:17]
	v_mfma_f32_16x16x32_bf16 v[10:13], v[142:145], v[216:219], v[10:13]
	s_setprio 0
	s_setprio 1
	v_mfma_f32_16x16x32_bf16 v[54:57], v[166:169], v[188:191], v[54:57]
	v_mfma_f32_16x16x32_bf16 v[50:53], v[180:183], v[188:191], v[50:53]
	v_mfma_f32_16x16x32_bf16 v[38:41], v[166:169], v[196:199], v[38:41]
	v_mfma_f32_16x16x32_bf16 v[34:37], v[180:183], v[196:199], v[34:37]
	v_mfma_f32_16x16x32_bf16 v[22:25], v[166:169], v[204:207], v[22:25]
	v_mfma_f32_16x16x32_bf16 v[18:21], v[180:183], v[204:207], v[18:21]
	v_mfma_f32_16x16x32_bf16 v[6:9], v[166:169], v[212:215], v[6:9]
	v_mfma_f32_16x16x32_bf16 v[2:5], v[180:183], v[212:215], v[2:5]
	v_mfma_f32_16x16x32_bf16 v[54:57], v[176:179], v[192:195], v[54:57]
	v_mfma_f32_16x16x32_bf16 v[50:53], v[184:187], v[192:195], v[50:53]
	v_mfma_f32_16x16x32_bf16 v[38:41], v[176:179], v[200:203], v[38:41]
	v_mfma_f32_16x16x32_bf16 v[34:37], v[184:187], v[200:203], v[34:37]
	v_mfma_f32_16x16x32_bf16 v[22:25], v[176:179], v[208:211], v[22:25]
	v_mfma_f32_16x16x32_bf16 v[18:21], v[184:187], v[208:211], v[18:21]
	v_mfma_f32_16x16x32_bf16 v[6:9], v[176:179], v[216:219], v[6:9]
	v_mfma_f32_16x16x32_bf16 v[2:5], v[184:187], v[216:219], v[2:5]
	s_setprio 0
	s_barrier
	s_add_i32 s43, 0, 0x18000
	s_add_i32 s45, 0, 0x1c000
	v_add_u32_e32 v142, s43, v170
	v_add_u32_e32 v184, s45, v170
	ds_read_b128 v[130:133], v142
	ds_read_b128 v[134:137], v142 offset:1024
	ds_read_b128 v[138:141], v142 offset:2048
	ds_read_b128 v[142:145], v142 offset:3072
	ds_read_b128 v[166:169], v184
	ds_read_b128 v[176:179], v184 offset:1024
	ds_read_b128 v[180:183], v184 offset:2048
	ds_read_b128 v[184:187], v184 offset:3072
	s_add_u32 s20, s56, 0x80000
	s_addc_u32 s21, s57, 0
	s_mov_b32 m0, s67
	v_lshl_add_u64 v[228:229], s[20:21], 0, v[146:147]
	ds_read_b128 v[188:191], v174 offset:32768
	ds_read_b128 v[192:195], v174 offset:33792
	ds_read_b128 v[196:199], v174 offset:34816
	ds_read_b128 v[200:203], v174 offset:35840
	ds_read_b128 v[204:207], v174 offset:36864
	ds_read_b128 v[208:211], v174 offset:37888
	ds_read_b128 v[212:215], v174 offset:38912
	ds_read_b128 v[216:219], v174 offset:39936
	global_load_lds_dwordx4 v[228:229], off
	v_lshl_add_u64 v[228:229], s[20:21], 0, v[148:149]
	s_mov_b32 m0, s68
	s_nop 0
	global_load_lds_dwordx4 v[228:229], off
	s_waitcnt vmcnt(8)
	s_waitcnt lgkmcnt(0)
	s_waitcnt lgkmcnt(0)
	v_mfma_f32_16x16x32_bf16 v[126:129], v[130:133], v[188:191], v[126:129]
	v_mfma_f32_16x16x32_bf16 v[122:125], v[138:141], v[188:191], v[122:125]
	v_mfma_f32_16x16x32_bf16 v[110:113], v[130:133], v[196:199], v[110:113]
	v_mfma_f32_16x16x32_bf16 v[106:109], v[138:141], v[196:199], v[106:109]
	s_barrier
	s_setprio 1
	v_mfma_f32_16x16x32_bf16 v[94:97], v[130:133], v[204:207], v[94:97]
	v_mfma_f32_16x16x32_bf16 v[90:93], v[138:141], v[204:207], v[90:93]
	v_mfma_f32_16x16x32_bf16 v[78:81], v[130:133], v[212:215], v[78:81]
	v_mfma_f32_16x16x32_bf16 v[74:77], v[138:141], v[212:215], v[74:77]
	v_mfma_f32_16x16x32_bf16 v[126:129], v[134:137], v[192:195], v[126:129]
	v_mfma_f32_16x16x32_bf16 v[122:125], v[142:145], v[192:195], v[122:125]
	v_mfma_f32_16x16x32_bf16 v[110:113], v[134:137], v[200:203], v[110:113]
	v_mfma_f32_16x16x32_bf16 v[106:109], v[142:145], v[200:203], v[106:109]
	v_mfma_f32_16x16x32_bf16 v[94:97], v[134:137], v[208:211], v[94:97]
	v_mfma_f32_16x16x32_bf16 v[90:93], v[142:145], v[208:211], v[90:93]
	v_mfma_f32_16x16x32_bf16 v[78:81], v[134:137], v[216:219], v[78:81]
	v_mfma_f32_16x16x32_bf16 v[74:77], v[142:145], v[216:219], v[74:77]
	s_setprio 0
	s_setprio 1
	v_mfma_f32_16x16x32_bf16 v[118:121], v[166:169], v[188:191], v[118:121]
	v_mfma_f32_16x16x32_bf16 v[114:117], v[180:183], v[188:191], v[114:117]
	v_mfma_f32_16x16x32_bf16 v[102:105], v[166:169], v[196:199], v[102:105]
	v_mfma_f32_16x16x32_bf16 v[98:101], v[180:183], v[196:199], v[98:101]
	v_mfma_f32_16x16x32_bf16 v[86:89], v[166:169], v[204:207], v[86:89]
	v_mfma_f32_16x16x32_bf16 v[82:85], v[180:183], v[204:207], v[82:85]
	v_mfma_f32_16x16x32_bf16 v[70:73], v[166:169], v[212:215], v[70:73]
	v_mfma_f32_16x16x32_bf16 v[66:69], v[180:183], v[212:215], v[66:69]
	v_mfma_f32_16x16x32_bf16 v[118:121], v[176:179], v[192:195], v[118:121]
	v_mfma_f32_16x16x32_bf16 v[114:117], v[184:187], v[192:195], v[114:117]
	v_mfma_f32_16x16x32_bf16 v[102:105], v[176:179], v[200:203], v[102:105]
	v_mfma_f32_16x16x32_bf16 v[98:101], v[184:187], v[200:203], v[98:101]
	v_mfma_f32_16x16x32_bf16 v[86:89], v[176:179], v[208:211], v[86:89]
	v_mfma_f32_16x16x32_bf16 v[82:85], v[184:187], v[208:211], v[82:85]
	v_mfma_f32_16x16x32_bf16 v[70:73], v[176:179], v[216:219], v[70:73]
	v_mfma_f32_16x16x32_bf16 v[66:69], v[184:187], v[216:219], v[66:69]
	s_setprio 0
	s_barrier
	s_add_i32 s20, s43, s64
	v_lshl_add_u64 v[220:221], v[220:221], 0, s[26:27]
	s_mov_b32 m0, s20
	ds_read_b128 v[188:191], v174 offset:49152
	ds_read_b128 v[192:195], v174 offset:50176
	ds_read_b128 v[196:199], v174 offset:51200
	ds_read_b128 v[200:203], v174 offset:52224
	ds_read_b128 v[204:207], v174 offset:53248
	ds_read_b128 v[208:211], v174 offset:54272
	ds_read_b128 v[212:215], v174 offset:55296
	ds_read_b128 v[216:219], v174 offset:56320
	global_load_lds_dwordx4 v[220:221], off
	s_add_i32 m0, s20, 0x2000
	s_add_u32 s20, s54, 0x80080
	v_lshl_add_u64 v[220:221], v[222:223], 0, s[26:27]
	s_addc_u32 s21, s55, 0
	s_add_i32 s43, s45, s64
	global_load_lds_dwordx4 v[220:221], off
	v_lshl_add_u64 v[220:221], s[20:21], 0, v[146:147]
	s_mov_b32 m0, s43
	s_nop 0
	global_load_lds_dwordx4 v[220:221], off
	v_lshl_add_u64 v[220:221], s[20:21], 0, v[148:149]
	s_add_i32 m0, s43, 0x2000
	s_nop 0
	global_load_lds_dwordx4 v[220:221], off
	v_lshl_add_u64 v[220:221], v[224:225], 0, s[26:27]
	s_mov_b32 m0, s73
	s_nop 0
	global_load_lds_dwordx4 v[220:221], off
	v_lshl_add_u64 v[220:221], v[226:227], 0, s[26:27]
	s_mov_b32 m0, s74
	s_nop 0
	global_load_lds_dwordx4 v[220:221], off
	s_waitcnt vmcnt(8)
	s_waitcnt lgkmcnt(0)
	s_waitcnt lgkmcnt(0)
	v_mfma_f32_16x16x32_bf16 v[62:65], v[130:133], v[188:191], v[62:65]
	v_mfma_f32_16x16x32_bf16 v[58:61], v[138:141], v[188:191], v[58:61]
	v_mfma_f32_16x16x32_bf16 v[46:49], v[130:133], v[196:199], v[46:49]
	v_mfma_f32_16x16x32_bf16 v[42:45], v[138:141], v[196:199], v[42:45]
	s_barrier
	s_setprio 1
	v_mfma_f32_16x16x32_bf16 v[30:33], v[130:133], v[204:207], v[30:33]
	v_mfma_f32_16x16x32_bf16 v[26:29], v[138:141], v[204:207], v[26:29]
	v_mfma_f32_16x16x32_bf16 v[14:17], v[130:133], v[212:215], v[14:17]
	v_mfma_f32_16x16x32_bf16 v[10:13], v[138:141], v[212:215], v[10:13]
	v_mfma_f32_16x16x32_bf16 v[62:65], v[134:137], v[192:195], v[62:65]
	v_mfma_f32_16x16x32_bf16 v[58:61], v[142:145], v[192:195], v[58:61]
	v_mfma_f32_16x16x32_bf16 v[46:49], v[134:137], v[200:203], v[46:49]
	v_mfma_f32_16x16x32_bf16 v[42:45], v[142:145], v[200:203], v[42:45]
	v_mfma_f32_16x16x32_bf16 v[30:33], v[134:137], v[208:211], v[30:33]
	v_mfma_f32_16x16x32_bf16 v[26:29], v[142:145], v[208:211], v[26:29]
	v_mfma_f32_16x16x32_bf16 v[14:17], v[134:137], v[216:219], v[14:17]
	v_mfma_f32_16x16x32_bf16 v[10:13], v[142:145], v[216:219], v[10:13]
	s_setprio 0
	s_setprio 1
	v_mfma_f32_16x16x32_bf16 v[54:57], v[166:169], v[188:191], v[54:57]
	v_mfma_f32_16x16x32_bf16 v[50:53], v[180:183], v[188:191], v[50:53]
	v_mfma_f32_16x16x32_bf16 v[38:41], v[166:169], v[196:199], v[38:41]
	v_mfma_f32_16x16x32_bf16 v[34:37], v[180:183], v[196:199], v[34:37]
	v_mfma_f32_16x16x32_bf16 v[22:25], v[166:169], v[204:207], v[22:25]
	v_mfma_f32_16x16x32_bf16 v[18:21], v[180:183], v[204:207], v[18:21]
	v_mfma_f32_16x16x32_bf16 v[6:9], v[166:169], v[212:215], v[6:9]
	v_mfma_f32_16x16x32_bf16 v[2:5], v[180:183], v[212:215], v[2:5]
	v_mfma_f32_16x16x32_bf16 v[54:57], v[176:179], v[192:195], v[54:57]
	v_mfma_f32_16x16x32_bf16 v[50:53], v[184:187], v[192:195], v[50:53]
	v_mfma_f32_16x16x32_bf16 v[38:41], v[176:179], v[200:203], v[38:41]
	v_mfma_f32_16x16x32_bf16 v[34:37], v[184:187], v[200:203], v[34:37]
	v_mfma_f32_16x16x32_bf16 v[22:25], v[176:179], v[208:211], v[22:25]
	v_mfma_f32_16x16x32_bf16 v[18:21], v[184:187], v[208:211], v[18:21]
	v_mfma_f32_16x16x32_bf16 v[6:9], v[176:179], v[216:219], v[6:9]
	v_mfma_f32_16x16x32_bf16 v[2:5], v[184:187], v[216:219], v[2:5]
	s_setprio 0
	s_barrier
	s_add_i32 s19, s19, 2
	s_add_u32 s52, s52, 0x100
	s_addc_u32 s53, s53, 0
	s_add_u32 s17, s17, 0x100
	s_addc_u32 s18, s18, 0
	s_cmp_gt_u32 s19, 29
	s_cbranch_scc0 .LBB0_986
	s_and_b64 vcc, exec, s[28:29]
	s_cbranch_vccnz .LBB0_991
	v_lshl_add_u32 v166, s50, 8, v163
	s_cmp_gt_i32 s10, 1
	s_mov_b64 s[50:51], -1
	s_cbranch_scc1 .LBB0_992

.LBB0_1213:
	ds_read_b128 v[130:133], v189
	ds_read_b128 v[134:137], v189 offset:1024
	ds_read_b128 v[138:141], v189 offset:2048
	ds_read_b128 v[142:145], v189 offset:3072
	ds_read_b128 v[164:167], v190
	ds_read_b128 v[168:171], v190 offset:1024
	ds_read_b128 v[172:175], v190 offset:2048
	ds_read_b128 v[194:197], v190 offset:3072
	s_add_u32 s20, s52, 0xfff80080
	s_addc_u32 s21, s53, -1
	s_cmp_eq_u32 s19, 28
	s_cselect_b32 s57, s3, s21
	s_cselect_b32 s56, s14, s20
	s_cselect_b32 s55, s15, s18
	s_cselect_b32 s54, s16, s17
	v_lshl_add_u64 v[230:231], s[52:53], 0, v[154:155]
	s_add_i32 m0, s65, 0xc000
	ds_read_b128 v[198:201], v191
	ds_read_b128 v[202:205], v191 offset:1024
	ds_read_b128 v[206:209], v191 offset:2048
	ds_read_b128 v[210:213], v191 offset:3072
	ds_read_b128 v[214:217], v191 offset:4096
	ds_read_b128 v[218:221], v191 offset:5120
	ds_read_b128 v[222:225], v191 offset:6144
	ds_read_b128 v[226:229], v191 offset:7168
	global_load_lds_dwordx4 v[230:231], off
	v_lshl_add_u64 v[230:231], s[52:53], 0, v[156:157]
	s_add_i32 m0, s65, 0xe000
	s_nop 0
	global_load_lds_dwordx4 v[230:231], off
	s_waitcnt vmcnt(8)
	s_waitcnt lgkmcnt(0)
	s_waitcnt lgkmcnt(0)
	v_mfma_f32_16x16x32_bf16 v[126:129], v[130:133], v[198:201], v[126:129]
	v_mfma_f32_16x16x32_bf16 v[122:125], v[138:141], v[198:201], v[122:125]
	v_mfma_f32_16x16x32_bf16 v[110:113], v[130:133], v[206:209], v[110:113]
	v_mfma_f32_16x16x32_bf16 v[106:109], v[138:141], v[206:209], v[106:109]
	s_barrier
	s_setprio 1
	v_mfma_f32_16x16x32_bf16 v[94:97], v[130:133], v[214:217], v[94:97]
	v_mfma_f32_16x16x32_bf16 v[90:93], v[138:141], v[214:217], v[90:93]
	v_mfma_f32_16x16x32_bf16 v[78:81], v[130:133], v[222:225], v[78:81]
	v_mfma_f32_16x16x32_bf16 v[74:77], v[138:141], v[222:225], v[74:77]
	v_mfma_f32_16x16x32_bf16 v[126:129], v[134:137], v[202:205], v[126:129]
	v_mfma_f32_16x16x32_bf16 v[122:125], v[142:145], v[202:205], v[122:125]
	v_mfma_f32_16x16x32_bf16 v[110:113], v[134:137], v[210:213], v[110:113]
	v_mfma_f32_16x16x32_bf16 v[106:109], v[142:145], v[210:213], v[106:109]
	v_mfma_f32_16x16x32_bf16 v[94:97], v[134:137], v[218:221], v[94:97]
	v_mfma_f32_16x16x32_bf16 v[90:93], v[142:145], v[218:221], v[90:93]
	v_mfma_f32_16x16x32_bf16 v[78:81], v[134:137], v[226:229], v[78:81]
	v_mfma_f32_16x16x32_bf16 v[74:77], v[142:145], v[226:229], v[74:77]
	s_setprio 0
	s_setprio 1
	v_mfma_f32_16x16x32_bf16 v[118:121], v[164:167], v[198:201], v[118:121]
	v_mfma_f32_16x16x32_bf16 v[114:117], v[172:175], v[198:201], v[114:117]
	v_mfma_f32_16x16x32_bf16 v[102:105], v[164:167], v[206:209], v[102:105]
	v_mfma_f32_16x16x32_bf16 v[98:101], v[172:175], v[206:209], v[98:101]
	v_mfma_f32_16x16x32_bf16 v[86:89], v[164:167], v[214:217], v[86:89]
	v_mfma_f32_16x16x32_bf16 v[82:85], v[172:175], v[214:217], v[82:85]
	v_mfma_f32_16x16x32_bf16 v[70:73], v[164:167], v[222:225], v[70:73]
	v_mfma_f32_16x16x32_bf16 v[66:69], v[172:175], v[222:225], v[66:69]
	v_mfma_f32_16x16x32_bf16 v[118:121], v[168:171], v[202:205], v[118:121]
	v_mfma_f32_16x16x32_bf16 v[114:117], v[194:197], v[202:205], v[114:117]
	v_mfma_f32_16x16x32_bf16 v[102:105], v[168:171], v[210:213], v[102:105]
	v_mfma_f32_16x16x32_bf16 v[98:101], v[194:197], v[210:213], v[98:101]
	v_mfma_f32_16x16x32_bf16 v[86:89], v[168:171], v[218:221], v[86:89]
	v_mfma_f32_16x16x32_bf16 v[82:85], v[194:197], v[218:221], v[82:85]
	v_mfma_f32_16x16x32_bf16 v[70:73], v[168:171], v[226:229], v[70:73]
	v_mfma_f32_16x16x32_bf16 v[66:69], v[194:197], v[226:229], v[66:69]
	s_setprio 0
	s_barrier
	s_add_i32 s20, s77, s64
	v_lshl_add_u64 v[230:231], s[54:55], 0, v[146:147]
	s_mov_b32 m0, s20
	ds_read_b128 v[198:201], v191 offset:16384
	ds_read_b128 v[202:205], v191 offset:17408
	ds_read_b128 v[206:209], v191 offset:18432
	ds_read_b128 v[210:213], v191 offset:19456
	ds_read_b128 v[214:217], v191 offset:20480
	ds_read_b128 v[218:221], v191 offset:21504
	ds_read_b128 v[222:225], v191 offset:22528
	ds_read_b128 v[226:229], v191 offset:23552
	global_load_lds_dwordx4 v[230:231], off
	s_add_i32 m0, s20, 0x2000
	s_add_u32 s20, s54, 0x80000
	v_lshl_add_u64 v[232:233], s[54:55], 0, v[148:149]
	s_addc_u32 s21, s55, 0
	s_add_i32 s43, s78, s64
	global_load_lds_dwordx4 v[232:233], off
	v_lshl_add_u64 v[234:235], s[20:21], 0, v[146:147]
	s_mov_b32 m0, s43
	v_lshl_add_u64 v[236:237], s[56:57], 0, v[148:149]
	global_load_lds_dwordx4 v[234:235], off
	v_lshl_add_u64 v[234:235], s[20:21], 0, v[148:149]
	s_add_i32 m0, s43, 0x2000
	s_nop 0
	global_load_lds_dwordx4 v[234:235], off
	v_lshl_add_u64 v[234:235], s[56:57], 0, v[146:147]
	s_mov_b32 m0, s65
	s_nop 0
	global_load_lds_dwordx4 v[234:235], off
	s_mov_b32 m0, s66
	s_nop 0
	global_load_lds_dwordx4 v[236:237], off
	s_waitcnt vmcnt(8)
	s_waitcnt lgkmcnt(0)
	s_waitcnt lgkmcnt(0)
	v_mfma_f32_16x16x32_bf16 v[62:65], v[130:133], v[198:201], v[62:65]
	v_mfma_f32_16x16x32_bf16 v[58:61], v[138:141], v[198:201], v[58:61]
	v_mfma_f32_16x16x32_bf16 v[46:49], v[130:133], v[206:209], v[46:49]
	v_mfma_f32_16x16x32_bf16 v[42:45], v[138:141], v[206:209], v[42:45]
	s_barrier
	s_setprio 1
	v_mfma_f32_16x16x32_bf16 v[30:33], v[130:133], v[214:217], v[30:33]
	v_mfma_f32_16x16x32_bf16 v[26:29], v[138:141], v[214:217], v[26:29]
	v_mfma_f32_16x16x32_bf16 v[14:17], v[130:133], v[222:225], v[14:17]
	v_mfma_f32_16x16x32_bf16 v[10:13], v[138:141], v[222:225], v[10:13]
	v_mfma_f32_16x16x32_bf16 v[62:65], v[134:137], v[202:205], v[62:65]
	v_mfma_f32_16x16x32_bf16 v[58:61], v[142:145], v[202:205], v[58:61]
	v_mfma_f32_16x16x32_bf16 v[46:49], v[134:137], v[210:213], v[46:49]
	v_mfma_f32_16x16x32_bf16 v[42:45], v[142:145], v[210:213], v[42:45]
	v_mfma_f32_16x16x32_bf16 v[30:33], v[134:137], v[218:221], v[30:33]
	v_mfma_f32_16x16x32_bf16 v[26:29], v[142:145], v[218:221], v[26:29]
	v_mfma_f32_16x16x32_bf16 v[14:17], v[134:137], v[226:229], v[14:17]
	v_mfma_f32_16x16x32_bf16 v[10:13], v[142:145], v[226:229], v[10:13]
	s_setprio 0
	s_setprio 1
	v_mfma_f32_16x16x32_bf16 v[54:57], v[164:167], v[198:201], v[54:57]
	v_mfma_f32_16x16x32_bf16 v[50:53], v[172:175], v[198:201], v[50:53]
	v_mfma_f32_16x16x32_bf16 v[38:41], v[164:167], v[206:209], v[38:41]
	v_mfma_f32_16x16x32_bf16 v[34:37], v[172:175], v[206:209], v[34:37]
	v_mfma_f32_16x16x32_bf16 v[22:25], v[164:167], v[214:217], v[22:25]
	v_mfma_f32_16x16x32_bf16 v[18:21], v[172:175], v[214:217], v[18:21]
	v_mfma_f32_16x16x32_bf16 v[6:9], v[164:167], v[222:225], v[6:9]
	v_mfma_f32_16x16x32_bf16 v[2:5], v[172:175], v[222:225], v[2:5]
	v_mfma_f32_16x16x32_bf16 v[54:57], v[168:171], v[202:205], v[54:57]
	v_mfma_f32_16x16x32_bf16 v[50:53], v[194:197], v[202:205], v[50:53]
	v_mfma_f32_16x16x32_bf16 v[38:41], v[168:171], v[210:213], v[38:41]
	v_mfma_f32_16x16x32_bf16 v[34:37], v[194:197], v[210:213], v[34:37]
	v_mfma_f32_16x16x32_bf16 v[22:25], v[168:171], v[218:221], v[22:25]
	v_mfma_f32_16x16x32_bf16 v[18:21], v[194:197], v[218:221], v[18:21]
	v_mfma_f32_16x16x32_bf16 v[6:9], v[168:171], v[226:229], v[6:9]
	v_mfma_f32_16x16x32_bf16 v[2:5], v[194:197], v[226:229], v[2:5]
	s_setprio 0
	s_barrier
	s_add_i32 s43, 0, 0x18000
	s_add_i32 s45, 0, 0x1c000
	v_add_u32_e32 v142, s43, v187
	v_add_u32_e32 v193, s45, v187
	ds_read_b128 v[130:133], v142
	ds_read_b128 v[134:137], v142 offset:1024
	ds_read_b128 v[138:141], v142 offset:2048
	ds_read_b128 v[142:145], v142 offset:3072
	ds_read_b128 v[164:167], v193
	ds_read_b128 v[168:171], v193 offset:1024
	ds_read_b128 v[172:175], v193 offset:2048
	ds_read_b128 v[194:197], v193 offset:3072
	s_add_u32 s20, s56, 0x80000
	s_addc_u32 s21, s57, 0
	s_mov_b32 m0, s67
	v_lshl_add_u64 v[238:239], s[20:21], 0, v[146:147]
	ds_read_b128 v[198:201], v191 offset:32768
	ds_read_b128 v[202:205], v191 offset:33792
	ds_read_b128 v[206:209], v191 offset:34816
	ds_read_b128 v[210:213], v191 offset:35840
	ds_read_b128 v[214:217], v191 offset:36864
	ds_read_b128 v[218:221], v191 offset:37888
	ds_read_b128 v[222:225], v191 offset:38912
	ds_read_b128 v[226:229], v191 offset:39936
	global_load_lds_dwordx4 v[238:239], off
	v_lshl_add_u64 v[238:239], s[20:21], 0, v[148:149]
	s_mov_b32 m0, s68
	s_nop 0
	global_load_lds_dwordx4 v[238:239], off
	s_waitcnt vmcnt(8)
	s_waitcnt lgkmcnt(0)
	s_waitcnt lgkmcnt(0)
	v_mfma_f32_16x16x32_bf16 v[126:129], v[130:133], v[198:201], v[126:129]
	v_mfma_f32_16x16x32_bf16 v[122:125], v[138:141], v[198:201], v[122:125]
	v_mfma_f32_16x16x32_bf16 v[110:113], v[130:133], v[206:209], v[110:113]
	v_mfma_f32_16x16x32_bf16 v[106:109], v[138:141], v[206:209], v[106:109]
	s_barrier
	s_setprio 1
	v_mfma_f32_16x16x32_bf16 v[94:97], v[130:133], v[214:217], v[94:97]
	v_mfma_f32_16x16x32_bf16 v[90:93], v[138:141], v[214:217], v[90:93]
	v_mfma_f32_16x16x32_bf16 v[78:81], v[130:133], v[222:225], v[78:81]
	v_mfma_f32_16x16x32_bf16 v[74:77], v[138:141], v[222:225], v[74:77]
	v_mfma_f32_16x16x32_bf16 v[126:129], v[134:137], v[202:205], v[126:129]
	v_mfma_f32_16x16x32_bf16 v[122:125], v[142:145], v[202:205], v[122:125]
	v_mfma_f32_16x16x32_bf16 v[110:113], v[134:137], v[210:213], v[110:113]
	v_mfma_f32_16x16x32_bf16 v[106:109], v[142:145], v[210:213], v[106:109]
	v_mfma_f32_16x16x32_bf16 v[94:97], v[134:137], v[218:221], v[94:97]
	v_mfma_f32_16x16x32_bf16 v[90:93], v[142:145], v[218:221], v[90:93]
	v_mfma_f32_16x16x32_bf16 v[78:81], v[134:137], v[226:229], v[78:81]
	v_mfma_f32_16x16x32_bf16 v[74:77], v[142:145], v[226:229], v[74:77]
	s_setprio 0
	s_setprio 1
	v_mfma_f32_16x16x32_bf16 v[118:121], v[164:167], v[198:201], v[118:121]
	v_mfma_f32_16x16x32_bf16 v[114:117], v[172:175], v[198:201], v[114:117]
	v_mfma_f32_16x16x32_bf16 v[102:105], v[164:167], v[206:209], v[102:105]
	v_mfma_f32_16x16x32_bf16 v[98:101], v[172:175], v[206:209], v[98:101]
	v_mfma_f32_16x16x32_bf16 v[86:89], v[164:167], v[214:217], v[86:89]
	v_mfma_f32_16x16x32_bf16 v[82:85], v[172:175], v[214:217], v[82:85]
	v_mfma_f32_16x16x32_bf16 v[70:73], v[164:167], v[222:225], v[70:73]
	v_mfma_f32_16x16x32_bf16 v[66:69], v[172:175], v[222:225], v[66:69]
	v_mfma_f32_16x16x32_bf16 v[118:121], v[168:171], v[202:205], v[118:121]
	v_mfma_f32_16x16x32_bf16 v[114:117], v[194:197], v[202:205], v[114:117]
	v_mfma_f32_16x16x32_bf16 v[102:105], v[168:171], v[210:213], v[102:105]
	v_mfma_f32_16x16x32_bf16 v[98:101], v[194:197], v[210:213], v[98:101]
	v_mfma_f32_16x16x32_bf16 v[86:89], v[168:171], v[218:221], v[86:89]
	v_mfma_f32_16x16x32_bf16 v[82:85], v[194:197], v[218:221], v[82:85]
	v_mfma_f32_16x16x32_bf16 v[70:73], v[168:171], v[226:229], v[70:73]
	v_mfma_f32_16x16x32_bf16 v[66:69], v[194:197], v[226:229], v[66:69]
	s_setprio 0
	s_barrier
	s_add_i32 s20, s43, s64
	v_lshl_add_u64 v[230:231], v[230:231], 0, s[26:27]
	s_mov_b32 m0, s20
	ds_read_b128 v[198:201], v191 offset:49152
	ds_read_b128 v[202:205], v191 offset:50176
	ds_read_b128 v[206:209], v191 offset:51200
	ds_read_b128 v[210:213], v191 offset:52224
	ds_read_b128 v[214:217], v191 offset:53248
	ds_read_b128 v[218:221], v191 offset:54272
	ds_read_b128 v[222:225], v191 offset:55296
	ds_read_b128 v[226:229], v191 offset:56320
	global_load_lds_dwordx4 v[230:231], off
	s_add_i32 m0, s20, 0x2000
	s_add_u32 s20, s54, 0x80080
	v_lshl_add_u64 v[230:231], v[232:233], 0, s[26:27]
	s_addc_u32 s21, s55, 0
	s_add_i32 s43, s45, s64
	global_load_lds_dwordx4 v[230:231], off
	v_lshl_add_u64 v[230:231], s[20:21], 0, v[146:147]
	s_mov_b32 m0, s43
	s_nop 0
	global_load_lds_dwordx4 v[230:231], off
	v_lshl_add_u64 v[230:231], s[20:21], 0, v[148:149]
	s_add_i32 m0, s43, 0x2000
	s_nop 0
	global_load_lds_dwordx4 v[230:231], off
	v_lshl_add_u64 v[230:231], v[234:235], 0, s[26:27]
	s_mov_b32 m0, s73
	s_nop 0
	global_load_lds_dwordx4 v[230:231], off
	v_lshl_add_u64 v[230:231], v[236:237], 0, s[26:27]
	s_mov_b32 m0, s74
	s_nop 0
	global_load_lds_dwordx4 v[230:231], off
	s_waitcnt vmcnt(8)
	s_waitcnt lgkmcnt(0)
	s_waitcnt lgkmcnt(0)
	v_mfma_f32_16x16x32_bf16 v[62:65], v[130:133], v[198:201], v[62:65]
	v_mfma_f32_16x16x32_bf16 v[58:61], v[138:141], v[198:201], v[58:61]
	v_mfma_f32_16x16x32_bf16 v[46:49], v[130:133], v[206:209], v[46:49]
	v_mfma_f32_16x16x32_bf16 v[42:45], v[138:141], v[206:209], v[42:45]
	s_barrier
	s_setprio 1
	v_mfma_f32_16x16x32_bf16 v[30:33], v[130:133], v[214:217], v[30:33]
	v_mfma_f32_16x16x32_bf16 v[26:29], v[138:141], v[214:217], v[26:29]
	v_mfma_f32_16x16x32_bf16 v[14:17], v[130:133], v[222:225], v[14:17]
	v_mfma_f32_16x16x32_bf16 v[10:13], v[138:141], v[222:225], v[10:13]
	v_mfma_f32_16x16x32_bf16 v[62:65], v[134:137], v[202:205], v[62:65]
	v_mfma_f32_16x16x32_bf16 v[58:61], v[142:145], v[202:205], v[58:61]
	v_mfma_f32_16x16x32_bf16 v[46:49], v[134:137], v[210:213], v[46:49]
	v_mfma_f32_16x16x32_bf16 v[42:45], v[142:145], v[210:213], v[42:45]
	v_mfma_f32_16x16x32_bf16 v[30:33], v[134:137], v[218:221], v[30:33]
	v_mfma_f32_16x16x32_bf16 v[26:29], v[142:145], v[218:221], v[26:29]
	v_mfma_f32_16x16x32_bf16 v[14:17], v[134:137], v[226:229], v[14:17]
	v_mfma_f32_16x16x32_bf16 v[10:13], v[142:145], v[226:229], v[10:13]
	s_setprio 0
	s_setprio 1
	v_mfma_f32_16x16x32_bf16 v[54:57], v[164:167], v[198:201], v[54:57]
	v_mfma_f32_16x16x32_bf16 v[50:53], v[172:175], v[198:201], v[50:53]
	v_mfma_f32_16x16x32_bf16 v[38:41], v[164:167], v[206:209], v[38:41]
	v_mfma_f32_16x16x32_bf16 v[34:37], v[172:175], v[206:209], v[34:37]
	v_mfma_f32_16x16x32_bf16 v[22:25], v[164:167], v[214:217], v[22:25]
	v_mfma_f32_16x16x32_bf16 v[18:21], v[172:175], v[214:217], v[18:21]
	v_mfma_f32_16x16x32_bf16 v[6:9], v[164:167], v[222:225], v[6:9]
	v_mfma_f32_16x16x32_bf16 v[2:5], v[172:175], v[222:225], v[2:5]
	v_mfma_f32_16x16x32_bf16 v[54:57], v[168:171], v[202:205], v[54:57]
	v_mfma_f32_16x16x32_bf16 v[50:53], v[194:197], v[202:205], v[50:53]
	v_mfma_f32_16x16x32_bf16 v[38:41], v[168:171], v[210:213], v[38:41]
	v_mfma_f32_16x16x32_bf16 v[34:37], v[194:197], v[210:213], v[34:37]
	v_mfma_f32_16x16x32_bf16 v[22:25], v[168:171], v[218:221], v[22:25]
	v_mfma_f32_16x16x32_bf16 v[18:21], v[194:197], v[218:221], v[18:21]
	v_mfma_f32_16x16x32_bf16 v[6:9], v[168:171], v[226:229], v[6:9]
	v_mfma_f32_16x16x32_bf16 v[2:5], v[194:197], v[226:229], v[2:5]
	s_setprio 0
	s_barrier
	s_add_i32 s19, s19, 2
	s_add_u32 s52, s52, 0x100
	s_addc_u32 s53, s53, 0
	s_add_u32 s17, s17, 0x100
	s_addc_u32 s18, s18, 0
	s_cmp_gt_u32 s19, 29
	s_cbranch_scc0 .LBB0_1213
	s_and_b64 vcc, exec, s[28:29]
	s_cbranch_vccnz .LBB0_1218
	v_lshl_add_u32 v164, s50, 8, v186
	s_cmp_gt_i32 s10, 1
	s_mov_b64 s[50:51], -1
	s_cbranch_scc1 .LBB0_1219

.LBB0_1264:
	ds_read_b128 v[142:145], v163
	ds_read_b128 v[146:149], v163 offset:1024
	ds_read_b128 v[150:153], v163 offset:2048
	ds_read_b128 v[154:157], v163 offset:3072
	ds_read_b128 v[170:173], v166
	ds_read_b128 v[174:177], v166 offset:1024
	ds_read_b128 v[178:181], v166 offset:2048
	ds_read_b128 v[182:185], v166 offset:3072
	s_add_u32 s44, s42, 0xfffe0080
	s_addc_u32 s45, s43, -1
	s_cmp_eq_u32 s29, 4
	s_cselect_b32 s47, s3, s45
	s_cselect_b32 s46, s16, s44
	s_cselect_b32 s45, s17, s27
	s_cselect_b32 s44, s18, s19
	v_lshl_add_u64 v[218:219], s[42:43], 0, v[138:139]
	s_add_i32 m0, s39, 0xc000
	ds_read_b128 v[186:189], v167
	ds_read_b128 v[190:193], v167 offset:1024
	ds_read_b128 v[194:197], v167 offset:2048
	ds_read_b128 v[198:201], v167 offset:3072
	ds_read_b128 v[202:205], v167 offset:4096
	ds_read_b128 v[206:209], v167 offset:5120
	ds_read_b128 v[210:213], v167 offset:6144
	ds_read_b128 v[214:217], v167 offset:7168
	global_load_lds_dwordx4 v[218:219], off
	v_lshl_add_u64 v[218:219], s[42:43], 0, v[140:141]
	s_add_i32 m0, s39, 0xe000
	s_nop 0
	global_load_lds_dwordx4 v[218:219], off
	s_waitcnt vmcnt(8)
	s_waitcnt lgkmcnt(0)
	s_waitcnt lgkmcnt(0)
	v_mfma_f32_16x16x32_bf16 v[126:129], v[142:145], v[186:189], v[126:129]
	v_mfma_f32_16x16x32_bf16 v[122:125], v[150:153], v[186:189], v[122:125]
	v_mfma_f32_16x16x32_bf16 v[118:121], v[142:145], v[194:197], v[118:121]
	v_mfma_f32_16x16x32_bf16 v[110:113], v[150:153], v[194:197], v[110:113]
	s_barrier
	s_setprio 1
	v_mfma_f32_16x16x32_bf16 v[102:105], v[142:145], v[202:205], v[102:105]
	v_mfma_f32_16x16x32_bf16 v[94:97], v[150:153], v[202:205], v[94:97]
	v_mfma_f32_16x16x32_bf16 v[86:89], v[142:145], v[210:213], v[86:89]
	v_mfma_f32_16x16x32_bf16 v[78:81], v[150:153], v[210:213], v[78:81]
	v_mfma_f32_16x16x32_bf16 v[126:129], v[146:149], v[190:193], v[126:129]
	v_mfma_f32_16x16x32_bf16 v[122:125], v[154:157], v[190:193], v[122:125]
	v_mfma_f32_16x16x32_bf16 v[118:121], v[146:149], v[198:201], v[118:121]
	v_mfma_f32_16x16x32_bf16 v[110:113], v[154:157], v[198:201], v[110:113]
	v_mfma_f32_16x16x32_bf16 v[102:105], v[146:149], v[206:209], v[102:105]
	v_mfma_f32_16x16x32_bf16 v[94:97], v[154:157], v[206:209], v[94:97]
	v_mfma_f32_16x16x32_bf16 v[86:89], v[146:149], v[214:217], v[86:89]
	v_mfma_f32_16x16x32_bf16 v[78:81], v[154:157], v[214:217], v[78:81]
	s_setprio 0
	s_setprio 1
	v_mfma_f32_16x16x32_bf16 v[114:117], v[170:173], v[186:189], v[114:117]
	v_mfma_f32_16x16x32_bf16 v[106:109], v[178:181], v[186:189], v[106:109]
	v_mfma_f32_16x16x32_bf16 v[98:101], v[170:173], v[194:197], v[98:101]
	v_mfma_f32_16x16x32_bf16 v[90:93], v[178:181], v[194:197], v[90:93]
	v_mfma_f32_16x16x32_bf16 v[82:85], v[170:173], v[202:205], v[82:85]
	v_mfma_f32_16x16x32_bf16 v[74:77], v[178:181], v[202:205], v[74:77]
	v_mfma_f32_16x16x32_bf16 v[70:73], v[170:173], v[210:213], v[70:73]
	v_mfma_f32_16x16x32_bf16 v[66:69], v[178:181], v[210:213], v[66:69]
	v_mfma_f32_16x16x32_bf16 v[114:117], v[174:177], v[190:193], v[114:117]
	v_mfma_f32_16x16x32_bf16 v[106:109], v[182:185], v[190:193], v[106:109]
	v_mfma_f32_16x16x32_bf16 v[98:101], v[174:177], v[198:201], v[98:101]
	v_mfma_f32_16x16x32_bf16 v[90:93], v[182:185], v[198:201], v[90:93]
	v_mfma_f32_16x16x32_bf16 v[82:85], v[174:177], v[206:209], v[82:85]
	v_mfma_f32_16x16x32_bf16 v[74:77], v[182:185], v[206:209], v[74:77]
	v_mfma_f32_16x16x32_bf16 v[70:73], v[174:177], v[214:217], v[70:73]
	v_mfma_f32_16x16x32_bf16 v[66:69], v[182:185], v[214:217], v[66:69]
	s_setprio 0
	s_barrier
	s_add_i32 s62, s60, s54
	v_lshl_add_u64 v[218:219], s[44:45], 0, v[132:133]
	s_mov_b32 m0, s62
	ds_read_b128 v[186:189], v167 offset:16384
	ds_read_b128 v[190:193], v167 offset:17408
	ds_read_b128 v[194:197], v167 offset:18432
	ds_read_b128 v[198:201], v167 offset:19456
	ds_read_b128 v[202:205], v167 offset:20480
	ds_read_b128 v[206:209], v167 offset:21504
	ds_read_b128 v[210:213], v167 offset:22528
	ds_read_b128 v[214:217], v167 offset:23552
	global_load_lds_dwordx4 v[218:219], off
	s_add_i32 m0, s62, 0x2000
	s_add_u32 s62, s44, 0x20000
	v_lshl_add_u64 v[220:221], s[44:45], 0, v[136:137]
	s_addc_u32 s63, s45, 0
	s_add_i32 s64, s61, s54
	global_load_lds_dwordx4 v[220:221], off
	v_lshl_add_u64 v[222:223], s[62:63], 0, v[132:133]
	s_mov_b32 m0, s64
	v_lshl_add_u64 v[224:225], s[46:47], 0, v[134:135]
	global_load_lds_dwordx4 v[222:223], off
	v_lshl_add_u64 v[222:223], s[62:63], 0, v[136:137]
	s_add_i32 m0, s64, 0x2000
	s_nop 0
	global_load_lds_dwordx4 v[222:223], off
	v_lshl_add_u64 v[222:223], s[46:47], 0, v[130:131]
	s_mov_b32 m0, s39
	s_nop 0
	global_load_lds_dwordx4 v[222:223], off
	s_mov_b32 m0, s41
	s_nop 0
	global_load_lds_dwordx4 v[224:225], off
	s_waitcnt vmcnt(8)
	s_waitcnt lgkmcnt(0)
	s_waitcnt lgkmcnt(0)
	v_mfma_f32_16x16x32_bf16 v[62:65], v[142:145], v[186:189], v[62:65]
	v_mfma_f32_16x16x32_bf16 v[58:61], v[150:153], v[186:189], v[58:61]
	v_mfma_f32_16x16x32_bf16 v[54:57], v[142:145], v[194:197], v[54:57]
	v_mfma_f32_16x16x32_bf16 v[46:49], v[150:153], v[194:197], v[46:49]
	s_barrier
	s_setprio 1
	v_mfma_f32_16x16x32_bf16 v[38:41], v[142:145], v[202:205], v[38:41]
	v_mfma_f32_16x16x32_bf16 v[30:33], v[150:153], v[202:205], v[30:33]
	v_mfma_f32_16x16x32_bf16 v[22:25], v[142:145], v[210:213], v[22:25]
	v_mfma_f32_16x16x32_bf16 v[14:17], v[150:153], v[210:213], v[14:17]
	v_mfma_f32_16x16x32_bf16 v[62:65], v[146:149], v[190:193], v[62:65]
	v_mfma_f32_16x16x32_bf16 v[58:61], v[154:157], v[190:193], v[58:61]
	v_mfma_f32_16x16x32_bf16 v[54:57], v[146:149], v[198:201], v[54:57]
	v_mfma_f32_16x16x32_bf16 v[46:49], v[154:157], v[198:201], v[46:49]
	v_mfma_f32_16x16x32_bf16 v[38:41], v[146:149], v[206:209], v[38:41]
	v_mfma_f32_16x16x32_bf16 v[30:33], v[154:157], v[206:209], v[30:33]
	v_mfma_f32_16x16x32_bf16 v[22:25], v[146:149], v[214:217], v[22:25]
	v_mfma_f32_16x16x32_bf16 v[14:17], v[154:157], v[214:217], v[14:17]
	s_setprio 0
	s_setprio 1
	v_mfma_f32_16x16x32_bf16 v[50:53], v[170:173], v[186:189], v[50:53]
	v_mfma_f32_16x16x32_bf16 v[42:45], v[178:181], v[186:189], v[42:45]
	v_mfma_f32_16x16x32_bf16 v[34:37], v[170:173], v[194:197], v[34:37]
	v_mfma_f32_16x16x32_bf16 v[26:29], v[178:181], v[194:197], v[26:29]
	v_mfma_f32_16x16x32_bf16 v[18:21], v[170:173], v[202:205], v[18:21]
	v_mfma_f32_16x16x32_bf16 v[10:13], v[178:181], v[202:205], v[10:13]
	v_mfma_f32_16x16x32_bf16 v[6:9], v[170:173], v[210:213], v[6:9]
	v_mfma_f32_16x16x32_bf16 v[2:5], v[178:181], v[210:213], v[2:5]
	v_mfma_f32_16x16x32_bf16 v[50:53], v[174:177], v[190:193], v[50:53]
	v_mfma_f32_16x16x32_bf16 v[42:45], v[182:185], v[190:193], v[42:45]
	v_mfma_f32_16x16x32_bf16 v[34:37], v[174:177], v[198:201], v[34:37]
	v_mfma_f32_16x16x32_bf16 v[26:29], v[182:185], v[198:201], v[26:29]
	v_mfma_f32_16x16x32_bf16 v[18:21], v[174:177], v[206:209], v[18:21]
	v_mfma_f32_16x16x32_bf16 v[10:13], v[182:185], v[206:209], v[10:13]
	v_mfma_f32_16x16x32_bf16 v[6:9], v[174:177], v[214:217], v[6:9]
	v_mfma_f32_16x16x32_bf16 v[2:5], v[182:185], v[214:217], v[2:5]
	s_setprio 0
	s_barrier
	s_add_i32 s62, 0, 0x18000
	s_add_i32 s63, 0, 0x1c000
	v_add_u32_e32 v154, s62, v161
	v_add_u32_e32 v158, s63, v161
	ds_read_b128 v[142:145], v154
	ds_read_b128 v[146:149], v154 offset:1024
	ds_read_b128 v[150:153], v154 offset:2048
	ds_read_b128 v[154:157], v154 offset:3072
	ds_read_b128 v[170:173], v158
	ds_read_b128 v[174:177], v158 offset:1024
	ds_read_b128 v[178:181], v158 offset:2048
	ds_read_b128 v[182:185], v158 offset:3072
	s_add_u32 s46, s46, 0x20000
	s_addc_u32 s47, s47, 0
	s_mov_b32 m0, s55
	v_lshl_add_u64 v[226:227], s[46:47], 0, v[130:131]
	ds_read_b128 v[186:189], v167 offset:32768
	ds_read_b128 v[190:193], v167 offset:33792
	ds_read_b128 v[194:197], v167 offset:34816
	ds_read_b128 v[198:201], v167 offset:35840
	ds_read_b128 v[202:205], v167 offset:36864
	ds_read_b128 v[206:209], v167 offset:37888
	ds_read_b128 v[210:213], v167 offset:38912
	ds_read_b128 v[214:217], v167 offset:39936
	global_load_lds_dwordx4 v[226:227], off
	v_lshl_add_u64 v[226:227], s[46:47], 0, v[134:135]
	s_mov_b32 m0, s56
	s_nop 0
	global_load_lds_dwordx4 v[226:227], off
	s_waitcnt vmcnt(8)
	s_waitcnt lgkmcnt(0)
	s_waitcnt lgkmcnt(0)
	v_mfma_f32_16x16x32_bf16 v[126:129], v[142:145], v[186:189], v[126:129]
	v_mfma_f32_16x16x32_bf16 v[122:125], v[150:153], v[186:189], v[122:125]
	v_mfma_f32_16x16x32_bf16 v[118:121], v[142:145], v[194:197], v[118:121]
	v_mfma_f32_16x16x32_bf16 v[110:113], v[150:153], v[194:197], v[110:113]
	s_barrier
	s_setprio 1
	v_mfma_f32_16x16x32_bf16 v[102:105], v[142:145], v[202:205], v[102:105]
	v_mfma_f32_16x16x32_bf16 v[94:97], v[150:153], v[202:205], v[94:97]
	v_mfma_f32_16x16x32_bf16 v[86:89], v[142:145], v[210:213], v[86:89]
	v_mfma_f32_16x16x32_bf16 v[78:81], v[150:153], v[210:213], v[78:81]
	v_mfma_f32_16x16x32_bf16 v[126:129], v[146:149], v[190:193], v[126:129]
	v_mfma_f32_16x16x32_bf16 v[122:125], v[154:157], v[190:193], v[122:125]
	v_mfma_f32_16x16x32_bf16 v[118:121], v[146:149], v[198:201], v[118:121]
	v_mfma_f32_16x16x32_bf16 v[110:113], v[154:157], v[198:201], v[110:113]
	v_mfma_f32_16x16x32_bf16 v[102:105], v[146:149], v[206:209], v[102:105]
	v_mfma_f32_16x16x32_bf16 v[94:97], v[154:157], v[206:209], v[94:97]
	v_mfma_f32_16x16x32_bf16 v[86:89], v[146:149], v[214:217], v[86:89]
	v_mfma_f32_16x16x32_bf16 v[78:81], v[154:157], v[214:217], v[78:81]
	s_setprio 0
	s_setprio 1
	v_mfma_f32_16x16x32_bf16 v[114:117], v[170:173], v[186:189], v[114:117]
	v_mfma_f32_16x16x32_bf16 v[106:109], v[178:181], v[186:189], v[106:109]
	v_mfma_f32_16x16x32_bf16 v[98:101], v[170:173], v[194:197], v[98:101]
	v_mfma_f32_16x16x32_bf16 v[90:93], v[178:181], v[194:197], v[90:93]
	v_mfma_f32_16x16x32_bf16 v[82:85], v[170:173], v[202:205], v[82:85]
	v_mfma_f32_16x16x32_bf16 v[74:77], v[178:181], v[202:205], v[74:77]
	v_mfma_f32_16x16x32_bf16 v[70:73], v[170:173], v[210:213], v[70:73]
	v_mfma_f32_16x16x32_bf16 v[66:69], v[178:181], v[210:213], v[66:69]
	v_mfma_f32_16x16x32_bf16 v[114:117], v[174:177], v[190:193], v[114:117]
	v_mfma_f32_16x16x32_bf16 v[106:109], v[182:185], v[190:193], v[106:109]
	v_mfma_f32_16x16x32_bf16 v[98:101], v[174:177], v[198:201], v[98:101]
	v_mfma_f32_16x16x32_bf16 v[90:93], v[182:185], v[198:201], v[90:93]
	v_mfma_f32_16x16x32_bf16 v[82:85], v[174:177], v[206:209], v[82:85]
	v_mfma_f32_16x16x32_bf16 v[74:77], v[182:185], v[206:209], v[74:77]
	v_mfma_f32_16x16x32_bf16 v[70:73], v[174:177], v[214:217], v[70:73]
	v_mfma_f32_16x16x32_bf16 v[66:69], v[182:185], v[214:217], v[66:69]
	s_setprio 0
	s_barrier
	s_add_i32 s46, s62, s54
	v_lshl_add_u64 v[218:219], v[218:219], 0, s[22:23]
	s_mov_b32 m0, s46
	ds_read_b128 v[186:189], v167 offset:49152
	ds_read_b128 v[190:193], v167 offset:50176
	ds_read_b128 v[194:197], v167 offset:51200
	ds_read_b128 v[198:201], v167 offset:52224
	ds_read_b128 v[202:205], v167 offset:53248
	ds_read_b128 v[206:209], v167 offset:54272
	ds_read_b128 v[210:213], v167 offset:55296
	ds_read_b128 v[214:217], v167 offset:56320
	global_load_lds_dwordx4 v[218:219], off
	s_add_i32 m0, s46, 0x2000
	s_add_u32 s44, s44, 0x20080
	v_lshl_add_u64 v[218:219], v[220:221], 0, s[22:23]
	s_addc_u32 s45, s45, 0
	s_add_i32 s46, s63, s54
	global_load_lds_dwordx4 v[218:219], off
	v_lshl_add_u64 v[218:219], s[44:45], 0, v[132:133]
	s_mov_b32 m0, s46
	s_nop 0
	global_load_lds_dwordx4 v[218:219], off
	v_lshl_add_u64 v[218:219], s[44:45], 0, v[136:137]
	s_add_i32 m0, s46, 0x2000
	s_nop 0
	global_load_lds_dwordx4 v[218:219], off
	v_lshl_add_u64 v[218:219], v[222:223], 0, s[22:23]
	s_mov_b32 m0, s14
	s_nop 0
	global_load_lds_dwordx4 v[218:219], off
	v_lshl_add_u64 v[218:219], v[224:225], 0, s[22:23]
	s_mov_b32 m0, s15
	s_nop 0
	global_load_lds_dwordx4 v[218:219], off
	s_waitcnt vmcnt(8)
	s_waitcnt lgkmcnt(0)
	s_waitcnt lgkmcnt(0)
	v_mfma_f32_16x16x32_bf16 v[62:65], v[142:145], v[186:189], v[62:65]
	v_mfma_f32_16x16x32_bf16 v[58:61], v[150:153], v[186:189], v[58:61]
	v_mfma_f32_16x16x32_bf16 v[54:57], v[142:145], v[194:197], v[54:57]
	v_mfma_f32_16x16x32_bf16 v[46:49], v[150:153], v[194:197], v[46:49]
	s_barrier
	s_setprio 1
	v_mfma_f32_16x16x32_bf16 v[38:41], v[142:145], v[202:205], v[38:41]
	v_mfma_f32_16x16x32_bf16 v[30:33], v[150:153], v[202:205], v[30:33]
	v_mfma_f32_16x16x32_bf16 v[22:25], v[142:145], v[210:213], v[22:25]
	v_mfma_f32_16x16x32_bf16 v[14:17], v[150:153], v[210:213], v[14:17]
	v_mfma_f32_16x16x32_bf16 v[62:65], v[146:149], v[190:193], v[62:65]
	v_mfma_f32_16x16x32_bf16 v[58:61], v[154:157], v[190:193], v[58:61]
	v_mfma_f32_16x16x32_bf16 v[54:57], v[146:149], v[198:201], v[54:57]
	v_mfma_f32_16x16x32_bf16 v[46:49], v[154:157], v[198:201], v[46:49]
	v_mfma_f32_16x16x32_bf16 v[38:41], v[146:149], v[206:209], v[38:41]
	v_mfma_f32_16x16x32_bf16 v[30:33], v[154:157], v[206:209], v[30:33]
	v_mfma_f32_16x16x32_bf16 v[22:25], v[146:149], v[214:217], v[22:25]
	v_mfma_f32_16x16x32_bf16 v[14:17], v[154:157], v[214:217], v[14:17]
	s_setprio 0
	s_setprio 1
	v_mfma_f32_16x16x32_bf16 v[50:53], v[170:173], v[186:189], v[50:53]
	v_mfma_f32_16x16x32_bf16 v[42:45], v[178:181], v[186:189], v[42:45]
	v_mfma_f32_16x16x32_bf16 v[34:37], v[170:173], v[194:197], v[34:37]
	v_mfma_f32_16x16x32_bf16 v[26:29], v[178:181], v[194:197], v[26:29]
	v_mfma_f32_16x16x32_bf16 v[18:21], v[170:173], v[202:205], v[18:21]
	v_mfma_f32_16x16x32_bf16 v[10:13], v[178:181], v[202:205], v[10:13]
	v_mfma_f32_16x16x32_bf16 v[6:9], v[170:173], v[210:213], v[6:9]
	v_mfma_f32_16x16x32_bf16 v[2:5], v[178:181], v[210:213], v[2:5]
	v_mfma_f32_16x16x32_bf16 v[50:53], v[174:177], v[190:193], v[50:53]
	v_mfma_f32_16x16x32_bf16 v[42:45], v[182:185], v[190:193], v[42:45]
	v_mfma_f32_16x16x32_bf16 v[34:37], v[174:177], v[198:201], v[34:37]
	v_mfma_f32_16x16x32_bf16 v[26:29], v[182:185], v[198:201], v[26:29]
	v_mfma_f32_16x16x32_bf16 v[18:21], v[174:177], v[206:209], v[18:21]
	v_mfma_f32_16x16x32_bf16 v[10:13], v[182:185], v[206:209], v[10:13]
	v_mfma_f32_16x16x32_bf16 v[6:9], v[174:177], v[214:217], v[6:9]
	v_mfma_f32_16x16x32_bf16 v[2:5], v[182:185], v[214:217], v[2:5]
	s_setprio 0
	s_barrier
	s_add_i32 s29, s29, 2
	s_add_u32 s42, s42, 0x100
	s_addc_u32 s43, s43, 0
	s_add_u32 s19, s19, 0x100
	s_addc_u32 s27, s27, 0
	s_cmp_gt_u32 s29, 5
	s_cbranch_scc0 .LBB0_1264
	s_and_b64 vcc, exec, s[24:25]
	s_cbranch_vccz .LBB0_1267
	s_barrier

.LBB0_1336:
	ds_read_b128 v[154:157], v175
	ds_read_b128 v[158:161], v175 offset:1024
	ds_read_b128 v[164:167], v175 offset:2048
	ds_read_b128 v[168:171], v175 offset:3072
	ds_read_b128 v[180:183], v176
	ds_read_b128 v[184:187], v176 offset:1024
	ds_read_b128 v[188:191], v176 offset:2048
	ds_read_b128 v[192:195], v176 offset:3072
	s_add_u32 s20, s36, 0xfffe0080
	s_addc_u32 s21, s37, -1
	s_cmp_eq_u32 s19, 4
	s_cselect_b32 s41, s3, s21
	s_cselect_b32 s40, s14, s20
	s_cselect_b32 s39, s15, s18
	s_cselect_b32 s38, s16, s17
	v_lshl_add_u64 v[228:229], s[36:37], 0, v[144:145]
	s_add_i32 m0, s49, 0xc000
	ds_read_b128 v[196:199], v177
	ds_read_b128 v[200:203], v177 offset:1024
	ds_read_b128 v[204:207], v177 offset:2048
	ds_read_b128 v[208:211], v177 offset:3072
	ds_read_b128 v[212:215], v177 offset:4096
	ds_read_b128 v[216:219], v177 offset:5120
	ds_read_b128 v[220:223], v177 offset:6144
	ds_read_b128 v[224:227], v177 offset:7168
	global_load_lds_dwordx4 v[228:229], off
	v_lshl_add_u64 v[228:229], s[36:37], 0, v[146:147]
	s_add_i32 m0, s49, 0xe000
	s_nop 0
	global_load_lds_dwordx4 v[228:229], off
	s_waitcnt vmcnt(8)
	s_waitcnt lgkmcnt(0)
	s_waitcnt lgkmcnt(0)
	v_mfma_f32_16x16x32_bf16 v[126:129], v[154:157], v[196:199], v[126:129]
	v_mfma_f32_16x16x32_bf16 v[122:125], v[164:167], v[196:199], v[122:125]
	v_mfma_f32_16x16x32_bf16 v[118:121], v[154:157], v[204:207], v[118:121]
	v_mfma_f32_16x16x32_bf16 v[110:113], v[164:167], v[204:207], v[110:113]
	s_barrier
	s_setprio 1
	v_mfma_f32_16x16x32_bf16 v[102:105], v[154:157], v[212:215], v[102:105]
	v_mfma_f32_16x16x32_bf16 v[94:97], v[164:167], v[212:215], v[94:97]
	v_mfma_f32_16x16x32_bf16 v[86:89], v[154:157], v[220:223], v[86:89]
	v_mfma_f32_16x16x32_bf16 v[78:81], v[164:167], v[220:223], v[78:81]
	v_mfma_f32_16x16x32_bf16 v[126:129], v[158:161], v[200:203], v[126:129]
	v_mfma_f32_16x16x32_bf16 v[122:125], v[168:171], v[200:203], v[122:125]
	v_mfma_f32_16x16x32_bf16 v[118:121], v[158:161], v[208:211], v[118:121]
	v_mfma_f32_16x16x32_bf16 v[110:113], v[168:171], v[208:211], v[110:113]
	v_mfma_f32_16x16x32_bf16 v[102:105], v[158:161], v[216:219], v[102:105]
	v_mfma_f32_16x16x32_bf16 v[94:97], v[168:171], v[216:219], v[94:97]
	v_mfma_f32_16x16x32_bf16 v[86:89], v[158:161], v[224:227], v[86:89]
	v_mfma_f32_16x16x32_bf16 v[78:81], v[168:171], v[224:227], v[78:81]
	s_setprio 0
	s_setprio 1
	v_mfma_f32_16x16x32_bf16 v[114:117], v[180:183], v[196:199], v[114:117]
	v_mfma_f32_16x16x32_bf16 v[106:109], v[188:191], v[196:199], v[106:109]
	v_mfma_f32_16x16x32_bf16 v[98:101], v[180:183], v[204:207], v[98:101]
	v_mfma_f32_16x16x32_bf16 v[90:93], v[188:191], v[204:207], v[90:93]
	v_mfma_f32_16x16x32_bf16 v[82:85], v[180:183], v[212:215], v[82:85]
	v_mfma_f32_16x16x32_bf16 v[74:77], v[188:191], v[212:215], v[74:77]
	v_mfma_f32_16x16x32_bf16 v[70:73], v[180:183], v[220:223], v[70:73]
	v_mfma_f32_16x16x32_bf16 v[66:69], v[188:191], v[220:223], v[66:69]
	v_mfma_f32_16x16x32_bf16 v[114:117], v[184:187], v[200:203], v[114:117]
	v_mfma_f32_16x16x32_bf16 v[106:109], v[192:195], v[200:203], v[106:109]
	v_mfma_f32_16x16x32_bf16 v[98:101], v[184:187], v[208:211], v[98:101]
	v_mfma_f32_16x16x32_bf16 v[90:93], v[192:195], v[208:211], v[90:93]
	v_mfma_f32_16x16x32_bf16 v[82:85], v[184:187], v[216:219], v[82:85]
	v_mfma_f32_16x16x32_bf16 v[74:77], v[192:195], v[216:219], v[74:77]
	v_mfma_f32_16x16x32_bf16 v[70:73], v[184:187], v[224:227], v[70:73]
	v_mfma_f32_16x16x32_bf16 v[66:69], v[192:195], v[224:227], v[66:69]
	s_setprio 0
	s_barrier
	s_add_i32 s20, s57, s46
	v_lshl_add_u64 v[228:229], s[38:39], 0, v[134:135]
	s_mov_b32 m0, s20
	ds_read_b128 v[196:199], v177 offset:16384
	ds_read_b128 v[200:203], v177 offset:17408
	ds_read_b128 v[204:207], v177 offset:18432
	ds_read_b128 v[208:211], v177 offset:19456
	ds_read_b128 v[212:215], v177 offset:20480
	ds_read_b128 v[216:219], v177 offset:21504
	ds_read_b128 v[220:223], v177 offset:22528
	ds_read_b128 v[224:227], v177 offset:23552
	global_load_lds_dwordx4 v[228:229], off
	s_add_i32 m0, s20, 0x2000
	s_add_u32 s20, s38, 0x20000
	v_lshl_add_u64 v[230:231], s[38:39], 0, v[130:131]
	s_addc_u32 s21, s39, 0
	s_add_i32 s27, s60, s46
	global_load_lds_dwordx4 v[230:231], off
	v_lshl_add_u64 v[232:233], s[20:21], 0, v[134:135]
	s_mov_b32 m0, s27
	v_lshl_add_u64 v[234:235], s[40:41], 0, v[132:133]
	global_load_lds_dwordx4 v[232:233], off
	v_lshl_add_u64 v[232:233], s[20:21], 0, v[130:131]
	s_add_i32 m0, s27, 0x2000
	s_nop 0
	global_load_lds_dwordx4 v[232:233], off
	v_lshl_add_u64 v[232:233], s[40:41], 0, v[136:137]
	s_mov_b32 m0, s49
	s_nop 0
	global_load_lds_dwordx4 v[232:233], off
	s_mov_b32 m0, s50
	s_nop 0
	global_load_lds_dwordx4 v[234:235], off
	s_waitcnt vmcnt(8)
	s_waitcnt lgkmcnt(0)
	s_waitcnt lgkmcnt(0)
	v_mfma_f32_16x16x32_bf16 v[62:65], v[154:157], v[196:199], v[62:65]
	v_mfma_f32_16x16x32_bf16 v[58:61], v[164:167], v[196:199], v[58:61]
	v_mfma_f32_16x16x32_bf16 v[54:57], v[154:157], v[204:207], v[54:57]
	v_mfma_f32_16x16x32_bf16 v[46:49], v[164:167], v[204:207], v[46:49]
	s_barrier
	s_setprio 1
	v_mfma_f32_16x16x32_bf16 v[38:41], v[154:157], v[212:215], v[38:41]
	v_mfma_f32_16x16x32_bf16 v[30:33], v[164:167], v[212:215], v[30:33]
	v_mfma_f32_16x16x32_bf16 v[22:25], v[154:157], v[220:223], v[22:25]
	v_mfma_f32_16x16x32_bf16 v[14:17], v[164:167], v[220:223], v[14:17]
	v_mfma_f32_16x16x32_bf16 v[62:65], v[158:161], v[200:203], v[62:65]
	v_mfma_f32_16x16x32_bf16 v[58:61], v[168:171], v[200:203], v[58:61]
	v_mfma_f32_16x16x32_bf16 v[54:57], v[158:161], v[208:211], v[54:57]
	v_mfma_f32_16x16x32_bf16 v[46:49], v[168:171], v[208:211], v[46:49]
	v_mfma_f32_16x16x32_bf16 v[38:41], v[158:161], v[216:219], v[38:41]
	v_mfma_f32_16x16x32_bf16 v[30:33], v[168:171], v[216:219], v[30:33]
	v_mfma_f32_16x16x32_bf16 v[22:25], v[158:161], v[224:227], v[22:25]
	v_mfma_f32_16x16x32_bf16 v[14:17], v[168:171], v[224:227], v[14:17]
	s_setprio 0
	s_setprio 1
	v_mfma_f32_16x16x32_bf16 v[50:53], v[180:183], v[196:199], v[50:53]
	v_mfma_f32_16x16x32_bf16 v[42:45], v[188:191], v[196:199], v[42:45]
	v_mfma_f32_16x16x32_bf16 v[34:37], v[180:183], v[204:207], v[34:37]
	v_mfma_f32_16x16x32_bf16 v[26:29], v[188:191], v[204:207], v[26:29]
	v_mfma_f32_16x16x32_bf16 v[18:21], v[180:183], v[212:215], v[18:21]
	v_mfma_f32_16x16x32_bf16 v[10:13], v[188:191], v[212:215], v[10:13]
	v_mfma_f32_16x16x32_bf16 v[6:9], v[180:183], v[220:223], v[6:9]
	v_mfma_f32_16x16x32_bf16 v[2:5], v[188:191], v[220:223], v[2:5]
	v_mfma_f32_16x16x32_bf16 v[50:53], v[184:187], v[200:203], v[50:53]
	v_mfma_f32_16x16x32_bf16 v[42:45], v[192:195], v[200:203], v[42:45]
	v_mfma_f32_16x16x32_bf16 v[34:37], v[184:187], v[208:211], v[34:37]
	v_mfma_f32_16x16x32_bf16 v[26:29], v[192:195], v[208:211], v[26:29]
	v_mfma_f32_16x16x32_bf16 v[18:21], v[184:187], v[216:219], v[18:21]
	v_mfma_f32_16x16x32_bf16 v[10:13], v[192:195], v[216:219], v[10:13]
	v_mfma_f32_16x16x32_bf16 v[6:9], v[184:187], v[224:227], v[6:9]
	v_mfma_f32_16x16x32_bf16 v[2:5], v[192:195], v[224:227], v[2:5]
	s_setprio 0
	s_barrier
	s_add_i32 s27, 0, 0x18000
	v_add_u32_e32 v153, s27, v173
	s_add_i32 s29, 0, 0x1c000
	ds_read_b128 v[154:157], v153
	ds_read_b128 v[158:161], v153 offset:1024
	ds_read_b128 v[164:167], v153 offset:2048
	ds_read_b128 v[168:171], v153 offset:3072
	v_add_u32_e32 v153, s29, v173
	ds_read_b128 v[180:183], v153
	ds_read_b128 v[184:187], v153 offset:1024
	ds_read_b128 v[188:191], v153 offset:2048
	ds_read_b128 v[192:195], v153 offset:3072
	s_add_u32 s20, s40, 0x20000
	s_addc_u32 s21, s41, 0
	s_mov_b32 m0, s51
	v_lshl_add_u64 v[236:237], s[20:21], 0, v[136:137]
	ds_read_b128 v[196:199], v177 offset:32768
	ds_read_b128 v[200:203], v177 offset:33792
	ds_read_b128 v[204:207], v177 offset:34816
	ds_read_b128 v[208:211], v177 offset:35840
	ds_read_b128 v[212:215], v177 offset:36864
	ds_read_b128 v[216:219], v177 offset:37888
	ds_read_b128 v[220:223], v177 offset:38912
	ds_read_b128 v[224:227], v177 offset:39936
	global_load_lds_dwordx4 v[236:237], off
	v_lshl_add_u64 v[236:237], s[20:21], 0, v[132:133]
	s_mov_b32 m0, s52
	s_nop 0
	global_load_lds_dwordx4 v[236:237], off
	s_waitcnt vmcnt(8)
	s_waitcnt lgkmcnt(0)
	s_waitcnt lgkmcnt(0)
	v_mfma_f32_16x16x32_bf16 v[126:129], v[154:157], v[196:199], v[126:129]
	v_mfma_f32_16x16x32_bf16 v[122:125], v[164:167], v[196:199], v[122:125]
	v_mfma_f32_16x16x32_bf16 v[118:121], v[154:157], v[204:207], v[118:121]
	v_mfma_f32_16x16x32_bf16 v[110:113], v[164:167], v[204:207], v[110:113]
	s_barrier
	s_setprio 1
	v_mfma_f32_16x16x32_bf16 v[102:105], v[154:157], v[212:215], v[102:105]
	v_mfma_f32_16x16x32_bf16 v[94:97], v[164:167], v[212:215], v[94:97]
	v_mfma_f32_16x16x32_bf16 v[86:89], v[154:157], v[220:223], v[86:89]
	v_mfma_f32_16x16x32_bf16 v[78:81], v[164:167], v[220:223], v[78:81]
	v_mfma_f32_16x16x32_bf16 v[126:129], v[158:161], v[200:203], v[126:129]
	v_mfma_f32_16x16x32_bf16 v[122:125], v[168:171], v[200:203], v[122:125]
	v_mfma_f32_16x16x32_bf16 v[118:121], v[158:161], v[208:211], v[118:121]
	v_mfma_f32_16x16x32_bf16 v[110:113], v[168:171], v[208:211], v[110:113]
	v_mfma_f32_16x16x32_bf16 v[102:105], v[158:161], v[216:219], v[102:105]
	v_mfma_f32_16x16x32_bf16 v[94:97], v[168:171], v[216:219], v[94:97]
	v_mfma_f32_16x16x32_bf16 v[86:89], v[158:161], v[224:227], v[86:89]
	v_mfma_f32_16x16x32_bf16 v[78:81], v[168:171], v[224:227], v[78:81]
	s_setprio 0
	s_setprio 1
	v_mfma_f32_16x16x32_bf16 v[114:117], v[180:183], v[196:199], v[114:117]
	v_mfma_f32_16x16x32_bf16 v[106:109], v[188:191], v[196:199], v[106:109]
	v_mfma_f32_16x16x32_bf16 v[98:101], v[180:183], v[204:207], v[98:101]
	v_mfma_f32_16x16x32_bf16 v[90:93], v[188:191], v[204:207], v[90:93]
	v_mfma_f32_16x16x32_bf16 v[82:85], v[180:183], v[212:215], v[82:85]
	v_mfma_f32_16x16x32_bf16 v[74:77], v[188:191], v[212:215], v[74:77]
	v_mfma_f32_16x16x32_bf16 v[70:73], v[180:183], v[220:223], v[70:73]
	v_mfma_f32_16x16x32_bf16 v[66:69], v[188:191], v[220:223], v[66:69]
	v_mfma_f32_16x16x32_bf16 v[114:117], v[184:187], v[200:203], v[114:117]
	v_mfma_f32_16x16x32_bf16 v[106:109], v[192:195], v[200:203], v[106:109]
	v_mfma_f32_16x16x32_bf16 v[98:101], v[184:187], v[208:211], v[98:101]
	v_mfma_f32_16x16x32_bf16 v[90:93], v[192:195], v[208:211], v[90:93]
	v_mfma_f32_16x16x32_bf16 v[82:85], v[184:187], v[216:219], v[82:85]
	v_mfma_f32_16x16x32_bf16 v[74:77], v[192:195], v[216:219], v[74:77]
	v_mfma_f32_16x16x32_bf16 v[70:73], v[184:187], v[224:227], v[70:73]
	v_mfma_f32_16x16x32_bf16 v[66:69], v[192:195], v[224:227], v[66:69]
	s_setprio 0
	s_barrier
	s_add_i32 s20, s27, s46
	v_lshl_add_u64 v[228:229], v[228:229], 0, s[22:23]
	s_mov_b32 m0, s20
	ds_read_b128 v[196:199], v177 offset:49152
	ds_read_b128 v[200:203], v177 offset:50176
	ds_read_b128 v[204:207], v177 offset:51200
	ds_read_b128 v[208:211], v177 offset:52224
	ds_read_b128 v[212:215], v177 offset:53248
	ds_read_b128 v[216:219], v177 offset:54272
	ds_read_b128 v[220:223], v177 offset:55296
	ds_read_b128 v[224:227], v177 offset:56320
	global_load_lds_dwordx4 v[228:229], off
	s_add_i32 m0, s20, 0x2000
	s_add_u32 s20, s38, 0x20080
	v_lshl_add_u64 v[228:229], v[230:231], 0, s[22:23]
	s_addc_u32 s21, s39, 0
	s_add_i32 s27, s29, s46
	global_load_lds_dwordx4 v[228:229], off
	v_lshl_add_u64 v[228:229], s[20:21], 0, v[134:135]
	s_mov_b32 m0, s27
	s_nop 0
	global_load_lds_dwordx4 v[228:229], off
	v_lshl_add_u64 v[228:229], s[20:21], 0, v[130:131]
	s_add_i32 m0, s27, 0x2000
	s_nop 0
	global_load_lds_dwordx4 v[228:229], off
	v_lshl_add_u64 v[228:229], v[232:233], 0, s[22:23]
	s_mov_b32 m0, s53
	s_nop 0
	global_load_lds_dwordx4 v[228:229], off
	v_lshl_add_u64 v[228:229], v[234:235], 0, s[22:23]
	s_mov_b32 m0, s54
	s_nop 0
	global_load_lds_dwordx4 v[228:229], off
	s_waitcnt vmcnt(8)
	s_waitcnt lgkmcnt(0)
	s_waitcnt lgkmcnt(0)
	v_mfma_f32_16x16x32_bf16 v[62:65], v[154:157], v[196:199], v[62:65]
	v_mfma_f32_16x16x32_bf16 v[58:61], v[164:167], v[196:199], v[58:61]
	v_mfma_f32_16x16x32_bf16 v[54:57], v[154:157], v[204:207], v[54:57]
	v_mfma_f32_16x16x32_bf16 v[46:49], v[164:167], v[204:207], v[46:49]
	s_barrier
	s_setprio 1
	v_mfma_f32_16x16x32_bf16 v[38:41], v[154:157], v[212:215], v[38:41]
	v_mfma_f32_16x16x32_bf16 v[30:33], v[164:167], v[212:215], v[30:33]
	v_mfma_f32_16x16x32_bf16 v[22:25], v[154:157], v[220:223], v[22:25]
	v_mfma_f32_16x16x32_bf16 v[14:17], v[164:167], v[220:223], v[14:17]
	v_mfma_f32_16x16x32_bf16 v[62:65], v[158:161], v[200:203], v[62:65]
	v_mfma_f32_16x16x32_bf16 v[58:61], v[168:171], v[200:203], v[58:61]
	v_mfma_f32_16x16x32_bf16 v[54:57], v[158:161], v[208:211], v[54:57]
	v_mfma_f32_16x16x32_bf16 v[46:49], v[168:171], v[208:211], v[46:49]
	v_mfma_f32_16x16x32_bf16 v[38:41], v[158:161], v[216:219], v[38:41]
	v_mfma_f32_16x16x32_bf16 v[30:33], v[168:171], v[216:219], v[30:33]
	v_mfma_f32_16x16x32_bf16 v[22:25], v[158:161], v[224:227], v[22:25]
	v_mfma_f32_16x16x32_bf16 v[14:17], v[168:171], v[224:227], v[14:17]
	s_setprio 0
	s_setprio 1
	v_mfma_f32_16x16x32_bf16 v[50:53], v[180:183], v[196:199], v[50:53]
	v_mfma_f32_16x16x32_bf16 v[42:45], v[188:191], v[196:199], v[42:45]
	v_mfma_f32_16x16x32_bf16 v[34:37], v[180:183], v[204:207], v[34:37]
	v_mfma_f32_16x16x32_bf16 v[26:29], v[188:191], v[204:207], v[26:29]
	v_mfma_f32_16x16x32_bf16 v[18:21], v[180:183], v[212:215], v[18:21]
	v_mfma_f32_16x16x32_bf16 v[10:13], v[188:191], v[212:215], v[10:13]
	v_mfma_f32_16x16x32_bf16 v[6:9], v[180:183], v[220:223], v[6:9]
	v_mfma_f32_16x16x32_bf16 v[2:5], v[188:191], v[220:223], v[2:5]
	v_mfma_f32_16x16x32_bf16 v[50:53], v[184:187], v[200:203], v[50:53]
	v_mfma_f32_16x16x32_bf16 v[42:45], v[192:195], v[200:203], v[42:45]
	v_mfma_f32_16x16x32_bf16 v[34:37], v[184:187], v[208:211], v[34:37]
	v_mfma_f32_16x16x32_bf16 v[26:29], v[192:195], v[208:211], v[26:29]
	v_mfma_f32_16x16x32_bf16 v[18:21], v[184:187], v[216:219], v[18:21]
	v_mfma_f32_16x16x32_bf16 v[10:13], v[192:195], v[216:219], v[10:13]
	v_mfma_f32_16x16x32_bf16 v[6:9], v[184:187], v[224:227], v[6:9]
	v_mfma_f32_16x16x32_bf16 v[2:5], v[192:195], v[224:227], v[2:5]
	s_setprio 0
	s_barrier
	s_add_i32 s19, s19, 2
	s_add_u32 s36, s36, 0x100
	s_addc_u32 s37, s37, 0
	s_add_u32 s17, s17, 0x100
	s_addc_u32 s18, s18, 0
	s_cmp_gt_u32 s19, 5
	s_cbranch_scc0 .LBB0_1336
	s_and_b64 vcc, exec, s[24:25]
	s_cbranch_vccz .LBB0_1339
	s_barrier

.LBB0_1497:
	ds_read_b128 v[134:137], v214
	ds_read_b128 v[138:141], v214 offset:1024
	ds_read_b128 v[142:145], v214 offset:2048
	ds_read_b128 v[178:181], v214 offset:3072
	ds_read_b128 v[182:185], v215
	ds_read_b128 v[186:189], v215 offset:1024
	ds_read_b128 v[190:193], v215 offset:2048
	ds_read_b128 v[194:197], v215 offset:3072
	s_add_u32 s40, s38, 0x100
	s_addc_u32 s41, s39, 0
	s_add_u32 s0, s15, s38
	s_addc_u32 s1, s16, s39
	s_cmp_eq_u32 s17, 28
	s_cselect_b32 s45, s3, s1
	s_cselect_b32 s1, 0, s40
	s_cselect_b32 s44, s14, s0
	s_cselect_b32 s0, 0, s41
	s_add_u32 s42, s10, s1
	s_addc_u32 s43, s11, s0
	s_mov_b32 m0, s64
	v_lshl_add_u64 v[244:245], v[130:131], 0, s[38:39]
	ds_read_b128 v[198:201], v216
	ds_read_b128 v[202:205], v216 offset:1024
	ds_read_b128 v[206:209], v216 offset:2048
	ds_read_b128 v[224:227], v216 offset:3072
	ds_read_b128 v[228:231], v216 offset:4096
	ds_read_b128 v[232:235], v216 offset:5120
	ds_read_b128 v[236:239], v216 offset:6144
	ds_read_b128 v[240:243], v216 offset:7168
	global_load_lds_dwordx4 v[244:245], off
	v_lshl_add_u64 v[244:245], v[132:133], 0, s[38:39]
	s_mov_b32 m0, s65
	s_nop 0
	global_load_lds_dwordx4 v[244:245], off
	s_waitcnt vmcnt(8)
	s_waitcnt lgkmcnt(0)
	s_waitcnt lgkmcnt(0)
	v_mfma_f32_16x16x32_bf16 v[82:85], v[134:137], v[198:201], v[82:85]
	v_mfma_f32_16x16x32_bf16 v[78:81], v[142:145], v[198:201], v[78:81]
	v_mfma_f32_16x16x32_bf16 v[110:113], v[134:137], v[206:209], v[110:113]
	v_mfma_f32_16x16x32_bf16 v[106:109], v[142:145], v[206:209], v[106:109]
	s_barrier
	s_setprio 1
	v_mfma_f32_16x16x32_bf16 v[118:121], v[134:137], v[228:231], v[118:121]
	v_mfma_f32_16x16x32_bf16 v[114:117], v[142:145], v[228:231], v[114:117]
	v_mfma_f32_16x16x32_bf16 v[126:129], v[134:137], v[236:239], v[126:129]
	v_mfma_f32_16x16x32_bf16 v[122:125], v[142:145], v[236:239], v[122:125]
	v_mfma_f32_16x16x32_bf16 v[82:85], v[138:141], v[202:205], v[82:85]
	v_mfma_f32_16x16x32_bf16 v[78:81], v[178:181], v[202:205], v[78:81]
	v_mfma_f32_16x16x32_bf16 v[110:113], v[138:141], v[224:227], v[110:113]
	v_mfma_f32_16x16x32_bf16 v[106:109], v[178:181], v[224:227], v[106:109]
	v_mfma_f32_16x16x32_bf16 v[118:121], v[138:141], v[232:235], v[118:121]
	v_mfma_f32_16x16x32_bf16 v[114:117], v[178:181], v[232:235], v[114:117]
	v_mfma_f32_16x16x32_bf16 v[126:129], v[138:141], v[240:243], v[126:129]
	v_mfma_f32_16x16x32_bf16 v[122:125], v[178:181], v[240:243], v[122:125]
	s_setprio 0
	s_setprio 1
	v_mfma_f32_16x16x32_bf16 v[22:25], v[182:185], v[198:201], v[22:25]
	v_mfma_f32_16x16x32_bf16 v[26:29], v[190:193], v[198:201], v[26:29]
	v_mfma_f32_16x16x32_bf16 v[42:45], v[182:185], v[206:209], v[42:45]
	v_mfma_f32_16x16x32_bf16 v[46:49], v[190:193], v[206:209], v[46:49]
	v_mfma_f32_16x16x32_bf16 v[62:65], v[182:185], v[228:231], v[62:65]
	v_mfma_f32_16x16x32_bf16 v[70:73], v[190:193], v[228:231], v[70:73]
	v_mfma_f32_16x16x32_bf16 v[90:93], v[182:185], v[236:239], v[90:93]
	v_mfma_f32_16x16x32_bf16 v[94:97], v[190:193], v[236:239], v[94:97]
	v_mfma_f32_16x16x32_bf16 v[22:25], v[186:189], v[202:205], v[22:25]
	v_mfma_f32_16x16x32_bf16 v[26:29], v[194:197], v[202:205], v[26:29]
	v_mfma_f32_16x16x32_bf16 v[42:45], v[186:189], v[224:227], v[42:45]
	v_mfma_f32_16x16x32_bf16 v[46:49], v[194:197], v[224:227], v[46:49]
	v_mfma_f32_16x16x32_bf16 v[62:65], v[186:189], v[232:235], v[62:65]
	v_mfma_f32_16x16x32_bf16 v[70:73], v[194:197], v[232:235], v[70:73]
	v_mfma_f32_16x16x32_bf16 v[90:93], v[186:189], v[240:243], v[90:93]
	v_mfma_f32_16x16x32_bf16 v[94:97], v[194:197], v[240:243], v[94:97]
	s_setprio 0
	s_barrier
	s_mov_b32 m0, s66
	v_lshl_add_u64 v[244:245], s[42:43], 0, v[150:151]
	s_add_u32 s18, s42, 0x80000
	ds_read_b128 v[198:201], v216 offset:16384
	ds_read_b128 v[202:205], v216 offset:17408
	ds_read_b128 v[206:209], v216 offset:18432
	ds_read_b128 v[224:227], v216 offset:19456
	ds_read_b128 v[228:231], v216 offset:20480
	ds_read_b128 v[232:235], v216 offset:21504
	ds_read_b128 v[236:239], v216 offset:22528
	ds_read_b128 v[240:243], v216 offset:23552
	global_load_lds_dwordx4 v[244:245], off
	v_lshl_add_u64 v[246:247], s[42:43], 0, v[146:147]
	s_mov_b32 m0, s67
	s_addc_u32 s19, s43, 0
	global_load_lds_dwordx4 v[246:247], off
	v_lshl_add_u64 v[248:249], s[18:19], 0, v[150:151]
	s_mov_b32 m0, s68
	v_lshl_add_u64 v[250:251], s[44:45], 0, v[148:149]
	global_load_lds_dwordx4 v[248:249], off
	v_lshl_add_u64 v[248:249], s[18:19], 0, v[146:147]
	s_mov_b32 m0, s69
	s_nop 0
	global_load_lds_dwordx4 v[248:249], off
	v_lshl_add_u64 v[248:249], s[44:45], 0, v[152:153]
	s_mov_b32 m0, s9
	s_nop 0
	global_load_lds_dwordx4 v[248:249], off
	s_mov_b32 m0, s55
	s_nop 0
	global_load_lds_dwordx4 v[250:251], off
	s_waitcnt vmcnt(8)
	s_waitcnt lgkmcnt(0)
	s_waitcnt lgkmcnt(0)
	v_mfma_f32_16x16x32_bf16 v[102:105], v[134:137], v[198:201], v[102:105]
	v_mfma_f32_16x16x32_bf16 v[98:101], v[142:145], v[198:201], v[98:101]
	v_mfma_f32_16x16x32_bf16 v[66:69], v[134:137], v[206:209], v[66:69]
	v_mfma_f32_16x16x32_bf16 v[58:61], v[142:145], v[206:209], v[58:61]
	s_barrier
	s_setprio 1
	v_mfma_f32_16x16x32_bf16 v[38:41], v[134:137], v[228:231], v[38:41]
	v_mfma_f32_16x16x32_bf16 v[34:37], v[142:145], v[228:231], v[34:37]
	v_mfma_f32_16x16x32_bf16 v[14:17], v[134:137], v[236:239], v[14:17]
	v_mfma_f32_16x16x32_bf16 v[10:13], v[142:145], v[236:239], v[10:13]
	v_mfma_f32_16x16x32_bf16 v[102:105], v[138:141], v[202:205], v[102:105]
	v_mfma_f32_16x16x32_bf16 v[98:101], v[178:181], v[202:205], v[98:101]
	v_mfma_f32_16x16x32_bf16 v[66:69], v[138:141], v[224:227], v[66:69]
	v_mfma_f32_16x16x32_bf16 v[58:61], v[178:181], v[224:227], v[58:61]
	v_mfma_f32_16x16x32_bf16 v[38:41], v[138:141], v[232:235], v[38:41]
	v_mfma_f32_16x16x32_bf16 v[34:37], v[178:181], v[232:235], v[34:37]
	v_mfma_f32_16x16x32_bf16 v[14:17], v[138:141], v[240:243], v[14:17]
	v_mfma_f32_16x16x32_bf16 v[10:13], v[178:181], v[240:243], v[10:13]
	s_setprio 0
	s_setprio 1
	v_mfma_f32_16x16x32_bf16 v[86:89], v[182:185], v[198:201], v[86:89]
	v_mfma_f32_16x16x32_bf16 v[74:77], v[190:193], v[198:201], v[74:77]
	v_mfma_f32_16x16x32_bf16 v[54:57], v[182:185], v[206:209], v[54:57]
	v_mfma_f32_16x16x32_bf16 v[50:53], v[190:193], v[206:209], v[50:53]
	v_mfma_f32_16x16x32_bf16 v[30:33], v[182:185], v[228:231], v[30:33]
	v_mfma_f32_16x16x32_bf16 v[18:21], v[190:193], v[228:231], v[18:21]
	v_mfma_f32_16x16x32_bf16 v[6:9], v[182:185], v[236:239], v[6:9]
	v_mfma_f32_16x16x32_bf16 v[2:5], v[190:193], v[236:239], v[2:5]
	v_mfma_f32_16x16x32_bf16 v[86:89], v[186:189], v[202:205], v[86:89]
	v_mfma_f32_16x16x32_bf16 v[74:77], v[194:197], v[202:205], v[74:77]
	v_mfma_f32_16x16x32_bf16 v[54:57], v[186:189], v[224:227], v[54:57]
	v_mfma_f32_16x16x32_bf16 v[50:53], v[194:197], v[224:227], v[50:53]
	v_mfma_f32_16x16x32_bf16 v[30:33], v[186:189], v[232:235], v[30:33]
	v_mfma_f32_16x16x32_bf16 v[18:21], v[194:197], v[232:235], v[18:21]
	v_mfma_f32_16x16x32_bf16 v[6:9], v[186:189], v[240:243], v[6:9]
	v_mfma_f32_16x16x32_bf16 v[2:5], v[194:197], v[240:243], v[2:5]
	s_setprio 0
	s_barrier
	s_add_i32 s0, 0, 0x1c000
	v_add_u32_e32 v194, s0, v212
	ds_read_b128 v[134:137], v220
	ds_read_b128 v[138:141], v220 offset:1024
	ds_read_b128 v[142:145], v220 offset:2048
	ds_read_b128 v[178:181], v220 offset:3072
	ds_read_b128 v[182:185], v194
	ds_read_b128 v[186:189], v194 offset:1024
	ds_read_b128 v[190:193], v194 offset:2048
	ds_read_b128 v[194:197], v194 offset:3072
	s_add_u32 s18, s44, 0x80000
	s_addc_u32 s19, s45, 0
	s_mov_b32 m0, s56
	v_lshl_add_u64 v[252:253], s[18:19], 0, v[152:153]
	ds_read_b128 v[198:201], v216 offset:32768
	ds_read_b128 v[202:205], v216 offset:33792
	ds_read_b128 v[206:209], v216 offset:34816
	ds_read_b128 v[224:227], v216 offset:35840
	ds_read_b128 v[228:231], v216 offset:36864
	ds_read_b128 v[232:235], v216 offset:37888
	ds_read_b128 v[236:239], v216 offset:38912
	ds_read_b128 v[240:243], v216 offset:39936
	global_load_lds_dwordx4 v[252:253], off
	v_lshl_add_u64 v[252:253], s[18:19], 0, v[148:149]
	s_mov_b32 m0, s57
	s_nop 0
	global_load_lds_dwordx4 v[252:253], off
	s_waitcnt vmcnt(8)
	s_waitcnt lgkmcnt(0)
	s_waitcnt lgkmcnt(0)
	v_mfma_f32_16x16x32_bf16 v[82:85], v[134:137], v[198:201], v[82:85]
	v_mfma_f32_16x16x32_bf16 v[78:81], v[142:145], v[198:201], v[78:81]
	v_mfma_f32_16x16x32_bf16 v[110:113], v[134:137], v[206:209], v[110:113]
	v_mfma_f32_16x16x32_bf16 v[106:109], v[142:145], v[206:209], v[106:109]
	s_barrier
	s_setprio 1
	v_mfma_f32_16x16x32_bf16 v[118:121], v[134:137], v[228:231], v[118:121]
	v_mfma_f32_16x16x32_bf16 v[114:117], v[142:145], v[228:231], v[114:117]
	v_mfma_f32_16x16x32_bf16 v[126:129], v[134:137], v[236:239], v[126:129]
	v_mfma_f32_16x16x32_bf16 v[122:125], v[142:145], v[236:239], v[122:125]
	v_mfma_f32_16x16x32_bf16 v[82:85], v[138:141], v[202:205], v[82:85]
	v_mfma_f32_16x16x32_bf16 v[78:81], v[178:181], v[202:205], v[78:81]
	v_mfma_f32_16x16x32_bf16 v[110:113], v[138:141], v[224:227], v[110:113]
	v_mfma_f32_16x16x32_bf16 v[106:109], v[178:181], v[224:227], v[106:109]
	v_mfma_f32_16x16x32_bf16 v[118:121], v[138:141], v[232:235], v[118:121]
	v_mfma_f32_16x16x32_bf16 v[114:117], v[178:181], v[232:235], v[114:117]
	v_mfma_f32_16x16x32_bf16 v[126:129], v[138:141], v[240:243], v[126:129]
	v_mfma_f32_16x16x32_bf16 v[122:125], v[178:181], v[240:243], v[122:125]
	s_setprio 0
	s_setprio 1
	v_mfma_f32_16x16x32_bf16 v[22:25], v[182:185], v[198:201], v[22:25]
	v_mfma_f32_16x16x32_bf16 v[26:29], v[190:193], v[198:201], v[26:29]
	v_mfma_f32_16x16x32_bf16 v[42:45], v[182:185], v[206:209], v[42:45]
	v_mfma_f32_16x16x32_bf16 v[46:49], v[190:193], v[206:209], v[46:49]
	v_mfma_f32_16x16x32_bf16 v[62:65], v[182:185], v[228:231], v[62:65]
	v_mfma_f32_16x16x32_bf16 v[70:73], v[190:193], v[228:231], v[70:73]
	v_mfma_f32_16x16x32_bf16 v[90:93], v[182:185], v[236:239], v[90:93]
	v_mfma_f32_16x16x32_bf16 v[94:97], v[190:193], v[236:239], v[94:97]
	v_mfma_f32_16x16x32_bf16 v[22:25], v[186:189], v[202:205], v[22:25]
	v_mfma_f32_16x16x32_bf16 v[26:29], v[194:197], v[202:205], v[26:29]
	v_mfma_f32_16x16x32_bf16 v[42:45], v[186:189], v[224:227], v[42:45]
	v_mfma_f32_16x16x32_bf16 v[46:49], v[194:197], v[224:227], v[46:49]
	v_mfma_f32_16x16x32_bf16 v[62:65], v[186:189], v[232:235], v[62:65]
	v_mfma_f32_16x16x32_bf16 v[70:73], v[194:197], v[232:235], v[70:73]
	v_mfma_f32_16x16x32_bf16 v[90:93], v[186:189], v[240:243], v[90:93]
	v_mfma_f32_16x16x32_bf16 v[94:97], v[194:197], v[240:243], v[94:97]
	s_setprio 0
	s_barrier
	s_add_i32 s1, s72, s54
	v_lshl_add_u64 v[244:245], v[244:245], 0, s[26:27]
	s_mov_b32 m0, s1
	ds_read_b128 v[198:201], v216 offset:49152
	ds_read_b128 v[202:205], v216 offset:50176
	ds_read_b128 v[206:209], v216 offset:51200
	ds_read_b128 v[224:227], v216 offset:52224
	ds_read_b128 v[228:231], v216 offset:53248
	ds_read_b128 v[232:235], v216 offset:54272
	ds_read_b128 v[236:239], v216 offset:55296
	ds_read_b128 v[240:243], v216 offset:56320
	global_load_lds_dwordx4 v[244:245], off
	s_add_i32 m0, s1, 0x2000
	s_add_u32 s18, s42, 0x80080
	v_lshl_add_u64 v[244:245], v[246:247], 0, s[26:27]
	s_addc_u32 s19, s43, 0
	s_add_i32 s0, s0, s54
	global_load_lds_dwordx4 v[244:245], off
	v_lshl_add_u64 v[244:245], s[18:19], 0, v[150:151]
	s_mov_b32 m0, s0
	s_nop 0
	global_load_lds_dwordx4 v[244:245], off
	v_lshl_add_u64 v[244:245], s[18:19], 0, v[146:147]
	s_add_i32 m0, s0, 0x2000
	s_nop 0
	global_load_lds_dwordx4 v[244:245], off
	v_lshl_add_u64 v[244:245], v[248:249], 0, s[26:27]
	s_mov_b32 m0, s61
	s_nop 0
	global_load_lds_dwordx4 v[244:245], off
	v_lshl_add_u64 v[244:245], v[250:251], 0, s[26:27]
	s_mov_b32 m0, s62
	s_nop 0
	global_load_lds_dwordx4 v[244:245], off
	s_waitcnt vmcnt(8)
	s_waitcnt lgkmcnt(0)
	s_waitcnt lgkmcnt(0)
	v_mfma_f32_16x16x32_bf16 v[102:105], v[134:137], v[198:201], v[102:105]
	v_mfma_f32_16x16x32_bf16 v[98:101], v[142:145], v[198:201], v[98:101]
	v_mfma_f32_16x16x32_bf16 v[66:69], v[134:137], v[206:209], v[66:69]
	v_mfma_f32_16x16x32_bf16 v[58:61], v[142:145], v[206:209], v[58:61]
	s_barrier
	s_setprio 1
	v_mfma_f32_16x16x32_bf16 v[38:41], v[134:137], v[228:231], v[38:41]
	v_mfma_f32_16x16x32_bf16 v[34:37], v[142:145], v[228:231], v[34:37]
	v_mfma_f32_16x16x32_bf16 v[14:17], v[134:137], v[236:239], v[14:17]
	v_mfma_f32_16x16x32_bf16 v[10:13], v[142:145], v[236:239], v[10:13]
	v_mfma_f32_16x16x32_bf16 v[102:105], v[138:141], v[202:205], v[102:105]
	v_mfma_f32_16x16x32_bf16 v[98:101], v[178:181], v[202:205], v[98:101]
	v_mfma_f32_16x16x32_bf16 v[66:69], v[138:141], v[224:227], v[66:69]
	v_mfma_f32_16x16x32_bf16 v[58:61], v[178:181], v[224:227], v[58:61]
	v_mfma_f32_16x16x32_bf16 v[38:41], v[138:141], v[232:235], v[38:41]
	v_mfma_f32_16x16x32_bf16 v[34:37], v[178:181], v[232:235], v[34:37]
	v_mfma_f32_16x16x32_bf16 v[14:17], v[138:141], v[240:243], v[14:17]
	v_mfma_f32_16x16x32_bf16 v[10:13], v[178:181], v[240:243], v[10:13]
	s_setprio 0
	s_setprio 1
	v_mfma_f32_16x16x32_bf16 v[86:89], v[182:185], v[198:201], v[86:89]
	v_mfma_f32_16x16x32_bf16 v[74:77], v[190:193], v[198:201], v[74:77]
	v_mfma_f32_16x16x32_bf16 v[54:57], v[182:185], v[206:209], v[54:57]
	v_mfma_f32_16x16x32_bf16 v[50:53], v[190:193], v[206:209], v[50:53]
	v_mfma_f32_16x16x32_bf16 v[30:33], v[182:185], v[228:231], v[30:33]
	v_mfma_f32_16x16x32_bf16 v[18:21], v[190:193], v[228:231], v[18:21]
	v_mfma_f32_16x16x32_bf16 v[6:9], v[182:185], v[236:239], v[6:9]
	v_mfma_f32_16x16x32_bf16 v[2:5], v[190:193], v[236:239], v[2:5]
	v_mfma_f32_16x16x32_bf16 v[86:89], v[186:189], v[202:205], v[86:89]
	v_mfma_f32_16x16x32_bf16 v[74:77], v[194:197], v[202:205], v[74:77]
	v_mfma_f32_16x16x32_bf16 v[54:57], v[186:189], v[224:227], v[54:57]
	v_mfma_f32_16x16x32_bf16 v[50:53], v[194:197], v[224:227], v[50:53]
	v_mfma_f32_16x16x32_bf16 v[30:33], v[186:189], v[232:235], v[30:33]
	v_mfma_f32_16x16x32_bf16 v[18:21], v[194:197], v[232:235], v[18:21]
	v_mfma_f32_16x16x32_bf16 v[6:9], v[186:189], v[240:243], v[6:9]
	v_mfma_f32_16x16x32_bf16 v[2:5], v[194:197], v[240:243], v[2:5]
	s_setprio 0
	s_barrier
	s_add_i32 s17, s17, 2
	s_cmp_gt_u32 s17, 29
	s_mov_b64 s[38:39], s[40:41]
	s_cbranch_scc0 .LBB0_1497
	s_and_b64 vcc, exec, s[28:29]
	s_cbranch_vccz .LBB0_1500
	s_barrier

.LBB0_1604:
	ds_read_b128 v[154:157], v151
	ds_read_b128 v[158:161], v151 offset:1024
	ds_read_b128 v[164:167], v151 offset:2048
	ds_read_b128 v[168:171], v151 offset:3072
	ds_read_b128 v[172:175], v152
	ds_read_b128 v[176:179], v152 offset:1024
	ds_read_b128 v[180:183], v152 offset:2048
	ds_read_b128 v[184:187], v152 offset:3072
	s_add_u32 s0, s34, 0xfff80080
	s_addc_u32 s1, s35, -1
	s_cmp_eq_u32 s53, 28
	s_cselect_b32 s39, s16, s1
	s_cselect_b32 s38, s17, s0
	s_cselect_b32 s37, s18, s25
	s_cselect_b32 s36, s19, s23
	v_lshl_add_u64 v[146:147], s[34:35], 0, v[138:139]
	s_add_i32 m0, s31, 0xc000
	ds_read_b128 v[188:191], v153
	ds_read_b128 v[192:195], v153 offset:1024
	ds_read_b128 v[196:199], v153 offset:2048
	ds_read_b128 v[200:203], v153 offset:3072
	ds_read_b128 v[204:207], v153 offset:4096
	ds_read_b128 v[208:211], v153 offset:5120
	ds_read_b128 v[212:215], v153 offset:6144
	ds_read_b128 v[216:219], v153 offset:7168
	global_load_lds_dwordx4 v[146:147], off
	v_lshl_add_u64 v[146:147], s[34:35], 0, v[140:141]
	s_add_i32 m0, s31, 0xe000
	s_nop 0
	global_load_lds_dwordx4 v[146:147], off
	s_waitcnt vmcnt(8)
	s_waitcnt lgkmcnt(0)
	s_waitcnt lgkmcnt(0)
	v_mfma_f32_16x16x32_bf16 v[126:129], v[154:157], v[188:191], v[126:129]
	v_mfma_f32_16x16x32_bf16 v[122:125], v[164:167], v[188:191], v[122:125]
	v_mfma_f32_16x16x32_bf16 v[110:113], v[154:157], v[196:199], v[110:113]
	v_mfma_f32_16x16x32_bf16 v[106:109], v[164:167], v[196:199], v[106:109]
	s_barrier
	s_setprio 1
	v_mfma_f32_16x16x32_bf16 v[94:97], v[154:157], v[204:207], v[94:97]
	v_mfma_f32_16x16x32_bf16 v[90:93], v[164:167], v[204:207], v[90:93]
	v_mfma_f32_16x16x32_bf16 v[78:81], v[154:157], v[212:215], v[78:81]
	v_mfma_f32_16x16x32_bf16 v[74:77], v[164:167], v[212:215], v[74:77]
	v_mfma_f32_16x16x32_bf16 v[126:129], v[158:161], v[192:195], v[126:129]
	v_mfma_f32_16x16x32_bf16 v[122:125], v[168:171], v[192:195], v[122:125]
	v_mfma_f32_16x16x32_bf16 v[110:113], v[158:161], v[200:203], v[110:113]
	v_mfma_f32_16x16x32_bf16 v[106:109], v[168:171], v[200:203], v[106:109]
	v_mfma_f32_16x16x32_bf16 v[94:97], v[158:161], v[208:211], v[94:97]
	v_mfma_f32_16x16x32_bf16 v[90:93], v[168:171], v[208:211], v[90:93]
	v_mfma_f32_16x16x32_bf16 v[78:81], v[158:161], v[216:219], v[78:81]
	v_mfma_f32_16x16x32_bf16 v[74:77], v[168:171], v[216:219], v[74:77]
	s_setprio 0
	s_setprio 1
	v_mfma_f32_16x16x32_bf16 v[118:121], v[172:175], v[188:191], v[118:121]
	v_mfma_f32_16x16x32_bf16 v[114:117], v[180:183], v[188:191], v[114:117]
	v_mfma_f32_16x16x32_bf16 v[102:105], v[172:175], v[196:199], v[102:105]
	v_mfma_f32_16x16x32_bf16 v[98:101], v[180:183], v[196:199], v[98:101]
	v_mfma_f32_16x16x32_bf16 v[86:89], v[172:175], v[204:207], v[86:89]
	v_mfma_f32_16x16x32_bf16 v[82:85], v[180:183], v[204:207], v[82:85]
	v_mfma_f32_16x16x32_bf16 v[70:73], v[172:175], v[212:215], v[70:73]
	v_mfma_f32_16x16x32_bf16 v[66:69], v[180:183], v[212:215], v[66:69]
	v_mfma_f32_16x16x32_bf16 v[118:121], v[176:179], v[192:195], v[118:121]
	v_mfma_f32_16x16x32_bf16 v[114:117], v[184:187], v[192:195], v[114:117]
	v_mfma_f32_16x16x32_bf16 v[102:105], v[176:179], v[200:203], v[102:105]
	v_mfma_f32_16x16x32_bf16 v[98:101], v[184:187], v[200:203], v[98:101]
	v_mfma_f32_16x16x32_bf16 v[86:89], v[176:179], v[208:211], v[86:89]
	v_mfma_f32_16x16x32_bf16 v[82:85], v[184:187], v[208:211], v[82:85]
	v_mfma_f32_16x16x32_bf16 v[70:73], v[176:179], v[216:219], v[70:73]
	v_mfma_f32_16x16x32_bf16 v[66:69], v[184:187], v[216:219], v[66:69]
	s_setprio 0
	s_barrier
	s_add_i32 s0, s15, s44
	v_lshl_add_u64 v[146:147], s[36:37], 0, v[134:135]
	s_mov_b32 m0, s0
	ds_read_b128 v[188:191], v153 offset:16384
	ds_read_b128 v[192:195], v153 offset:17408
	ds_read_b128 v[196:199], v153 offset:18432
	ds_read_b128 v[200:203], v153 offset:19456
	ds_read_b128 v[204:207], v153 offset:20480
	ds_read_b128 v[208:211], v153 offset:21504
	ds_read_b128 v[212:215], v153 offset:22528
	ds_read_b128 v[216:219], v153 offset:23552
	global_load_lds_dwordx4 v[146:147], off
	s_add_i32 m0, s0, 0x2000
	s_add_u32 s54, s36, 0x80000
	v_lshl_add_u64 v[220:221], s[36:37], 0, v[130:131]
	s_addc_u32 s55, s37, 0
	s_add_i32 s0, s51, s44
	global_load_lds_dwordx4 v[220:221], off
	v_lshl_add_u64 v[222:223], s[54:55], 0, v[134:135]
	s_mov_b32 m0, s0
	v_lshl_add_u64 v[224:225], s[38:39], 0, v[132:133]
	global_load_lds_dwordx4 v[222:223], off
	v_lshl_add_u64 v[222:223], s[54:55], 0, v[130:131]
	s_add_i32 m0, s0, 0x2000
	s_nop 0
	global_load_lds_dwordx4 v[222:223], off
	v_lshl_add_u64 v[222:223], s[38:39], 0, v[136:137]
	s_mov_b32 m0, s31
	s_nop 0
	global_load_lds_dwordx4 v[222:223], off
	s_mov_b32 m0, s47
	s_nop 0
	global_load_lds_dwordx4 v[224:225], off
	s_waitcnt vmcnt(8)
	s_waitcnt lgkmcnt(0)
	s_waitcnt lgkmcnt(0)
	v_mfma_f32_16x16x32_bf16 v[62:65], v[154:157], v[188:191], v[62:65]
	v_mfma_f32_16x16x32_bf16 v[58:61], v[164:167], v[188:191], v[58:61]
	v_mfma_f32_16x16x32_bf16 v[46:49], v[154:157], v[196:199], v[46:49]
	v_mfma_f32_16x16x32_bf16 v[42:45], v[164:167], v[196:199], v[42:45]
	s_barrier
	s_setprio 1
	v_mfma_f32_16x16x32_bf16 v[30:33], v[154:157], v[204:207], v[30:33]
	v_mfma_f32_16x16x32_bf16 v[26:29], v[164:167], v[204:207], v[26:29]
	v_mfma_f32_16x16x32_bf16 v[14:17], v[154:157], v[212:215], v[14:17]
	v_mfma_f32_16x16x32_bf16 v[10:13], v[164:167], v[212:215], v[10:13]
	v_mfma_f32_16x16x32_bf16 v[62:65], v[158:161], v[192:195], v[62:65]
	v_mfma_f32_16x16x32_bf16 v[58:61], v[168:171], v[192:195], v[58:61]
	v_mfma_f32_16x16x32_bf16 v[46:49], v[158:161], v[200:203], v[46:49]
	v_mfma_f32_16x16x32_bf16 v[42:45], v[168:171], v[200:203], v[42:45]
	v_mfma_f32_16x16x32_bf16 v[30:33], v[158:161], v[208:211], v[30:33]
	v_mfma_f32_16x16x32_bf16 v[26:29], v[168:171], v[208:211], v[26:29]
	v_mfma_f32_16x16x32_bf16 v[14:17], v[158:161], v[216:219], v[14:17]
	v_mfma_f32_16x16x32_bf16 v[10:13], v[168:171], v[216:219], v[10:13]
	s_setprio 0
	s_setprio 1
	v_mfma_f32_16x16x32_bf16 v[54:57], v[172:175], v[188:191], v[54:57]
	v_mfma_f32_16x16x32_bf16 v[50:53], v[180:183], v[188:191], v[50:53]
	v_mfma_f32_16x16x32_bf16 v[38:41], v[172:175], v[196:199], v[38:41]
	v_mfma_f32_16x16x32_bf16 v[34:37], v[180:183], v[196:199], v[34:37]
	v_mfma_f32_16x16x32_bf16 v[22:25], v[172:175], v[204:207], v[22:25]
	v_mfma_f32_16x16x32_bf16 v[18:21], v[180:183], v[204:207], v[18:21]
	v_mfma_f32_16x16x32_bf16 v[6:9], v[172:175], v[212:215], v[6:9]
	v_mfma_f32_16x16x32_bf16 v[2:5], v[180:183], v[212:215], v[2:5]
	v_mfma_f32_16x16x32_bf16 v[54:57], v[176:179], v[192:195], v[54:57]
	v_mfma_f32_16x16x32_bf16 v[50:53], v[184:187], v[192:195], v[50:53]
	v_mfma_f32_16x16x32_bf16 v[38:41], v[176:179], v[200:203], v[38:41]
	v_mfma_f32_16x16x32_bf16 v[34:37], v[184:187], v[200:203], v[34:37]
	v_mfma_f32_16x16x32_bf16 v[22:25], v[176:179], v[208:211], v[22:25]
	v_mfma_f32_16x16x32_bf16 v[18:21], v[184:187], v[208:211], v[18:21]
	v_mfma_f32_16x16x32_bf16 v[6:9], v[176:179], v[216:219], v[6:9]
	v_mfma_f32_16x16x32_bf16 v[2:5], v[184:187], v[216:219], v[2:5]
	s_setprio 0
	s_barrier
	s_add_i32 s0, 0, 0x18000
	v_add_u32_e32 v163, s0, v149
	s_add_i32 s1, 0, 0x1c000
	ds_read_b128 v[154:157], v163
	ds_read_b128 v[158:161], v163 offset:1024
	ds_read_b128 v[164:167], v163 offset:2048
	ds_read_b128 v[168:171], v163 offset:3072
	v_add_u32_e32 v163, s1, v149
	ds_read_b128 v[172:175], v163
	ds_read_b128 v[176:179], v163 offset:1024
	ds_read_b128 v[180:183], v163 offset:2048
	ds_read_b128 v[184:187], v163 offset:3072
	s_add_u32 s38, s38, 0x80000
	s_addc_u32 s39, s39, 0
	s_mov_b32 m0, s48
	v_lshl_add_u64 v[226:227], s[38:39], 0, v[136:137]
	ds_read_b128 v[188:191], v153 offset:32768
	ds_read_b128 v[192:195], v153 offset:33792
	ds_read_b128 v[196:199], v153 offset:34816
	ds_read_b128 v[200:203], v153 offset:35840
	ds_read_b128 v[204:207], v153 offset:36864
	ds_read_b128 v[208:211], v153 offset:37888
	ds_read_b128 v[212:215], v153 offset:38912
	ds_read_b128 v[216:219], v153 offset:39936
	global_load_lds_dwordx4 v[226:227], off
	v_lshl_add_u64 v[226:227], s[38:39], 0, v[132:133]
	s_mov_b32 m0, s49
	s_nop 0
	global_load_lds_dwordx4 v[226:227], off
	s_waitcnt vmcnt(8)
	s_waitcnt lgkmcnt(0)
	s_waitcnt lgkmcnt(0)
	v_mfma_f32_16x16x32_bf16 v[126:129], v[154:157], v[188:191], v[126:129]
	v_mfma_f32_16x16x32_bf16 v[122:125], v[164:167], v[188:191], v[122:125]
	v_mfma_f32_16x16x32_bf16 v[110:113], v[154:157], v[196:199], v[110:113]
	v_mfma_f32_16x16x32_bf16 v[106:109], v[164:167], v[196:199], v[106:109]
	s_barrier
	s_setprio 1
	v_mfma_f32_16x16x32_bf16 v[94:97], v[154:157], v[204:207], v[94:97]
	v_mfma_f32_16x16x32_bf16 v[90:93], v[164:167], v[204:207], v[90:93]
	v_mfma_f32_16x16x32_bf16 v[78:81], v[154:157], v[212:215], v[78:81]
	v_mfma_f32_16x16x32_bf16 v[74:77], v[164:167], v[212:215], v[74:77]
	v_mfma_f32_16x16x32_bf16 v[126:129], v[158:161], v[192:195], v[126:129]
	v_mfma_f32_16x16x32_bf16 v[122:125], v[168:171], v[192:195], v[122:125]
	v_mfma_f32_16x16x32_bf16 v[110:113], v[158:161], v[200:203], v[110:113]
	v_mfma_f32_16x16x32_bf16 v[106:109], v[168:171], v[200:203], v[106:109]
	v_mfma_f32_16x16x32_bf16 v[94:97], v[158:161], v[208:211], v[94:97]
	v_mfma_f32_16x16x32_bf16 v[90:93], v[168:171], v[208:211], v[90:93]
	v_mfma_f32_16x16x32_bf16 v[78:81], v[158:161], v[216:219], v[78:81]
	v_mfma_f32_16x16x32_bf16 v[74:77], v[168:171], v[216:219], v[74:77]
	s_setprio 0
	s_setprio 1
	v_mfma_f32_16x16x32_bf16 v[118:121], v[172:175], v[188:191], v[118:121]
	v_mfma_f32_16x16x32_bf16 v[114:117], v[180:183], v[188:191], v[114:117]
	v_mfma_f32_16x16x32_bf16 v[102:105], v[172:175], v[196:199], v[102:105]
	v_mfma_f32_16x16x32_bf16 v[98:101], v[180:183], v[196:199], v[98:101]
	v_mfma_f32_16x16x32_bf16 v[86:89], v[172:175], v[204:207], v[86:89]
	v_mfma_f32_16x16x32_bf16 v[82:85], v[180:183], v[204:207], v[82:85]
	v_mfma_f32_16x16x32_bf16 v[70:73], v[172:175], v[212:215], v[70:73]
	v_mfma_f32_16x16x32_bf16 v[66:69], v[180:183], v[212:215], v[66:69]
	v_mfma_f32_16x16x32_bf16 v[118:121], v[176:179], v[192:195], v[118:121]
	v_mfma_f32_16x16x32_bf16 v[114:117], v[184:187], v[192:195], v[114:117]
	v_mfma_f32_16x16x32_bf16 v[102:105], v[176:179], v[200:203], v[102:105]
	v_mfma_f32_16x16x32_bf16 v[98:101], v[184:187], v[200:203], v[98:101]
	v_mfma_f32_16x16x32_bf16 v[86:89], v[176:179], v[208:211], v[86:89]
	v_mfma_f32_16x16x32_bf16 v[82:85], v[184:187], v[208:211], v[82:85]
	v_mfma_f32_16x16x32_bf16 v[70:73], v[176:179], v[216:219], v[70:73]
	v_mfma_f32_16x16x32_bf16 v[66:69], v[184:187], v[216:219], v[66:69]
	s_setprio 0
	s_barrier
	s_add_i32 s0, s0, s44
	v_lshl_add_u64 v[146:147], v[146:147], 0, s[10:11]
	s_mov_b32 m0, s0
	ds_read_b128 v[188:191], v153 offset:49152
	ds_read_b128 v[192:195], v153 offset:50176
	ds_read_b128 v[196:199], v153 offset:51200
	ds_read_b128 v[200:203], v153 offset:52224
	ds_read_b128 v[204:207], v153 offset:53248
	ds_read_b128 v[208:211], v153 offset:54272
	ds_read_b128 v[212:215], v153 offset:55296
	ds_read_b128 v[216:219], v153 offset:56320
	global_load_lds_dwordx4 v[146:147], off
	s_add_i32 m0, s0, 0x2000
	s_add_u32 s36, s36, 0x80080
	v_lshl_add_u64 v[146:147], v[220:221], 0, s[10:11]
	s_addc_u32 s37, s37, 0
	s_add_i32 s0, s1, s44
	global_load_lds_dwordx4 v[146:147], off
	v_lshl_add_u64 v[146:147], s[36:37], 0, v[134:135]
	s_mov_b32 m0, s0
	s_nop 0
	global_load_lds_dwordx4 v[146:147], off
	v_lshl_add_u64 v[146:147], s[36:37], 0, v[130:131]
	s_add_i32 m0, s0, 0x2000
	s_nop 0
	global_load_lds_dwordx4 v[146:147], off
	v_lshl_add_u64 v[146:147], v[222:223], 0, s[10:11]
	s_mov_b32 m0, s20
	s_nop 0
	global_load_lds_dwordx4 v[146:147], off
	v_lshl_add_u64 v[146:147], v[224:225], 0, s[10:11]
	s_mov_b32 m0, s21
	s_nop 0
	global_load_lds_dwordx4 v[146:147], off
	s_waitcnt vmcnt(8)
	s_waitcnt lgkmcnt(0)
	s_waitcnt lgkmcnt(0)
	v_mfma_f32_16x16x32_bf16 v[62:65], v[154:157], v[188:191], v[62:65]
	v_mfma_f32_16x16x32_bf16 v[58:61], v[164:167], v[188:191], v[58:61]
	v_mfma_f32_16x16x32_bf16 v[46:49], v[154:157], v[196:199], v[46:49]
	v_mfma_f32_16x16x32_bf16 v[42:45], v[164:167], v[196:199], v[42:45]
	s_barrier
	s_setprio 1
	v_mfma_f32_16x16x32_bf16 v[30:33], v[154:157], v[204:207], v[30:33]
	v_mfma_f32_16x16x32_bf16 v[26:29], v[164:167], v[204:207], v[26:29]
	v_mfma_f32_16x16x32_bf16 v[14:17], v[154:157], v[212:215], v[14:17]
	v_mfma_f32_16x16x32_bf16 v[10:13], v[164:167], v[212:215], v[10:13]
	v_mfma_f32_16x16x32_bf16 v[62:65], v[158:161], v[192:195], v[62:65]
	v_mfma_f32_16x16x32_bf16 v[58:61], v[168:171], v[192:195], v[58:61]
	v_mfma_f32_16x16x32_bf16 v[46:49], v[158:161], v[200:203], v[46:49]
	v_mfma_f32_16x16x32_bf16 v[42:45], v[168:171], v[200:203], v[42:45]
	v_mfma_f32_16x16x32_bf16 v[30:33], v[158:161], v[208:211], v[30:33]
	v_mfma_f32_16x16x32_bf16 v[26:29], v[168:171], v[208:211], v[26:29]
	v_mfma_f32_16x16x32_bf16 v[14:17], v[158:161], v[216:219], v[14:17]
	v_mfma_f32_16x16x32_bf16 v[10:13], v[168:171], v[216:219], v[10:13]
	s_setprio 0
	s_setprio 1
	v_mfma_f32_16x16x32_bf16 v[54:57], v[172:175], v[188:191], v[54:57]
	v_mfma_f32_16x16x32_bf16 v[50:53], v[180:183], v[188:191], v[50:53]
	v_mfma_f32_16x16x32_bf16 v[38:41], v[172:175], v[196:199], v[38:41]
	v_mfma_f32_16x16x32_bf16 v[34:37], v[180:183], v[196:199], v[34:37]
	v_mfma_f32_16x16x32_bf16 v[22:25], v[172:175], v[204:207], v[22:25]
	v_mfma_f32_16x16x32_bf16 v[18:21], v[180:183], v[204:207], v[18:21]
	v_mfma_f32_16x16x32_bf16 v[6:9], v[172:175], v[212:215], v[6:9]
	v_mfma_f32_16x16x32_bf16 v[2:5], v[180:183], v[212:215], v[2:5]
	v_mfma_f32_16x16x32_bf16 v[54:57], v[176:179], v[192:195], v[54:57]
	v_mfma_f32_16x16x32_bf16 v[50:53], v[184:187], v[192:195], v[50:53]
	v_mfma_f32_16x16x32_bf16 v[38:41], v[176:179], v[200:203], v[38:41]
	v_mfma_f32_16x16x32_bf16 v[34:37], v[184:187], v[200:203], v[34:37]
	v_mfma_f32_16x16x32_bf16 v[22:25], v[176:179], v[208:211], v[22:25]
	v_mfma_f32_16x16x32_bf16 v[18:21], v[184:187], v[208:211], v[18:21]
	v_mfma_f32_16x16x32_bf16 v[6:9], v[176:179], v[216:219], v[6:9]
	v_mfma_f32_16x16x32_bf16 v[2:5], v[184:187], v[216:219], v[2:5]
	s_setprio 0
	s_barrier
	s_add_i32 s53, s53, 2
	s_add_u32 s34, s34, 0x100
	s_addc_u32 s35, s35, 0
	s_add_u32 s23, s23, 0x100
	s_addc_u32 s25, s25, 0
	s_cmp_gt_u32 s53, 29
	s_cbranch_scc0 .LBB0_1604
	s_and_b64 vcc, exec, s[12:13]
	s_cbranch_vccz .LBB0_1607
	s_barrier

.LBB0_1675:
	ds_read_b128 v[156:159], v191
	ds_read_b128 v[160:163], v191 offset:1024
	ds_read_b128 v[164:167], v191 offset:2048
	ds_read_b128 v[168:171], v191 offset:3072
	ds_read_b128 v[172:175], v192
	ds_read_b128 v[176:179], v192 offset:1024
	ds_read_b128 v[180:183], v192 offset:2048
	ds_read_b128 v[184:187], v192 offset:3072
	s_add_u32 s36, s30, 0xffea0080
	s_addc_u32 s37, s31, -1
	s_cmpk_eq_i32 s29, 0x54
	s_cselect_b32 s39, s25, s37
	s_cselect_b32 s38, s24, s36
	s_cselect_b32 s37, s5, s35
	s_cselect_b32 s36, s4, s34
	s_mov_b32 m0, s57
	v_lshl_add_u64 v[234:235], s[30:31], 0, v[150:151]
	ds_read_b128 v[202:205], v193
	ds_read_b128 v[206:209], v193 offset:1024
	ds_read_b128 v[210:213], v193 offset:2048
	ds_read_b128 v[214:217], v193 offset:3072
	ds_read_b128 v[218:221], v193 offset:4096
	ds_read_b128 v[222:225], v193 offset:5120
	ds_read_b128 v[226:229], v193 offset:6144
	ds_read_b128 v[230:233], v193 offset:7168
	global_load_lds_dwordx4 v[234:235], off
	v_lshl_add_u64 v[234:235], s[30:31], 0, v[152:153]
	s_mov_b32 m0, s58
	s_nop 0
	global_load_lds_dwordx4 v[234:235], off
	s_waitcnt vmcnt(8)
	s_waitcnt lgkmcnt(0)
	s_waitcnt lgkmcnt(0)
	v_mfma_f32_16x16x32_bf16 v[126:129], v[156:159], v[202:205], v[126:129]
	v_mfma_f32_16x16x32_bf16 v[122:125], v[164:167], v[202:205], v[122:125]
	v_mfma_f32_16x16x32_bf16 v[110:113], v[156:159], v[210:213], v[110:113]
	v_mfma_f32_16x16x32_bf16 v[106:109], v[164:167], v[210:213], v[106:109]
	s_barrier
	s_setprio 1
	v_mfma_f32_16x16x32_bf16 v[94:97], v[156:159], v[218:221], v[94:97]
	v_mfma_f32_16x16x32_bf16 v[90:93], v[164:167], v[218:221], v[90:93]
	v_mfma_f32_16x16x32_bf16 v[78:81], v[156:159], v[226:229], v[78:81]
	v_mfma_f32_16x16x32_bf16 v[74:77], v[164:167], v[226:229], v[74:77]
	v_mfma_f32_16x16x32_bf16 v[126:129], v[160:163], v[206:209], v[126:129]
	v_mfma_f32_16x16x32_bf16 v[122:125], v[168:171], v[206:209], v[122:125]
	v_mfma_f32_16x16x32_bf16 v[110:113], v[160:163], v[214:217], v[110:113]
	v_mfma_f32_16x16x32_bf16 v[106:109], v[168:171], v[214:217], v[106:109]
	v_mfma_f32_16x16x32_bf16 v[94:97], v[160:163], v[222:225], v[94:97]
	v_mfma_f32_16x16x32_bf16 v[90:93], v[168:171], v[222:225], v[90:93]
	v_mfma_f32_16x16x32_bf16 v[78:81], v[160:163], v[230:233], v[78:81]
	v_mfma_f32_16x16x32_bf16 v[74:77], v[168:171], v[230:233], v[74:77]
	s_setprio 0
	s_setprio 1
	v_mfma_f32_16x16x32_bf16 v[118:121], v[172:175], v[202:205], v[118:121]
	v_mfma_f32_16x16x32_bf16 v[114:117], v[180:183], v[202:205], v[114:117]
	v_mfma_f32_16x16x32_bf16 v[102:105], v[172:175], v[210:213], v[102:105]
	v_mfma_f32_16x16x32_bf16 v[98:101], v[180:183], v[210:213], v[98:101]
	v_mfma_f32_16x16x32_bf16 v[86:89], v[172:175], v[218:221], v[86:89]
	v_mfma_f32_16x16x32_bf16 v[82:85], v[180:183], v[218:221], v[82:85]
	v_mfma_f32_16x16x32_bf16 v[70:73], v[172:175], v[226:229], v[70:73]
	v_mfma_f32_16x16x32_bf16 v[66:69], v[180:183], v[226:229], v[66:69]
	v_mfma_f32_16x16x32_bf16 v[118:121], v[176:179], v[206:209], v[118:121]
	v_mfma_f32_16x16x32_bf16 v[114:117], v[184:187], v[206:209], v[114:117]
	v_mfma_f32_16x16x32_bf16 v[102:105], v[176:179], v[214:217], v[102:105]
	v_mfma_f32_16x16x32_bf16 v[98:101], v[184:187], v[214:217], v[98:101]
	v_mfma_f32_16x16x32_bf16 v[86:89], v[176:179], v[222:225], v[86:89]
	v_mfma_f32_16x16x32_bf16 v[82:85], v[184:187], v[222:225], v[82:85]
	v_mfma_f32_16x16x32_bf16 v[70:73], v[176:179], v[230:233], v[70:73]
	v_mfma_f32_16x16x32_bf16 v[66:69], v[184:187], v[230:233], v[66:69]
	s_setprio 0
	s_barrier
	s_mov_b32 m0, s59
	v_lshl_add_u64 v[234:235], s[36:37], 0, v[134:135]
	s_add_u32 s40, s36, 0x160000
	ds_read_b128 v[202:205], v193 offset:16384
	ds_read_b128 v[206:209], v193 offset:17408
	ds_read_b128 v[210:213], v193 offset:18432
	ds_read_b128 v[214:217], v193 offset:19456
	ds_read_b128 v[218:221], v193 offset:20480
	ds_read_b128 v[222:225], v193 offset:21504
	ds_read_b128 v[226:229], v193 offset:22528
	ds_read_b128 v[230:233], v193 offset:23552
	global_load_lds_dwordx4 v[234:235], off
	v_lshl_add_u64 v[236:237], s[36:37], 0, v[130:131]
	s_mov_b32 m0, s60
	s_addc_u32 s41, s37, 0
	global_load_lds_dwordx4 v[236:237], off
	v_lshl_add_u64 v[238:239], s[40:41], 0, v[134:135]
	s_mov_b32 m0, s61
	v_lshl_add_u64 v[240:241], s[38:39], 0, v[132:133]
	global_load_lds_dwordx4 v[238:239], off
	v_lshl_add_u64 v[238:239], s[40:41], 0, v[130:131]
	s_mov_b32 m0, s62
	s_nop 0
	global_load_lds_dwordx4 v[238:239], off
	v_lshl_add_u64 v[238:239], s[38:39], 0, v[136:137]
	s_mov_b32 m0, s48
	s_nop 0
	global_load_lds_dwordx4 v[238:239], off
	s_mov_b32 m0, s49
	s_nop 0
	global_load_lds_dwordx4 v[240:241], off
	s_waitcnt vmcnt(8)
	s_waitcnt lgkmcnt(0)
	s_waitcnt lgkmcnt(0)
	v_mfma_f32_16x16x32_bf16 v[62:65], v[156:159], v[202:205], v[62:65]
	v_mfma_f32_16x16x32_bf16 v[58:61], v[164:167], v[202:205], v[58:61]
	v_mfma_f32_16x16x32_bf16 v[46:49], v[156:159], v[210:213], v[46:49]
	v_mfma_f32_16x16x32_bf16 v[42:45], v[164:167], v[210:213], v[42:45]
	s_barrier
	s_setprio 1
	v_mfma_f32_16x16x32_bf16 v[30:33], v[156:159], v[218:221], v[30:33]
	v_mfma_f32_16x16x32_bf16 v[26:29], v[164:167], v[218:221], v[26:29]
	v_mfma_f32_16x16x32_bf16 v[14:17], v[156:159], v[226:229], v[14:17]
	v_mfma_f32_16x16x32_bf16 v[10:13], v[164:167], v[226:229], v[10:13]
	v_mfma_f32_16x16x32_bf16 v[62:65], v[160:163], v[206:209], v[62:65]
	v_mfma_f32_16x16x32_bf16 v[58:61], v[168:171], v[206:209], v[58:61]
	v_mfma_f32_16x16x32_bf16 v[46:49], v[160:163], v[214:217], v[46:49]
	v_mfma_f32_16x16x32_bf16 v[42:45], v[168:171], v[214:217], v[42:45]
	v_mfma_f32_16x16x32_bf16 v[30:33], v[160:163], v[222:225], v[30:33]
	v_mfma_f32_16x16x32_bf16 v[26:29], v[168:171], v[222:225], v[26:29]
	v_mfma_f32_16x16x32_bf16 v[14:17], v[160:163], v[230:233], v[14:17]
	v_mfma_f32_16x16x32_bf16 v[10:13], v[168:171], v[230:233], v[10:13]
	s_setprio 0
	s_setprio 1
	v_mfma_f32_16x16x32_bf16 v[54:57], v[172:175], v[202:205], v[54:57]
	v_mfma_f32_16x16x32_bf16 v[50:53], v[180:183], v[202:205], v[50:53]
	v_mfma_f32_16x16x32_bf16 v[38:41], v[172:175], v[210:213], v[38:41]
	v_mfma_f32_16x16x32_bf16 v[34:37], v[180:183], v[210:213], v[34:37]
	v_mfma_f32_16x16x32_bf16 v[22:25], v[172:175], v[218:221], v[22:25]
	v_mfma_f32_16x16x32_bf16 v[18:21], v[180:183], v[218:221], v[18:21]
	v_mfma_f32_16x16x32_bf16 v[6:9], v[172:175], v[226:229], v[6:9]
	v_mfma_f32_16x16x32_bf16 v[2:5], v[180:183], v[226:229], v[2:5]
	v_mfma_f32_16x16x32_bf16 v[54:57], v[176:179], v[206:209], v[54:57]
	v_mfma_f32_16x16x32_bf16 v[50:53], v[184:187], v[206:209], v[50:53]
	v_mfma_f32_16x16x32_bf16 v[38:41], v[176:179], v[214:217], v[38:41]
	v_mfma_f32_16x16x32_bf16 v[34:37], v[184:187], v[214:217], v[34:37]
	v_mfma_f32_16x16x32_bf16 v[22:25], v[176:179], v[222:225], v[22:25]
	v_mfma_f32_16x16x32_bf16 v[18:21], v[184:187], v[222:225], v[18:21]
	v_mfma_f32_16x16x32_bf16 v[6:9], v[176:179], v[230:233], v[6:9]
	v_mfma_f32_16x16x32_bf16 v[2:5], v[184:187], v[230:233], v[2:5]
	s_setprio 0
	s_barrier
	ds_read_b128 v[156:159], v197
	ds_read_b128 v[160:163], v197 offset:1024
	ds_read_b128 v[164:167], v197 offset:2048
	ds_read_b128 v[168:171], v197 offset:3072
	ds_read_b128 v[172:175], v198
	ds_read_b128 v[176:179], v198 offset:1024
	ds_read_b128 v[180:183], v198 offset:2048
	ds_read_b128 v[184:187], v198 offset:3072
	s_add_u32 s38, s38, 0x160000
	s_addc_u32 s39, s39, 0
	s_mov_b32 m0, s50
	v_lshl_add_u64 v[242:243], s[38:39], 0, v[136:137]
	ds_read_b128 v[202:205], v193 offset:32768
	ds_read_b128 v[206:209], v193 offset:33792
	ds_read_b128 v[210:213], v193 offset:34816
	ds_read_b128 v[214:217], v193 offset:35840
	ds_read_b128 v[218:221], v193 offset:36864
	ds_read_b128 v[222:225], v193 offset:37888
	ds_read_b128 v[226:229], v193 offset:38912
	ds_read_b128 v[230:233], v193 offset:39936
	global_load_lds_dwordx4 v[242:243], off
	v_lshl_add_u64 v[242:243], s[38:39], 0, v[132:133]
	s_mov_b32 m0, s51
	s_nop 0
	global_load_lds_dwordx4 v[242:243], off
	s_waitcnt vmcnt(8)
	s_waitcnt lgkmcnt(0)
	s_waitcnt lgkmcnt(0)
	v_mfma_f32_16x16x32_bf16 v[126:129], v[156:159], v[202:205], v[126:129]
	v_mfma_f32_16x16x32_bf16 v[122:125], v[164:167], v[202:205], v[122:125]
	v_mfma_f32_16x16x32_bf16 v[110:113], v[156:159], v[210:213], v[110:113]
	v_mfma_f32_16x16x32_bf16 v[106:109], v[164:167], v[210:213], v[106:109]
	s_barrier
	s_setprio 1
	v_mfma_f32_16x16x32_bf16 v[94:97], v[156:159], v[218:221], v[94:97]
	v_mfma_f32_16x16x32_bf16 v[90:93], v[164:167], v[218:221], v[90:93]
	v_mfma_f32_16x16x32_bf16 v[78:81], v[156:159], v[226:229], v[78:81]
	v_mfma_f32_16x16x32_bf16 v[74:77], v[164:167], v[226:229], v[74:77]
	v_mfma_f32_16x16x32_bf16 v[126:129], v[160:163], v[206:209], v[126:129]
	v_mfma_f32_16x16x32_bf16 v[122:125], v[168:171], v[206:209], v[122:125]
	v_mfma_f32_16x16x32_bf16 v[110:113], v[160:163], v[214:217], v[110:113]
	v_mfma_f32_16x16x32_bf16 v[106:109], v[168:171], v[214:217], v[106:109]
	v_mfma_f32_16x16x32_bf16 v[94:97], v[160:163], v[222:225], v[94:97]
	v_mfma_f32_16x16x32_bf16 v[90:93], v[168:171], v[222:225], v[90:93]
	v_mfma_f32_16x16x32_bf16 v[78:81], v[160:163], v[230:233], v[78:81]
	v_mfma_f32_16x16x32_bf16 v[74:77], v[168:171], v[230:233], v[74:77]
	s_setprio 0
	s_setprio 1
	v_mfma_f32_16x16x32_bf16 v[118:121], v[172:175], v[202:205], v[118:121]
	v_mfma_f32_16x16x32_bf16 v[114:117], v[180:183], v[202:205], v[114:117]
	v_mfma_f32_16x16x32_bf16 v[102:105], v[172:175], v[210:213], v[102:105]
	v_mfma_f32_16x16x32_bf16 v[98:101], v[180:183], v[210:213], v[98:101]
	v_mfma_f32_16x16x32_bf16 v[86:89], v[172:175], v[218:221], v[86:89]
	v_mfma_f32_16x16x32_bf16 v[82:85], v[180:183], v[218:221], v[82:85]
	v_mfma_f32_16x16x32_bf16 v[70:73], v[172:175], v[226:229], v[70:73]
	v_mfma_f32_16x16x32_bf16 v[66:69], v[180:183], v[226:229], v[66:69]
	v_mfma_f32_16x16x32_bf16 v[118:121], v[176:179], v[206:209], v[118:121]
	v_mfma_f32_16x16x32_bf16 v[114:117], v[184:187], v[206:209], v[114:117]
	v_mfma_f32_16x16x32_bf16 v[102:105], v[176:179], v[214:217], v[102:105]
	v_mfma_f32_16x16x32_bf16 v[98:101], v[184:187], v[214:217], v[98:101]
	v_mfma_f32_16x16x32_bf16 v[86:89], v[176:179], v[222:225], v[86:89]
	v_mfma_f32_16x16x32_bf16 v[82:85], v[184:187], v[222:225], v[82:85]
	v_mfma_f32_16x16x32_bf16 v[70:73], v[176:179], v[230:233], v[70:73]
	v_mfma_f32_16x16x32_bf16 v[66:69], v[184:187], v[230:233], v[66:69]
	s_setprio 0
	s_barrier
	s_mov_b32 m0, s64
	v_lshl_add_u64 v[234:235], v[234:235], 0, s[12:13]
	s_add_u32 s36, s36, 0x160080
	ds_read_b128 v[202:205], v193 offset:49152
	ds_read_b128 v[206:209], v193 offset:50176
	ds_read_b128 v[210:213], v193 offset:51200
	ds_read_b128 v[214:217], v193 offset:52224
	ds_read_b128 v[218:221], v193 offset:53248
	ds_read_b128 v[222:225], v193 offset:54272
	ds_read_b128 v[226:229], v193 offset:55296
	ds_read_b128 v[230:233], v193 offset:56320
	global_load_lds_dwordx4 v[234:235], off
	v_lshl_add_u64 v[234:235], v[236:237], 0, s[12:13]
	s_mov_b32 m0, s65
	s_addc_u32 s37, s37, 0
	s_add_i32 s38, s63, s47
	global_load_lds_dwordx4 v[234:235], off
	v_lshl_add_u64 v[234:235], s[36:37], 0, v[134:135]
	s_mov_b32 m0, s38
	s_nop 0
	global_load_lds_dwordx4 v[234:235], off
	v_lshl_add_u64 v[234:235], s[36:37], 0, v[130:131]
	s_add_i32 m0, s38, 0x2000
	s_nop 0
	global_load_lds_dwordx4 v[234:235], off
	v_lshl_add_u64 v[234:235], v[238:239], 0, s[12:13]
	s_mov_b32 m0, s55
	s_nop 0
	global_load_lds_dwordx4 v[234:235], off
	v_lshl_add_u64 v[234:235], v[240:241], 0, s[12:13]
	s_mov_b32 m0, s56
	s_nop 0
	global_load_lds_dwordx4 v[234:235], off
	s_waitcnt vmcnt(8)
	s_waitcnt lgkmcnt(0)
	s_waitcnt lgkmcnt(0)
	v_mfma_f32_16x16x32_bf16 v[62:65], v[156:159], v[202:205], v[62:65]
	v_mfma_f32_16x16x32_bf16 v[58:61], v[164:167], v[202:205], v[58:61]
	v_mfma_f32_16x16x32_bf16 v[46:49], v[156:159], v[210:213], v[46:49]
	v_mfma_f32_16x16x32_bf16 v[42:45], v[164:167], v[210:213], v[42:45]
	s_barrier
	s_setprio 1
	v_mfma_f32_16x16x32_bf16 v[30:33], v[156:159], v[218:221], v[30:33]
	v_mfma_f32_16x16x32_bf16 v[26:29], v[164:167], v[218:221], v[26:29]
	v_mfma_f32_16x16x32_bf16 v[14:17], v[156:159], v[226:229], v[14:17]
	v_mfma_f32_16x16x32_bf16 v[10:13], v[164:167], v[226:229], v[10:13]
	v_mfma_f32_16x16x32_bf16 v[62:65], v[160:163], v[206:209], v[62:65]
	v_mfma_f32_16x16x32_bf16 v[58:61], v[168:171], v[206:209], v[58:61]
	v_mfma_f32_16x16x32_bf16 v[46:49], v[160:163], v[214:217], v[46:49]
	v_mfma_f32_16x16x32_bf16 v[42:45], v[168:171], v[214:217], v[42:45]
	v_mfma_f32_16x16x32_bf16 v[30:33], v[160:163], v[222:225], v[30:33]
	v_mfma_f32_16x16x32_bf16 v[26:29], v[168:171], v[222:225], v[26:29]
	v_mfma_f32_16x16x32_bf16 v[14:17], v[160:163], v[230:233], v[14:17]
	v_mfma_f32_16x16x32_bf16 v[10:13], v[168:171], v[230:233], v[10:13]
	s_setprio 0
	s_setprio 1
	v_mfma_f32_16x16x32_bf16 v[54:57], v[172:175], v[202:205], v[54:57]
	v_mfma_f32_16x16x32_bf16 v[50:53], v[180:183], v[202:205], v[50:53]
	v_mfma_f32_16x16x32_bf16 v[38:41], v[172:175], v[210:213], v[38:41]
	v_mfma_f32_16x16x32_bf16 v[34:37], v[180:183], v[210:213], v[34:37]
	v_mfma_f32_16x16x32_bf16 v[22:25], v[172:175], v[218:221], v[22:25]
	v_mfma_f32_16x16x32_bf16 v[18:21], v[180:183], v[218:221], v[18:21]
	v_mfma_f32_16x16x32_bf16 v[6:9], v[172:175], v[226:229], v[6:9]
	v_mfma_f32_16x16x32_bf16 v[2:5], v[180:183], v[226:229], v[2:5]
	v_mfma_f32_16x16x32_bf16 v[54:57], v[176:179], v[206:209], v[54:57]
	v_mfma_f32_16x16x32_bf16 v[50:53], v[184:187], v[206:209], v[50:53]
	v_mfma_f32_16x16x32_bf16 v[38:41], v[176:179], v[214:217], v[38:41]
	v_mfma_f32_16x16x32_bf16 v[34:37], v[184:187], v[214:217], v[34:37]
	v_mfma_f32_16x16x32_bf16 v[22:25], v[176:179], v[222:225], v[22:25]
	v_mfma_f32_16x16x32_bf16 v[18:21], v[184:187], v[222:225], v[18:21]
	v_mfma_f32_16x16x32_bf16 v[6:9], v[176:179], v[230:233], v[6:9]
	v_mfma_f32_16x16x32_bf16 v[2:5], v[184:187], v[230:233], v[2:5]
	s_setprio 0
	s_barrier
	s_add_i32 s29, s29, 2
	s_add_u32 s30, s30, 0x100
	s_addc_u32 s31, s31, 0
	s_add_u32 s34, s34, 0x100
	s_addc_u32 s35, s35, 0
	s_cmpk_gt_u32 s29, 0x55
	s_cbranch_scc0 .LBB0_1675
	s_and_b64 vcc, exec, s[14:15]
	s_cbranch_vccz .LBB0_1678
	s_barrier
